# all 8 GEMM K-loops: dropped mid-segment setprio 0/1 flip pairs and the duplicate lgkmcnt(0) after each pre-MFMA barrier (on top of saddr LDS-DMA in gate/up)
# speedup vs baseline: 1.0025x; 1.0025x over previous
; #define PG8_STAGE(bufoff, gbase, voff) do { _Pragma("unroll") for (int _i = 0; _i < 2; ++_i) \
;         __builtin_amdgcn_global_load_lds((const unsigned*)((const char*)(gbase) + (voff)[_i]), (LAS unsigned*)(lds + (bufoff) + ldsw + _i * 8192), 16, 0, 0); } while (0)
; #define PG8_LDA(dst, b, h) do { _Pragma("unroll") for (int m = 0; m < 4; ++m) _Pragma("unroll") for (int k = 0; k < 2; ++k) dst[m][k] = *(const LAS bf16x8*)(pA + PG8_SA(b, h) + m * 2048 + k * 1024); } while (0)
; #define PG8_LDB(dst, b, h) do { _Pragma("unroll") for (int n = 0; n < 2; ++n) _Pragma("unroll") for (int k = 0; k < 2; ++k) dst[n][k] = *(const LAS bf16x8*)(pB + (PG8_SB(b, h) - 4 * HTB) + n * 2048 + k * 1024); } while (0)
; #define PG8_MMA(ai, bj, At, Bt) do { __builtin_amdgcn_s_setprio(1); _Pragma("unroll") for (int m = 0; m < 4; ++m) _Pragma("unroll") for (int n = 0; n < 2; ++n) _Pragma("unroll") for (int k = 0; k < 2; ++k) \
;         acc[ai][bj][m][n] = __builtin_amdgcn_mfma_f32_16x16x32_bf16(Bt[n][k], At[m][k], acc[ai][bj][m][n], 0, 0, 0); __builtin_amdgcn_s_setprio(0); } while (0)
; #define PG8_WAIT_V(n) asm volatile("s_waitcnt vmcnt(" #n ")" ::: "memory")
; #define PG8_WAIT_L(n) asm volatile("s_waitcnt lgkmcnt(" #n ")" ::: "memory")
; #define PG8_BAR __builtin_amdgcn_s_barrier()
; #define PG8_SCHED __builtin_amdgcn_sched_barrier(0)
; template <class Desc, class Epi, bool ALIGN_EPI>
; __device__ __forceinline__ void gemm_phase(LAS unsigned char* lds, const Desc& D, const Epi& E, int G, int c) {
;     ...
;             const char* a1 = cA + (size_t)(t + 1) * kstep;
;             const char* a2 = last ? nA : cA + (size_t)(t + 2) * kstep; const char* b2 = last ? nB : cB + (size_t)(t + 2) * kstep;
;             const char* a3 = a2 + kstep; const char* b3 = b2 + kstep;
;             PG8_LDB(B0, 0, 0); PG8_LDB(B1, 0, 1); PG8_SCHED; PG8_LDA(At, 0, 0); PG8_STAGE(PG8_SA(1, 1), a1 + hstepA, voffA);
;             PG8_WAIT_V(8); PG8_WAIT_L(0); PG8_BAR; PG8_MMA(0, 0, At, B0); PG8_MMA(0, 1, At, B1); PG8_BAR; PG8_SCHED;
;             PG8_LDA(At, 0, 1); PG8_STAGE(PG8_SB(0, 0), b2, voffB); PG8_STAGE(PG8_SB(0, 1), b2 + hstepB, voffB); PG8_STAGE(PG8_SA(0, 0), a2, voffA);
;             PG8_WAIT_V(8); PG8_WAIT_L(0); PG8_BAR; PG8_MMA(1, 0, At, B0); PG8_MMA(1, 1, At, B1); PG8_BAR; PG8_SCHED;
.LBB0_172:
	s_or_b32 s14, s17, 1
	s_lshl_b64 s[26:27], s[14:15], 7
	s_add_i32 s14, s17, 2
	s_lshl_b64 s[40:41], s[14:15], 7
	s_add_u32 s17, s12, s40
	ds_read_b128 v[134:137], v169
	ds_read_b128 v[138:141], v169 offset:1024
	ds_read_b128 v[142:145], v169 offset:2048
	ds_read_b128 v[146:149], v169 offset:3072
	ds_read_b128 v[160:163], v169 offset:16384
	ds_read_b128 v[164:167], v169 offset:17408
	ds_read_b128 v[174:177], v169 offset:18432
	ds_read_b128 v[178:181], v169 offset:19456
	s_addc_u32 s21, s13, s41
	s_and_b64 s[38:39], s[30:31], exec
	s_cselect_b32 s39, s61, s21
	s_cselect_b32 s38, s60, s17
	s_add_u32 s17, s18, s40
	s_addc_u32 s21, s19, s41
	s_and_b64 s[30:31], s[30:31], exec
	s_cselect_b32 s31, s63, s21
	s_cselect_b32 s30, s62, s17
	s_add_u32 s17, s12, s26
	s_addc_u32 s21, s13, s27
	s_add_u32 s26, s17, 0x100000
	s_addc_u32 s27, s21, 0
	s_mov_b32 m0, s50
	v_lshl_add_u64 v[150:151], s[26:27], 0, v[152:153]
	ds_read_b128 v[182:185], v168
	ds_read_b128 v[186:189], v168 offset:1024
	ds_read_b128 v[190:193], v168 offset:2048
	ds_read_b128 v[194:197], v168 offset:3072
	ds_read_b128 v[198:201], v168 offset:4096
	ds_read_b128 v[202:205], v168 offset:5120
	ds_read_b128 v[206:209], v168 offset:6144
	ds_read_b128 v[210:213], v168 offset:7168
	global_load_lds_dwordx4 v[150:151], off
	v_lshl_add_u64 v[150:151], s[26:27], 0, v[156:157]
	s_mov_b32 m0, s51
	s_nop 0
	global_load_lds_dwordx4 v[150:151], off
	s_waitcnt vmcnt(8)
	s_waitcnt lgkmcnt(0)
	s_barrier
	s_setprio 1
	v_mfma_f32_16x16x32_bf16 v[128:131], v[134:137], v[182:185], v[128:131]
	v_mfma_f32_16x16x32_bf16 v[124:127], v[142:145], v[182:185], v[124:127]
	v_mfma_f32_16x16x32_bf16 v[120:123], v[134:137], v[190:193], v[120:123]
	v_mfma_f32_16x16x32_bf16 v[116:119], v[142:145], v[190:193], v[116:119]
	v_mfma_f32_16x16x32_bf16 v[112:115], v[134:137], v[198:201], v[112:115]
	v_mfma_f32_16x16x32_bf16 v[108:111], v[142:145], v[198:201], v[108:111]
	v_mfma_f32_16x16x32_bf16 v[104:107], v[134:137], v[206:209], v[104:107]
	v_mfma_f32_16x16x32_bf16 v[100:103], v[142:145], v[206:209], v[100:103]
	v_mfma_f32_16x16x32_bf16 v[128:131], v[138:141], v[186:189], v[128:131]
	v_mfma_f32_16x16x32_bf16 v[124:127], v[146:149], v[186:189], v[124:127]
	v_mfma_f32_16x16x32_bf16 v[120:123], v[138:141], v[194:197], v[120:123]
	v_mfma_f32_16x16x32_bf16 v[116:119], v[146:149], v[194:197], v[116:119]
	v_mfma_f32_16x16x32_bf16 v[112:115], v[138:141], v[202:205], v[112:115]
	v_mfma_f32_16x16x32_bf16 v[108:111], v[146:149], v[202:205], v[108:111]
	v_mfma_f32_16x16x32_bf16 v[104:107], v[138:141], v[210:213], v[104:107]
	v_mfma_f32_16x16x32_bf16 v[100:103], v[146:149], v[210:213], v[100:103]
	v_mfma_f32_16x16x32_bf16 v[96:99], v[160:163], v[182:185], v[96:99]
	v_mfma_f32_16x16x32_bf16 v[92:95], v[174:177], v[182:185], v[92:95]
	v_mfma_f32_16x16x32_bf16 v[88:91], v[160:163], v[190:193], v[88:91]
	v_mfma_f32_16x16x32_bf16 v[84:87], v[174:177], v[190:193], v[84:87]
	v_mfma_f32_16x16x32_bf16 v[80:83], v[160:163], v[198:201], v[80:83]
	v_mfma_f32_16x16x32_bf16 v[76:79], v[174:177], v[198:201], v[76:79]
	v_mfma_f32_16x16x32_bf16 v[72:75], v[160:163], v[206:209], v[72:75]
	v_mfma_f32_16x16x32_bf16 v[68:71], v[174:177], v[206:209], v[68:71]
	v_mfma_f32_16x16x32_bf16 v[96:99], v[164:167], v[186:189], v[96:99]
	v_mfma_f32_16x16x32_bf16 v[92:95], v[178:181], v[186:189], v[92:95]
	v_mfma_f32_16x16x32_bf16 v[88:91], v[164:167], v[194:197], v[88:91]
	v_mfma_f32_16x16x32_bf16 v[84:87], v[178:181], v[194:197], v[84:87]
	v_mfma_f32_16x16x32_bf16 v[80:83], v[164:167], v[202:205], v[80:83]
	v_mfma_f32_16x16x32_bf16 v[76:79], v[178:181], v[202:205], v[76:79]
	v_mfma_f32_16x16x32_bf16 v[72:75], v[164:167], v[210:213], v[72:75]
	v_mfma_f32_16x16x32_bf16 v[68:71], v[178:181], v[210:213], v[68:71]
	s_setprio 0
	s_barrier
	s_mov_b32 m0, s84
	v_lshl_add_u64 v[150:151], s[30:31], 0, v[154:155]
	s_add_u32 s26, s30, 0x100000
	ds_read_b128 v[182:185], v168 offset:16384
	ds_read_b128 v[186:189], v168 offset:17408
	ds_read_b128 v[190:193], v168 offset:18432
	ds_read_b128 v[194:197], v168 offset:19456
	ds_read_b128 v[198:201], v168 offset:20480
	ds_read_b128 v[202:205], v168 offset:21504
	ds_read_b128 v[206:209], v168 offset:22528
	ds_read_b128 v[210:213], v168 offset:23552
	global_load_lds_dwordx4 v[150:151], off
	v_lshl_add_u64 v[214:215], s[30:31], 0, v[158:159]
	s_mov_b32 m0, s85
	s_addc_u32 s27, s31, 0
	global_load_lds_dwordx4 v[214:215], off
	v_lshl_add_u64 v[216:217], s[26:27], 0, v[154:155]
	s_mov_b32 m0, s86
	v_lshl_add_u64 v[218:219], s[38:39], 0, v[156:157]
	global_load_lds_dwordx4 v[216:217], off
	v_lshl_add_u64 v[216:217], s[26:27], 0, v[158:159]
	s_mov_b32 m0, s87
	s_nop 0
	global_load_lds_dwordx4 v[216:217], off
	v_lshl_add_u64 v[216:217], s[38:39], 0, v[152:153]
	s_mov_b32 m0, s83
	s_nop 0
	global_load_lds_dwordx4 v[216:217], off
	s_mov_b32 m0, s88
	s_nop 0
	global_load_lds_dwordx4 v[218:219], off
	s_waitcnt vmcnt(8)
	s_waitcnt lgkmcnt(0)
	s_barrier
; #define PG8_STAGE(bufoff, gbase, voff) do { _Pragma("unroll") for (int _i = 0; _i < 2; ++_i) \
;         __builtin_amdgcn_global_load_lds((const unsigned*)((const char*)(gbase) + (voff)[_i]), (LAS unsigned*)(lds + (bufoff) + ldsw + _i * 8192), 16, 0, 0); } while (0)
; #define PG8_LDA(dst, b, h) do { _Pragma("unroll") for (int m = 0; m < 4; ++m) _Pragma("unroll") for (int k = 0; k < 2; ++k) dst[m][k] = *(const LAS bf16x8*)(pA + PG8_SA(b, h) + m * 2048 + k * 1024); } while (0)
; #define PG8_LDB(dst, b, h) do { _Pragma("unroll") for (int n = 0; n < 2; ++n) _Pragma("unroll") for (int k = 0; k < 2; ++k) dst[n][k] = *(const LAS bf16x8*)(pB + (PG8_SB(b, h) - 4 * HTB) + n * 2048 + k * 1024); } while (0)
; #define PG8_MMA(ai, bj, At, Bt) do { __builtin_amdgcn_s_setprio(1); _Pragma("unroll") for (int m = 0; m < 4; ++m) _Pragma("unroll") for (int n = 0; n < 2; ++n) _Pragma("unroll") for (int k = 0; k < 2; ++k) \
;         acc[ai][bj][m][n] = __builtin_amdgcn_mfma_f32_16x16x32_bf16(Bt[n][k], At[m][k], acc[ai][bj][m][n], 0, 0, 0); __builtin_amdgcn_s_setprio(0); } while (0)
; #define PG8_WAIT_V(n) asm volatile("s_waitcnt vmcnt(" #n ")" ::: "memory")
; #define PG8_WAIT_L(n) asm volatile("s_waitcnt lgkmcnt(" #n ")" ::: "memory")
; #define PG8_BAR __builtin_amdgcn_s_barrier()
; #define PG8_SCHED __builtin_amdgcn_sched_barrier(0)
; template <class Desc, class Epi, bool ALIGN_EPI>
; __device__ __forceinline__ void gemm_phase(LAS unsigned char* lds, const Desc& D, const Epi& E, int G, int c) {
;     ...
;             PG8_WAIT_V(8); PG8_WAIT_L(0); PG8_BAR; PG8_MMA(1, 0, At, B0); PG8_MMA(1, 1, At, B1); PG8_BAR; PG8_SCHED;
;             PG8_LDB(B0, 1, 0); PG8_LDB(B1, 1, 1); PG8_SCHED; PG8_LDA(At, 1, 0); PG8_STAGE(PG8_SA(0, 1), a2 + hstepA, voffA);
;             PG8_WAIT_V(8); PG8_WAIT_L(0); PG8_BAR; PG8_MMA(0, 0, At, B0); PG8_MMA(0, 1, At, B1); PG8_BAR; PG8_SCHED;
	s_setprio 1
	v_mfma_f32_16x16x32_bf16 v[64:67], v[134:137], v[182:185], v[64:67]
	v_mfma_f32_16x16x32_bf16 v[52:55], v[142:145], v[182:185], v[52:55]
	v_mfma_f32_16x16x32_bf16 v[32:35], v[134:137], v[190:193], v[32:35]
	v_mfma_f32_16x16x32_bf16 v[20:23], v[142:145], v[190:193], v[20:23]
	v_mfma_f32_16x16x32_bf16 v[16:19], v[134:137], v[198:201], v[16:19]
	v_mfma_f32_16x16x32_bf16 v[12:15], v[142:145], v[198:201], v[12:15]
	v_mfma_f32_16x16x32_bf16 v[8:11], v[134:137], v[206:209], v[8:11]
	v_mfma_f32_16x16x32_bf16 v[4:7], v[142:145], v[206:209], v[4:7]
	v_mfma_f32_16x16x32_bf16 v[64:67], v[138:141], v[186:189], v[64:67]
	v_mfma_f32_16x16x32_bf16 v[52:55], v[146:149], v[186:189], v[52:55]
	v_mfma_f32_16x16x32_bf16 v[32:35], v[138:141], v[194:197], v[32:35]
	v_mfma_f32_16x16x32_bf16 v[20:23], v[146:149], v[194:197], v[20:23]
	v_mfma_f32_16x16x32_bf16 v[16:19], v[138:141], v[202:205], v[16:19]
	v_mfma_f32_16x16x32_bf16 v[12:15], v[146:149], v[202:205], v[12:15]
	v_mfma_f32_16x16x32_bf16 v[8:11], v[138:141], v[210:213], v[8:11]
	v_mfma_f32_16x16x32_bf16 v[4:7], v[146:149], v[210:213], v[4:7]
	v_mfma_f32_16x16x32_bf16 v[60:63], v[160:163], v[182:185], v[60:63]
	v_mfma_f32_16x16x32_bf16 v[56:59], v[174:177], v[182:185], v[56:59]
	v_mfma_f32_16x16x32_bf16 v[48:51], v[160:163], v[190:193], v[48:51]
	v_mfma_f32_16x16x32_bf16 v[44:47], v[174:177], v[190:193], v[44:47]
	v_mfma_f32_16x16x32_bf16 v[40:43], v[160:163], v[198:201], v[40:43]
	v_mfma_f32_16x16x32_bf16 v[36:39], v[174:177], v[198:201], v[36:39]
	v_mfma_f32_16x16x32_bf16 v[28:31], v[160:163], v[206:209], v[28:31]
	v_mfma_f32_16x16x32_bf16 v[24:27], v[174:177], v[206:209], v[24:27]
	v_mfma_f32_16x16x32_bf16 v[60:63], v[164:167], v[186:189], v[60:63]
	v_mfma_f32_16x16x32_bf16 v[56:59], v[178:181], v[186:189], v[56:59]
	v_mfma_f32_16x16x32_bf16 v[48:51], v[164:167], v[194:197], v[48:51]
	v_mfma_f32_16x16x32_bf16 v[44:47], v[178:181], v[194:197], v[44:47]
	v_mfma_f32_16x16x32_bf16 v[40:43], v[164:167], v[202:205], v[40:43]
	v_mfma_f32_16x16x32_bf16 v[36:39], v[178:181], v[202:205], v[36:39]
	v_mfma_f32_16x16x32_bf16 v[28:31], v[164:167], v[210:213], v[28:31]
	v_mfma_f32_16x16x32_bf16 v[24:27], v[178:181], v[210:213], v[24:27]
	s_setprio 0
	s_barrier
	ds_read_b128 v[134:137], v169 offset:32768
	ds_read_b128 v[138:141], v169 offset:33792
	ds_read_b128 v[142:145], v169 offset:34816
	ds_read_b128 v[146:149], v169 offset:35840
	ds_read_b128 v[160:163], v169 offset:49152
	ds_read_b128 v[164:167], v169 offset:50176
	ds_read_b128 v[174:177], v169 offset:51200
	ds_read_b128 v[178:181], v169 offset:52224
	s_add_u32 s26, s38, 0x100000
	s_addc_u32 s27, s39, 0
	s_mov_b32 m0, s89
	v_lshl_add_u64 v[220:221], s[26:27], 0, v[152:153]
	ds_read_b128 v[182:185], v168 offset:32768
	ds_read_b128 v[186:189], v168 offset:33792
	ds_read_b128 v[190:193], v168 offset:34816
	ds_read_b128 v[194:197], v168 offset:35840
	ds_read_b128 v[198:201], v168 offset:36864
	ds_read_b128 v[202:205], v168 offset:37888
	ds_read_b128 v[206:209], v168 offset:38912
	ds_read_b128 v[210:213], v168 offset:39936
	global_load_lds_dwordx4 v[220:221], off
	v_lshl_add_u64 v[220:221], s[26:27], 0, v[156:157]
	s_mov_b32 m0, s90
	s_nop 0
	global_load_lds_dwordx4 v[220:221], off
	s_waitcnt vmcnt(8)
	s_waitcnt lgkmcnt(0)
	s_barrier
	s_setprio 1
	v_mfma_f32_16x16x32_bf16 v[128:131], v[134:137], v[182:185], v[128:131]
	v_mfma_f32_16x16x32_bf16 v[124:127], v[142:145], v[182:185], v[124:127]
	v_mfma_f32_16x16x32_bf16 v[120:123], v[134:137], v[190:193], v[120:123]
	v_mfma_f32_16x16x32_bf16 v[116:119], v[142:145], v[190:193], v[116:119]
	v_mfma_f32_16x16x32_bf16 v[112:115], v[134:137], v[198:201], v[112:115]
	v_mfma_f32_16x16x32_bf16 v[108:111], v[142:145], v[198:201], v[108:111]
	v_mfma_f32_16x16x32_bf16 v[104:107], v[134:137], v[206:209], v[104:107]
	v_mfma_f32_16x16x32_bf16 v[100:103], v[142:145], v[206:209], v[100:103]
	v_mfma_f32_16x16x32_bf16 v[128:131], v[138:141], v[186:189], v[128:131]
	v_mfma_f32_16x16x32_bf16 v[124:127], v[146:149], v[186:189], v[124:127]
	v_mfma_f32_16x16x32_bf16 v[120:123], v[138:141], v[194:197], v[120:123]
	v_mfma_f32_16x16x32_bf16 v[116:119], v[146:149], v[194:197], v[116:119]
	v_mfma_f32_16x16x32_bf16 v[112:115], v[138:141], v[202:205], v[112:115]
	v_mfma_f32_16x16x32_bf16 v[108:111], v[146:149], v[202:205], v[108:111]
	v_mfma_f32_16x16x32_bf16 v[104:107], v[138:141], v[210:213], v[104:107]
	v_mfma_f32_16x16x32_bf16 v[100:103], v[146:149], v[210:213], v[100:103]
	v_mfma_f32_16x16x32_bf16 v[96:99], v[160:163], v[182:185], v[96:99]
	v_mfma_f32_16x16x32_bf16 v[92:95], v[174:177], v[182:185], v[92:95]
	v_mfma_f32_16x16x32_bf16 v[88:91], v[160:163], v[190:193], v[88:91]
	v_mfma_f32_16x16x32_bf16 v[84:87], v[174:177], v[190:193], v[84:87]
	v_mfma_f32_16x16x32_bf16 v[80:83], v[160:163], v[198:201], v[80:83]
	v_mfma_f32_16x16x32_bf16 v[76:79], v[174:177], v[198:201], v[76:79]
	v_mfma_f32_16x16x32_bf16 v[72:75], v[160:163], v[206:209], v[72:75]
	v_mfma_f32_16x16x32_bf16 v[68:71], v[174:177], v[206:209], v[68:71]
	v_mfma_f32_16x16x32_bf16 v[96:99], v[164:167], v[186:189], v[96:99]
	v_mfma_f32_16x16x32_bf16 v[92:95], v[178:181], v[186:189], v[92:95]
	v_mfma_f32_16x16x32_bf16 v[88:91], v[164:167], v[194:197], v[88:91]
	v_mfma_f32_16x16x32_bf16 v[84:87], v[178:181], v[194:197], v[84:87]
	v_mfma_f32_16x16x32_bf16 v[80:83], v[164:167], v[202:205], v[80:83]
	v_mfma_f32_16x16x32_bf16 v[76:79], v[178:181], v[202:205], v[76:79]
	v_mfma_f32_16x16x32_bf16 v[72:75], v[164:167], v[210:213], v[72:75]
	v_mfma_f32_16x16x32_bf16 v[68:71], v[178:181], v[210:213], v[68:71]
	s_setprio 0
	s_barrier
;     __device__ __forceinline__ int nt(const Unit& u) const { return (u.pn >> 1) < 2 ? 22 : 20; }
; #define PG8_STAGE(bufoff, gbase, voff) do { _Pragma("unroll") for (int _i = 0; _i < 2; ++_i) \
;         __builtin_amdgcn_global_load_lds((const unsigned*)((const char*)(gbase) + (voff)[_i]), (LAS unsigned*)(lds + (bufoff) + ldsw + _i * 8192), 16, 0, 0); } while (0)
; #define PG8_LDA(dst, b, h) do { _Pragma("unroll") for (int m = 0; m < 4; ++m) _Pragma("unroll") for (int k = 0; k < 2; ++k) dst[m][k] = *(const LAS bf16x8*)(pA + PG8_SA(b, h) + m * 2048 + k * 1024); } while (0)
; #define PG8_MMA(ai, bj, At, Bt) do { __builtin_amdgcn_s_setprio(1); _Pragma("unroll") for (int m = 0; m < 4; ++m) _Pragma("unroll") for (int n = 0; n < 2; ++n) _Pragma("unroll") for (int k = 0; k < 2; ++k) \
;         acc[ai][bj][m][n] = __builtin_amdgcn_mfma_f32_16x16x32_bf16(Bt[n][k], At[m][k], acc[ai][bj][m][n], 0, 0, 0); __builtin_amdgcn_s_setprio(0); } while (0)
; #define PG8_WAIT_V(n) asm volatile("s_waitcnt vmcnt(" #n ")" ::: "memory")
; #define PG8_WAIT_L(n) asm volatile("s_waitcnt lgkmcnt(" #n ")" ::: "memory")
; #define PG8_BAR __builtin_amdgcn_s_barrier()
; #define PG8_SCHED __builtin_amdgcn_sched_barrier(0)
; template <class Desc, class Epi, bool ALIGN_EPI>
; __device__ __forceinline__ void gemm_phase(LAS unsigned char* lds, const Desc& D, const Epi& E, int G, int c) {
;     ...
;         for (int t = 0; t < nt; t += 2) {
;     ...
;             PG8_LDA(At, 1, 1); PG8_STAGE(PG8_SB(1, 0), b3, voffB); PG8_STAGE(PG8_SB(1, 1), b3 + hstepB, voffB); PG8_STAGE(PG8_SA(1, 0), a3, voffA);
;             PG8_WAIT_V(8); PG8_WAIT_L(0); PG8_BAR; PG8_MMA(1, 0, At, B0); PG8_MMA(1, 1, At, B1); PG8_BAR; PG8_SCHED;
;         }
	s_mov_b32 m0, s92
	v_lshl_add_u64 v[150:151], v[150:151], 0, s[76:77]
	s_add_u32 s26, s30, 0x100080
	ds_read_b128 v[182:185], v168 offset:49152
	ds_read_b128 v[186:189], v168 offset:50176
	ds_read_b128 v[190:193], v168 offset:51200
	ds_read_b128 v[194:197], v168 offset:52224
	ds_read_b128 v[198:201], v168 offset:53248
	ds_read_b128 v[202:205], v168 offset:54272
	ds_read_b128 v[206:209], v168 offset:55296
	ds_read_b128 v[210:213], v168 offset:56320
	global_load_lds_dwordx4 v[150:151], off
	v_lshl_add_u64 v[150:151], v[214:215], 0, s[76:77]
	s_mov_b32 m0, s93
	s_addc_u32 s27, s31, 0
	global_load_lds_dwordx4 v[150:151], off
	v_lshl_add_u64 v[150:151], s[26:27], 0, v[154:155]
	s_mov_b32 m0, s97
	s_nop 0
	global_load_lds_dwordx4 v[150:151], off
	v_lshl_add_u64 v[150:151], s[26:27], 0, v[158:159]
	s_mov_b32 m0, s82
	s_nop 0
	global_load_lds_dwordx4 v[150:151], off
	v_lshl_add_u64 v[150:151], v[216:217], 0, s[76:77]
	s_mov_b32 m0, s94
	s_nop 0
	global_load_lds_dwordx4 v[150:151], off
	v_lshl_add_u64 v[150:151], v[218:219], 0, s[76:77]
	s_mov_b32 m0, s95
	s_nop 0
	global_load_lds_dwordx4 v[150:151], off
	s_waitcnt vmcnt(8)
	s_waitcnt lgkmcnt(0)
	s_barrier
	s_setprio 1
	v_mfma_f32_16x16x32_bf16 v[64:67], v[134:137], v[182:185], v[64:67]
	v_mfma_f32_16x16x32_bf16 v[52:55], v[142:145], v[182:185], v[52:55]
	v_mfma_f32_16x16x32_bf16 v[32:35], v[134:137], v[190:193], v[32:35]
	v_mfma_f32_16x16x32_bf16 v[20:23], v[142:145], v[190:193], v[20:23]
	v_mfma_f32_16x16x32_bf16 v[16:19], v[134:137], v[198:201], v[16:19]
	v_mfma_f32_16x16x32_bf16 v[12:15], v[142:145], v[198:201], v[12:15]
	v_mfma_f32_16x16x32_bf16 v[8:11], v[134:137], v[206:209], v[8:11]
	v_mfma_f32_16x16x32_bf16 v[4:7], v[142:145], v[206:209], v[4:7]
	v_mfma_f32_16x16x32_bf16 v[64:67], v[138:141], v[186:189], v[64:67]
	v_mfma_f32_16x16x32_bf16 v[52:55], v[146:149], v[186:189], v[52:55]
	v_mfma_f32_16x16x32_bf16 v[32:35], v[138:141], v[194:197], v[32:35]
	v_mfma_f32_16x16x32_bf16 v[20:23], v[146:149], v[194:197], v[20:23]
	v_mfma_f32_16x16x32_bf16 v[16:19], v[138:141], v[202:205], v[16:19]
	v_mfma_f32_16x16x32_bf16 v[12:15], v[146:149], v[202:205], v[12:15]
	v_mfma_f32_16x16x32_bf16 v[8:11], v[138:141], v[210:213], v[8:11]
	v_mfma_f32_16x16x32_bf16 v[4:7], v[146:149], v[210:213], v[4:7]
	v_mfma_f32_16x16x32_bf16 v[60:63], v[160:163], v[182:185], v[60:63]
	v_mfma_f32_16x16x32_bf16 v[56:59], v[174:177], v[182:185], v[56:59]
	v_mfma_f32_16x16x32_bf16 v[48:51], v[160:163], v[190:193], v[48:51]
	v_mfma_f32_16x16x32_bf16 v[44:47], v[174:177], v[190:193], v[44:47]
	v_mfma_f32_16x16x32_bf16 v[40:43], v[160:163], v[198:201], v[40:43]
	v_mfma_f32_16x16x32_bf16 v[36:39], v[174:177], v[198:201], v[36:39]
	v_mfma_f32_16x16x32_bf16 v[28:31], v[160:163], v[206:209], v[28:31]
	v_mfma_f32_16x16x32_bf16 v[24:27], v[174:177], v[206:209], v[24:27]
	v_mfma_f32_16x16x32_bf16 v[60:63], v[164:167], v[186:189], v[60:63]
	v_mfma_f32_16x16x32_bf16 v[56:59], v[178:181], v[186:189], v[56:59]
	v_mfma_f32_16x16x32_bf16 v[48:51], v[164:167], v[194:197], v[48:51]
	v_mfma_f32_16x16x32_bf16 v[44:47], v[178:181], v[194:197], v[44:47]
	v_mfma_f32_16x16x32_bf16 v[40:43], v[164:167], v[202:205], v[40:43]
	v_mfma_f32_16x16x32_bf16 v[36:39], v[178:181], v[202:205], v[36:39]
	v_mfma_f32_16x16x32_bf16 v[28:31], v[164:167], v[210:213], v[28:31]
	v_mfma_f32_16x16x32_bf16 v[24:27], v[178:181], v[210:213], v[24:27]
	s_setprio 0
	s_barrier
	s_cmp_ge_u32 s14, s3
	s_mov_b32 s17, s14
	s_cbranch_scc1 .LBB0_183

; #define PG8_STAGE(bufoff, gbase, voff) do { _Pragma("unroll") for (int _i = 0; _i < 2; ++_i) \
;         __builtin_amdgcn_global_load_lds((const unsigned*)((const char*)(gbase) + (voff)[_i]), (LAS unsigned*)(lds + (bufoff) + ldsw + _i * 8192), 16, 0, 0); } while (0)
; #define PG8_LDA(dst, b, h) do { _Pragma("unroll") for (int m = 0; m < 4; ++m) _Pragma("unroll") for (int k = 0; k < 2; ++k) dst[m][k] = *(const LAS bf16x8*)(pA + PG8_SA(b, h) + m * 2048 + k * 1024); } while (0)
; #define PG8_LDB(dst, b, h) do { _Pragma("unroll") for (int n = 0; n < 2; ++n) _Pragma("unroll") for (int k = 0; k < 2; ++k) dst[n][k] = *(const LAS bf16x8*)(pB + (PG8_SB(b, h) - 4 * HTB) + n * 2048 + k * 1024); } while (0)
; #define PG8_MMA(ai, bj, At, Bt) do { __builtin_amdgcn_s_setprio(1); _Pragma("unroll") for (int m = 0; m < 4; ++m) _Pragma("unroll") for (int n = 0; n < 2; ++n) _Pragma("unroll") for (int k = 0; k < 2; ++k) \
;         acc[ai][bj][m][n] = __builtin_amdgcn_mfma_f32_16x16x32_bf16(Bt[n][k], At[m][k], acc[ai][bj][m][n], 0, 0, 0); __builtin_amdgcn_s_setprio(0); } while (0)
; #define PG8_WAIT_V(n) asm volatile("s_waitcnt vmcnt(" #n ")" ::: "memory")
; #define PG8_WAIT_L(n) asm volatile("s_waitcnt lgkmcnt(" #n ")" ::: "memory")
; #define PG8_BAR __builtin_amdgcn_s_barrier()
; #define PG8_SCHED __builtin_amdgcn_sched_barrier(0)
; template <class Desc, class Epi, bool ALIGN_EPI>
; __device__ __forceinline__ void gemm_phase(LAS unsigned char* lds, const Desc& D, const Epi& E, int G, int c) {
;     ...
;             const char* a1 = cA + (size_t)(t + 1) * kstep;
;             const char* a2 = last ? nA : cA + (size_t)(t + 2) * kstep; const char* b2 = last ? nB : cB + (size_t)(t + 2) * kstep;
;             const char* a3 = a2 + kstep; const char* b3 = b2 + kstep;
;             PG8_LDB(B0, 0, 0); PG8_LDB(B1, 0, 1); PG8_SCHED; PG8_LDA(At, 0, 0); PG8_STAGE(PG8_SA(1, 1), a1 + hstepA, voffA);
;             PG8_WAIT_V(8); PG8_WAIT_L(0); PG8_BAR; PG8_MMA(0, 0, At, B0); PG8_MMA(0, 1, At, B1); PG8_BAR; PG8_SCHED;
;             PG8_LDA(At, 0, 1); PG8_STAGE(PG8_SB(0, 0), b2, voffB); PG8_STAGE(PG8_SB(0, 1), b2 + hstepB, voffB); PG8_STAGE(PG8_SA(0, 0), a2, voffA);
;             PG8_WAIT_V(8); PG8_WAIT_L(0); PG8_BAR; PG8_MMA(1, 0, At, B0); PG8_MMA(1, 1, At, B1); PG8_BAR; PG8_SCHED;
.LBB0_603:
	ds_read_b128 v[144:147], v149
	ds_read_b128 v[152:155], v149 offset:1024
	ds_read_b128 v[156:159], v149 offset:2048
	ds_read_b128 v[160:163], v149 offset:3072
	ds_read_b128 v[164:167], v149 offset:16384
	ds_read_b128 v[168:171], v149 offset:17408
	ds_read_b128 v[172:175], v149 offset:18432
	ds_read_b128 v[176:179], v149 offset:19456
	s_add_u32 s16, s12, 0xfff80080
	s_addc_u32 s17, s13, -1
	s_cmp_eq_u32 s46, 4
	s_cselect_b32 s19, s9, s17
	s_cselect_b32 s18, s8, s16
	s_cselect_b32 s17, s11, s45
	s_cselect_b32 s16, s10, s7
	v_lshl_add_u64 v[212:213], s[12:13], 0, v[140:141]
	s_add_i32 m0, s20, 0xc000
	ds_read_b128 v[180:183], v148
	ds_read_b128 v[184:187], v148 offset:1024
	ds_read_b128 v[188:191], v148 offset:2048
	ds_read_b128 v[192:195], v148 offset:3072
	ds_read_b128 v[196:199], v148 offset:4096
	ds_read_b128 v[200:203], v148 offset:5120
	ds_read_b128 v[204:207], v148 offset:6144
	ds_read_b128 v[208:211], v148 offset:7168
	global_load_lds_dwordx4 v[212:213], off
	v_lshl_add_u64 v[212:213], s[12:13], 0, v[142:143]
	s_add_i32 m0, s20, 0xe000
	s_nop 0
	global_load_lds_dwordx4 v[212:213], off
	s_waitcnt vmcnt(8)
	s_waitcnt lgkmcnt(0)
	s_barrier
	s_setprio 1
	v_mfma_f32_16x16x32_bf16 v[128:131], v[144:147], v[180:183], v[128:131]
	v_mfma_f32_16x16x32_bf16 v[124:127], v[156:159], v[180:183], v[124:127]
	v_mfma_f32_16x16x32_bf16 v[116:119], v[144:147], v[188:191], v[116:119]
	v_mfma_f32_16x16x32_bf16 v[108:111], v[156:159], v[188:191], v[108:111]
	v_mfma_f32_16x16x32_bf16 v[100:103], v[144:147], v[196:199], v[100:103]
	v_mfma_f32_16x16x32_bf16 v[92:95], v[156:159], v[196:199], v[92:95]
	v_mfma_f32_16x16x32_bf16 v[84:87], v[144:147], v[204:207], v[84:87]
	v_mfma_f32_16x16x32_bf16 v[76:79], v[156:159], v[204:207], v[76:79]
	v_mfma_f32_16x16x32_bf16 v[128:131], v[152:155], v[184:187], v[128:131]
	v_mfma_f32_16x16x32_bf16 v[124:127], v[160:163], v[184:187], v[124:127]
	v_mfma_f32_16x16x32_bf16 v[116:119], v[152:155], v[192:195], v[116:119]
	v_mfma_f32_16x16x32_bf16 v[108:111], v[160:163], v[192:195], v[108:111]
	v_mfma_f32_16x16x32_bf16 v[100:103], v[152:155], v[200:203], v[100:103]
	v_mfma_f32_16x16x32_bf16 v[92:95], v[160:163], v[200:203], v[92:95]
	v_mfma_f32_16x16x32_bf16 v[84:87], v[152:155], v[208:211], v[84:87]
	v_mfma_f32_16x16x32_bf16 v[76:79], v[160:163], v[208:211], v[76:79]
	v_mfma_f32_16x16x32_bf16 v[120:123], v[164:167], v[180:183], v[120:123]
	v_mfma_f32_16x16x32_bf16 v[112:115], v[172:175], v[180:183], v[112:115]
	v_mfma_f32_16x16x32_bf16 v[104:107], v[164:167], v[188:191], v[104:107]
	v_mfma_f32_16x16x32_bf16 v[96:99], v[172:175], v[188:191], v[96:99]
	v_mfma_f32_16x16x32_bf16 v[88:91], v[164:167], v[196:199], v[88:91]
	v_mfma_f32_16x16x32_bf16 v[80:83], v[172:175], v[196:199], v[80:83]
	v_mfma_f32_16x16x32_bf16 v[72:75], v[164:167], v[204:207], v[72:75]
	v_mfma_f32_16x16x32_bf16 v[68:71], v[172:175], v[204:207], v[68:71]
	v_mfma_f32_16x16x32_bf16 v[120:123], v[168:171], v[184:187], v[120:123]
	v_mfma_f32_16x16x32_bf16 v[112:115], v[176:179], v[184:187], v[112:115]
	v_mfma_f32_16x16x32_bf16 v[104:107], v[168:171], v[192:195], v[104:107]
	v_mfma_f32_16x16x32_bf16 v[96:99], v[176:179], v[192:195], v[96:99]
	v_mfma_f32_16x16x32_bf16 v[88:91], v[168:171], v[200:203], v[88:91]
	v_mfma_f32_16x16x32_bf16 v[80:83], v[176:179], v[200:203], v[80:83]
	v_mfma_f32_16x16x32_bf16 v[72:75], v[168:171], v[208:211], v[72:75]
	v_mfma_f32_16x16x32_bf16 v[68:71], v[176:179], v[208:211], v[68:71]
	s_setprio 0
	s_barrier
	s_mov_b32 m0, s21
	v_lshl_add_u64 v[212:213], s[16:17], 0, v[136:137]
	s_add_u32 s48, s16, 0x20000
	ds_read_b128 v[180:183], v148 offset:16384
	ds_read_b128 v[184:187], v148 offset:17408
	ds_read_b128 v[188:191], v148 offset:18432
	ds_read_b128 v[192:195], v148 offset:19456
	ds_read_b128 v[196:199], v148 offset:20480
	ds_read_b128 v[200:203], v148 offset:21504
	ds_read_b128 v[204:207], v148 offset:22528
	ds_read_b128 v[208:211], v148 offset:23552
	global_load_lds_dwordx4 v[212:213], off
	v_lshl_add_u64 v[214:215], s[16:17], 0, v[132:133]
	s_mov_b32 m0, s23
	s_addc_u32 s49, s17, 0
	global_load_lds_dwordx4 v[214:215], off
	v_lshl_add_u64 v[216:217], s[48:49], 0, v[136:137]
	s_mov_b32 m0, s24
	v_lshl_add_u64 v[218:219], s[18:19], 0, v[134:135]
	global_load_lds_dwordx4 v[216:217], off
	v_lshl_add_u64 v[216:217], s[48:49], 0, v[132:133]
	s_mov_b32 m0, s25
	s_nop 0
	global_load_lds_dwordx4 v[216:217], off
	v_lshl_add_u64 v[216:217], s[18:19], 0, v[138:139]
	s_mov_b32 m0, s20
	s_nop 0
	global_load_lds_dwordx4 v[216:217], off
	s_mov_b32 m0, s26
	s_nop 0
	global_load_lds_dwordx4 v[218:219], off
	s_waitcnt vmcnt(8)
	s_waitcnt lgkmcnt(0)
	s_barrier
; #define PG8_STAGE(bufoff, gbase, voff) do { _Pragma("unroll") for (int _i = 0; _i < 2; ++_i) \
;         __builtin_amdgcn_global_load_lds((const unsigned*)((const char*)(gbase) + (voff)[_i]), (LAS unsigned*)(lds + (bufoff) + ldsw + _i * 8192), 16, 0, 0); } while (0)
; #define PG8_LDA(dst, b, h) do { _Pragma("unroll") for (int m = 0; m < 4; ++m) _Pragma("unroll") for (int k = 0; k < 2; ++k) dst[m][k] = *(const LAS bf16x8*)(pA + PG8_SA(b, h) + m * 2048 + k * 1024); } while (0)
; #define PG8_LDB(dst, b, h) do { _Pragma("unroll") for (int n = 0; n < 2; ++n) _Pragma("unroll") for (int k = 0; k < 2; ++k) dst[n][k] = *(const LAS bf16x8*)(pB + (PG8_SB(b, h) - 4 * HTB) + n * 2048 + k * 1024); } while (0)
; #define PG8_MMA(ai, bj, At, Bt) do { __builtin_amdgcn_s_setprio(1); _Pragma("unroll") for (int m = 0; m < 4; ++m) _Pragma("unroll") for (int n = 0; n < 2; ++n) _Pragma("unroll") for (int k = 0; k < 2; ++k) \
;         acc[ai][bj][m][n] = __builtin_amdgcn_mfma_f32_16x16x32_bf16(Bt[n][k], At[m][k], acc[ai][bj][m][n], 0, 0, 0); __builtin_amdgcn_s_setprio(0); } while (0)
; #define PG8_WAIT_V(n) asm volatile("s_waitcnt vmcnt(" #n ")" ::: "memory")
; #define PG8_WAIT_L(n) asm volatile("s_waitcnt lgkmcnt(" #n ")" ::: "memory")
; #define PG8_BAR __builtin_amdgcn_s_barrier()
; #define PG8_SCHED __builtin_amdgcn_sched_barrier(0)
; template <class Desc, class Epi, bool ALIGN_EPI>
; __device__ __forceinline__ void gemm_phase(LAS unsigned char* lds, const Desc& D, const Epi& E, int G, int c) {
;     ...
;             PG8_WAIT_V(8); PG8_WAIT_L(0); PG8_BAR; PG8_MMA(1, 0, At, B0); PG8_MMA(1, 1, At, B1); PG8_BAR; PG8_SCHED;
;             PG8_LDB(B0, 1, 0); PG8_LDB(B1, 1, 1); PG8_SCHED; PG8_LDA(At, 1, 0); PG8_STAGE(PG8_SA(0, 1), a2 + hstepA, voffA);
;             PG8_WAIT_V(8); PG8_WAIT_L(0); PG8_BAR; PG8_MMA(0, 0, At, B0); PG8_MMA(0, 1, At, B1); PG8_BAR; PG8_SCHED;
	s_setprio 1
	v_mfma_f32_16x16x32_bf16 v[64:67], v[144:147], v[180:183], v[64:67]
	v_mfma_f32_16x16x32_bf16 v[60:63], v[156:159], v[180:183], v[60:63]
	v_mfma_f32_16x16x32_bf16 v[52:55], v[144:147], v[188:191], v[52:55]
	v_mfma_f32_16x16x32_bf16 v[44:47], v[156:159], v[188:191], v[44:47]
	v_mfma_f32_16x16x32_bf16 v[36:39], v[144:147], v[196:199], v[36:39]
	v_mfma_f32_16x16x32_bf16 v[28:31], v[156:159], v[196:199], v[28:31]
	v_mfma_f32_16x16x32_bf16 v[20:23], v[144:147], v[204:207], v[20:23]
	v_mfma_f32_16x16x32_bf16 v[12:15], v[156:159], v[204:207], v[12:15]
	v_mfma_f32_16x16x32_bf16 v[64:67], v[152:155], v[184:187], v[64:67]
	v_mfma_f32_16x16x32_bf16 v[60:63], v[160:163], v[184:187], v[60:63]
	v_mfma_f32_16x16x32_bf16 v[52:55], v[152:155], v[192:195], v[52:55]
	v_mfma_f32_16x16x32_bf16 v[44:47], v[160:163], v[192:195], v[44:47]
	v_mfma_f32_16x16x32_bf16 v[36:39], v[152:155], v[200:203], v[36:39]
	v_mfma_f32_16x16x32_bf16 v[28:31], v[160:163], v[200:203], v[28:31]
	v_mfma_f32_16x16x32_bf16 v[20:23], v[152:155], v[208:211], v[20:23]
	v_mfma_f32_16x16x32_bf16 v[12:15], v[160:163], v[208:211], v[12:15]
	v_mfma_f32_16x16x32_bf16 v[56:59], v[164:167], v[180:183], v[56:59]
	v_mfma_f32_16x16x32_bf16 v[48:51], v[172:175], v[180:183], v[48:51]
	v_mfma_f32_16x16x32_bf16 v[40:43], v[164:167], v[188:191], v[40:43]
	v_mfma_f32_16x16x32_bf16 v[32:35], v[172:175], v[188:191], v[32:35]
	v_mfma_f32_16x16x32_bf16 v[24:27], v[164:167], v[196:199], v[24:27]
	v_mfma_f32_16x16x32_bf16 v[16:19], v[172:175], v[196:199], v[16:19]
	v_mfma_f32_16x16x32_bf16 v[8:11], v[164:167], v[204:207], v[8:11]
	v_mfma_f32_16x16x32_bf16 v[4:7], v[172:175], v[204:207], v[4:7]
	v_mfma_f32_16x16x32_bf16 v[56:59], v[168:171], v[184:187], v[56:59]
	v_mfma_f32_16x16x32_bf16 v[48:51], v[176:179], v[184:187], v[48:51]
	v_mfma_f32_16x16x32_bf16 v[40:43], v[168:171], v[192:195], v[40:43]
	v_mfma_f32_16x16x32_bf16 v[32:35], v[176:179], v[192:195], v[32:35]
	v_mfma_f32_16x16x32_bf16 v[24:27], v[168:171], v[200:203], v[24:27]
	v_mfma_f32_16x16x32_bf16 v[16:19], v[176:179], v[200:203], v[16:19]
	v_mfma_f32_16x16x32_bf16 v[8:11], v[168:171], v[208:211], v[8:11]
	v_mfma_f32_16x16x32_bf16 v[4:7], v[176:179], v[208:211], v[4:7]
	s_setprio 0
	s_barrier
	ds_read_b128 v[144:147], v149 offset:32768
	ds_read_b128 v[152:155], v149 offset:33792
	ds_read_b128 v[156:159], v149 offset:34816
	ds_read_b128 v[160:163], v149 offset:35840
	ds_read_b128 v[164:167], v149 offset:49152
	ds_read_b128 v[168:171], v149 offset:50176
	ds_read_b128 v[172:175], v149 offset:51200
	ds_read_b128 v[176:179], v149 offset:52224
	s_add_u32 s18, s18, 0x80000
	s_addc_u32 s19, s19, 0
	s_mov_b32 m0, s27
	v_lshl_add_u64 v[220:221], s[18:19], 0, v[138:139]
	ds_read_b128 v[180:183], v148 offset:32768
	ds_read_b128 v[184:187], v148 offset:33792
	ds_read_b128 v[188:191], v148 offset:34816
	ds_read_b128 v[192:195], v148 offset:35840
	ds_read_b128 v[196:199], v148 offset:36864
	ds_read_b128 v[200:203], v148 offset:37888
	ds_read_b128 v[204:207], v148 offset:38912
	ds_read_b128 v[208:211], v148 offset:39936
	global_load_lds_dwordx4 v[220:221], off
	v_lshl_add_u64 v[220:221], s[18:19], 0, v[134:135]
	s_mov_b32 m0, s30
	s_nop 0
	global_load_lds_dwordx4 v[220:221], off
	s_waitcnt vmcnt(8)
	s_waitcnt lgkmcnt(0)
	s_barrier
	s_setprio 1
	v_mfma_f32_16x16x32_bf16 v[128:131], v[144:147], v[180:183], v[128:131]
	v_mfma_f32_16x16x32_bf16 v[124:127], v[156:159], v[180:183], v[124:127]
	v_mfma_f32_16x16x32_bf16 v[116:119], v[144:147], v[188:191], v[116:119]
	v_mfma_f32_16x16x32_bf16 v[108:111], v[156:159], v[188:191], v[108:111]
	v_mfma_f32_16x16x32_bf16 v[100:103], v[144:147], v[196:199], v[100:103]
	v_mfma_f32_16x16x32_bf16 v[92:95], v[156:159], v[196:199], v[92:95]
	v_mfma_f32_16x16x32_bf16 v[84:87], v[144:147], v[204:207], v[84:87]
	v_mfma_f32_16x16x32_bf16 v[76:79], v[156:159], v[204:207], v[76:79]
	v_mfma_f32_16x16x32_bf16 v[128:131], v[152:155], v[184:187], v[128:131]
	v_mfma_f32_16x16x32_bf16 v[124:127], v[160:163], v[184:187], v[124:127]
	v_mfma_f32_16x16x32_bf16 v[116:119], v[152:155], v[192:195], v[116:119]
	v_mfma_f32_16x16x32_bf16 v[108:111], v[160:163], v[192:195], v[108:111]
	v_mfma_f32_16x16x32_bf16 v[100:103], v[152:155], v[200:203], v[100:103]
	v_mfma_f32_16x16x32_bf16 v[92:95], v[160:163], v[200:203], v[92:95]
	v_mfma_f32_16x16x32_bf16 v[84:87], v[152:155], v[208:211], v[84:87]
	v_mfma_f32_16x16x32_bf16 v[76:79], v[160:163], v[208:211], v[76:79]
	v_mfma_f32_16x16x32_bf16 v[120:123], v[164:167], v[180:183], v[120:123]
	v_mfma_f32_16x16x32_bf16 v[112:115], v[172:175], v[180:183], v[112:115]
	v_mfma_f32_16x16x32_bf16 v[104:107], v[164:167], v[188:191], v[104:107]
	v_mfma_f32_16x16x32_bf16 v[96:99], v[172:175], v[188:191], v[96:99]
	v_mfma_f32_16x16x32_bf16 v[88:91], v[164:167], v[196:199], v[88:91]
	v_mfma_f32_16x16x32_bf16 v[80:83], v[172:175], v[196:199], v[80:83]
	v_mfma_f32_16x16x32_bf16 v[72:75], v[164:167], v[204:207], v[72:75]
	v_mfma_f32_16x16x32_bf16 v[68:71], v[172:175], v[204:207], v[68:71]
	v_mfma_f32_16x16x32_bf16 v[120:123], v[168:171], v[184:187], v[120:123]
	v_mfma_f32_16x16x32_bf16 v[112:115], v[176:179], v[184:187], v[112:115]
	v_mfma_f32_16x16x32_bf16 v[104:107], v[168:171], v[192:195], v[104:107]
	v_mfma_f32_16x16x32_bf16 v[96:99], v[176:179], v[192:195], v[96:99]
	v_mfma_f32_16x16x32_bf16 v[88:91], v[168:171], v[200:203], v[88:91]
	v_mfma_f32_16x16x32_bf16 v[80:83], v[176:179], v[200:203], v[80:83]
	v_mfma_f32_16x16x32_bf16 v[72:75], v[168:171], v[208:211], v[72:75]
	v_mfma_f32_16x16x32_bf16 v[68:71], v[176:179], v[208:211], v[68:71]
	s_setprio 0
	s_barrier
;     __device__ __forceinline__ int nt(const Unit& u) const { return (u.pn >> 1) < 2 ? 22 : 20; }
; #define PG8_STAGE(bufoff, gbase, voff) do { _Pragma("unroll") for (int _i = 0; _i < 2; ++_i) \
;         __builtin_amdgcn_global_load_lds((const unsigned*)((const char*)(gbase) + (voff)[_i]), (LAS unsigned*)(lds + (bufoff) + ldsw + _i * 8192), 16, 0, 0); } while (0)
; #define PG8_LDA(dst, b, h) do { _Pragma("unroll") for (int m = 0; m < 4; ++m) _Pragma("unroll") for (int k = 0; k < 2; ++k) dst[m][k] = *(const LAS bf16x8*)(pA + PG8_SA(b, h) + m * 2048 + k * 1024); } while (0)
; #define PG8_MMA(ai, bj, At, Bt) do { __builtin_amdgcn_s_setprio(1); _Pragma("unroll") for (int m = 0; m < 4; ++m) _Pragma("unroll") for (int n = 0; n < 2; ++n) _Pragma("unroll") for (int k = 0; k < 2; ++k) \
;         acc[ai][bj][m][n] = __builtin_amdgcn_mfma_f32_16x16x32_bf16(Bt[n][k], At[m][k], acc[ai][bj][m][n], 0, 0, 0); __builtin_amdgcn_s_setprio(0); } while (0)
; #define PG8_WAIT_V(n) asm volatile("s_waitcnt vmcnt(" #n ")" ::: "memory")
; #define PG8_WAIT_L(n) asm volatile("s_waitcnt lgkmcnt(" #n ")" ::: "memory")
; #define PG8_BAR __builtin_amdgcn_s_barrier()
; #define PG8_SCHED __builtin_amdgcn_sched_barrier(0)
; template <class Desc, class Epi, bool ALIGN_EPI>
; __device__ __forceinline__ void gemm_phase(LAS unsigned char* lds, const Desc& D, const Epi& E, int G, int c) {
;     ...
;         for (int t = 0; t < nt; t += 2) {
;     ...
;             PG8_LDA(At, 1, 1); PG8_STAGE(PG8_SB(1, 0), b3, voffB); PG8_STAGE(PG8_SB(1, 1), b3 + hstepB, voffB); PG8_STAGE(PG8_SA(1, 0), a3, voffA);
;             PG8_WAIT_V(8); PG8_WAIT_L(0); PG8_BAR; PG8_MMA(1, 0, At, B0); PG8_MMA(1, 1, At, B1); PG8_BAR; PG8_SCHED;
;         }
	s_mov_b32 m0, s31
	v_lshl_add_u64 v[212:213], v[212:213], 0, s[76:77]
	s_add_u32 s16, s16, 0x20080
	ds_read_b128 v[180:183], v148 offset:49152
	ds_read_b128 v[184:187], v148 offset:50176
	ds_read_b128 v[188:191], v148 offset:51200
	ds_read_b128 v[192:195], v148 offset:52224
	ds_read_b128 v[196:199], v148 offset:53248
	ds_read_b128 v[200:203], v148 offset:54272
	ds_read_b128 v[204:207], v148 offset:55296
	ds_read_b128 v[208:211], v148 offset:56320
	global_load_lds_dwordx4 v[212:213], off
	v_lshl_add_u64 v[212:213], v[214:215], 0, s[76:77]
	s_mov_b32 m0, s33
	s_addc_u32 s17, s17, 0
	global_load_lds_dwordx4 v[212:213], off
	v_lshl_add_u64 v[212:213], s[16:17], 0, v[136:137]
	s_mov_b32 m0, s38
	s_nop 0
	global_load_lds_dwordx4 v[212:213], off
	v_lshl_add_u64 v[212:213], s[16:17], 0, v[132:133]
	s_mov_b32 m0, s39
	s_nop 0
	global_load_lds_dwordx4 v[212:213], off
	v_lshl_add_u64 v[212:213], v[216:217], 0, s[76:77]
	s_mov_b32 m0, s34
	s_nop 0
	global_load_lds_dwordx4 v[212:213], off
	v_lshl_add_u64 v[212:213], v[218:219], 0, s[76:77]
	s_mov_b32 m0, s35
	s_nop 0
	global_load_lds_dwordx4 v[212:213], off
	s_waitcnt vmcnt(8)
	s_waitcnt lgkmcnt(0)
	s_barrier
	s_setprio 1
	v_mfma_f32_16x16x32_bf16 v[64:67], v[144:147], v[180:183], v[64:67]
	v_mfma_f32_16x16x32_bf16 v[60:63], v[156:159], v[180:183], v[60:63]
	v_mfma_f32_16x16x32_bf16 v[52:55], v[144:147], v[188:191], v[52:55]
	v_mfma_f32_16x16x32_bf16 v[44:47], v[156:159], v[188:191], v[44:47]
	v_mfma_f32_16x16x32_bf16 v[36:39], v[144:147], v[196:199], v[36:39]
	v_mfma_f32_16x16x32_bf16 v[28:31], v[156:159], v[196:199], v[28:31]
	v_mfma_f32_16x16x32_bf16 v[20:23], v[144:147], v[204:207], v[20:23]
	v_mfma_f32_16x16x32_bf16 v[12:15], v[156:159], v[204:207], v[12:15]
	v_mfma_f32_16x16x32_bf16 v[64:67], v[152:155], v[184:187], v[64:67]
	v_mfma_f32_16x16x32_bf16 v[60:63], v[160:163], v[184:187], v[60:63]
	v_mfma_f32_16x16x32_bf16 v[52:55], v[152:155], v[192:195], v[52:55]
	v_mfma_f32_16x16x32_bf16 v[44:47], v[160:163], v[192:195], v[44:47]
	v_mfma_f32_16x16x32_bf16 v[36:39], v[152:155], v[200:203], v[36:39]
	v_mfma_f32_16x16x32_bf16 v[28:31], v[160:163], v[200:203], v[28:31]
	v_mfma_f32_16x16x32_bf16 v[20:23], v[152:155], v[208:211], v[20:23]
	v_mfma_f32_16x16x32_bf16 v[12:15], v[160:163], v[208:211], v[12:15]
	v_mfma_f32_16x16x32_bf16 v[56:59], v[164:167], v[180:183], v[56:59]
	v_mfma_f32_16x16x32_bf16 v[48:51], v[172:175], v[180:183], v[48:51]
	v_mfma_f32_16x16x32_bf16 v[40:43], v[164:167], v[188:191], v[40:43]
	v_mfma_f32_16x16x32_bf16 v[32:35], v[172:175], v[188:191], v[32:35]
	v_mfma_f32_16x16x32_bf16 v[24:27], v[164:167], v[196:199], v[24:27]
	v_mfma_f32_16x16x32_bf16 v[16:19], v[172:175], v[196:199], v[16:19]
	v_mfma_f32_16x16x32_bf16 v[8:11], v[164:167], v[204:207], v[8:11]
	v_mfma_f32_16x16x32_bf16 v[4:7], v[172:175], v[204:207], v[4:7]
	v_mfma_f32_16x16x32_bf16 v[56:59], v[168:171], v[184:187], v[56:59]
	v_mfma_f32_16x16x32_bf16 v[48:51], v[176:179], v[184:187], v[48:51]
	v_mfma_f32_16x16x32_bf16 v[40:43], v[168:171], v[192:195], v[40:43]
	v_mfma_f32_16x16x32_bf16 v[32:35], v[176:179], v[192:195], v[32:35]
	v_mfma_f32_16x16x32_bf16 v[24:27], v[168:171], v[200:203], v[24:27]
	v_mfma_f32_16x16x32_bf16 v[16:19], v[176:179], v[200:203], v[16:19]
	v_mfma_f32_16x16x32_bf16 v[8:11], v[168:171], v[208:211], v[8:11]
	v_mfma_f32_16x16x32_bf16 v[4:7], v[176:179], v[208:211], v[4:7]
	s_setprio 0
	s_barrier
	s_add_i32 s46, s46, 2
	s_add_u32 s12, s12, 0x100
	s_addc_u32 s13, s13, 0
	s_add_u32 s7, s7, 0x100
	s_addc_u32 s45, s45, 0
	s_cmp_gt_u32 s46, 5
	s_cbranch_scc0 .LBB0_603
	v_readlane_b32 s46, v255, 36
	s_and_b64 vcc, exec, s[4:5]
	v_readlane_b32 s47, v255, 37
	s_cbranch_vccz .LBB0_606
	s_barrier

; #define PG8_STAGE(bufoff, gbase, voff) do { _Pragma("unroll") for (int _i = 0; _i < 2; ++_i) \
;         __builtin_amdgcn_global_load_lds((const unsigned*)((const char*)(gbase) + (voff)[_i]), (LAS unsigned*)(lds + (bufoff) + ldsw + _i * 8192), 16, 0, 0); } while (0)
; #define PG8_LDA(dst, b, h) do { _Pragma("unroll") for (int m = 0; m < 4; ++m) _Pragma("unroll") for (int k = 0; k < 2; ++k) dst[m][k] = *(const LAS bf16x8*)(pA + PG8_SA(b, h) + m * 2048 + k * 1024); } while (0)
; #define PG8_LDB(dst, b, h) do { _Pragma("unroll") for (int n = 0; n < 2; ++n) _Pragma("unroll") for (int k = 0; k < 2; ++k) dst[n][k] = *(const LAS bf16x8*)(pB + (PG8_SB(b, h) - 4 * HTB) + n * 2048 + k * 1024); } while (0)
; #define PG8_MMA(ai, bj, At, Bt) do { __builtin_amdgcn_s_setprio(1); _Pragma("unroll") for (int m = 0; m < 4; ++m) _Pragma("unroll") for (int n = 0; n < 2; ++n) _Pragma("unroll") for (int k = 0; k < 2; ++k) \
;         acc[ai][bj][m][n] = __builtin_amdgcn_mfma_f32_16x16x32_bf16(Bt[n][k], At[m][k], acc[ai][bj][m][n], 0, 0, 0); __builtin_amdgcn_s_setprio(0); } while (0)
; #define PG8_WAIT_V(n) asm volatile("s_waitcnt vmcnt(" #n ")" ::: "memory")
; #define PG8_WAIT_L(n) asm volatile("s_waitcnt lgkmcnt(" #n ")" ::: "memory")
; #define PG8_BAR __builtin_amdgcn_s_barrier()
; #define PG8_SCHED __builtin_amdgcn_sched_barrier(0)
; template <class Desc, class Epi, bool ALIGN_EPI>
; __device__ __forceinline__ void gemm_phase(LAS unsigned char* lds, const Desc& D, const Epi& E, int G, int c) {
;     ...
;             const char* a1 = cA + (size_t)(t + 1) * kstep;
;             const char* a2 = last ? nA : cA + (size_t)(t + 2) * kstep; const char* b2 = last ? nB : cB + (size_t)(t + 2) * kstep;
;             const char* a3 = a2 + kstep; const char* b3 = b2 + kstep;
;             PG8_LDB(B0, 0, 0); PG8_LDB(B1, 0, 1); PG8_SCHED; PG8_LDA(At, 0, 0); PG8_STAGE(PG8_SA(1, 1), a1 + hstepA, voffA);
;             PG8_WAIT_V(8); PG8_WAIT_L(0); PG8_BAR; PG8_MMA(0, 0, At, B0); PG8_MMA(0, 1, At, B1); PG8_BAR; PG8_SCHED;
;             PG8_LDA(At, 0, 1); PG8_STAGE(PG8_SB(0, 0), b2, voffB); PG8_STAGE(PG8_SB(0, 1), b2 + hstepB, voffB); PG8_STAGE(PG8_SA(0, 0), a2, voffA);
;             PG8_WAIT_V(8); PG8_WAIT_L(0); PG8_BAR; PG8_MMA(1, 0, At, B0); PG8_MMA(1, 1, At, B1); PG8_BAR; PG8_SCHED;
.LBB0_1164:
	s_waitcnt lgkmcnt(0)
	ds_read_b128 v[132:135], v229
	ds_read_b128 v[136:139], v229 offset:1024
	ds_read_b128 v[140:143], v229 offset:2048
	ds_read_b128 v[144:147], v229 offset:3072
	ds_read_b128 v[148:151], v229 offset:16384
	ds_read_b128 v[152:155], v229 offset:17408
	ds_read_b128 v[156:159], v229 offset:18432
	ds_read_b128 v[160:163], v229 offset:19456
	s_add_i32 s20, s14, 2
	s_add_u32 s16, s12, 0xfff00080
	s_addc_u32 s17, s13, -1
	s_cmp_eq_u32 s1, s14
	s_cselect_b32 s19, s39, s17
	s_cselect_b32 s18, s38, s16
	s_cselect_b32 s17, s41, s11
	s_cselect_b32 s16, s40, s3
	v_lshl_add_u64 v[208:209], s[12:13], 0, v[204:205]
	s_add_i32 m0, s35, 0xc000
	ds_read_b128 v[164:167], v228
	ds_read_b128 v[168:171], v228 offset:1024
	ds_read_b128 v[172:175], v228 offset:2048
	ds_read_b128 v[176:179], v228 offset:3072
	ds_read_b128 v[180:183], v228 offset:4096
	ds_read_b128 v[184:187], v228 offset:5120
	ds_read_b128 v[188:191], v228 offset:6144
	ds_read_b128 v[192:195], v228 offset:7168
	global_load_lds_dwordx4 v[208:209], off
	v_lshl_add_u64 v[208:209], s[12:13], 0, v[206:207]
	s_add_i32 m0, s35, 0xe000
	s_nop 0
	global_load_lds_dwordx4 v[208:209], off
	s_waitcnt vmcnt(8)
	s_waitcnt lgkmcnt(0)
	s_barrier
	s_setprio 1
	v_mfma_f32_16x16x32_bf16 v[128:131], v[132:135], v[164:167], v[128:131]
	v_mfma_f32_16x16x32_bf16 v[124:127], v[140:143], v[164:167], v[124:127]
	v_mfma_f32_16x16x32_bf16 v[120:123], v[132:135], v[172:175], v[120:123]
	v_mfma_f32_16x16x32_bf16 v[116:119], v[140:143], v[172:175], v[116:119]
	v_mfma_f32_16x16x32_bf16 v[112:115], v[132:135], v[180:183], v[112:115]
	v_mfma_f32_16x16x32_bf16 v[108:111], v[140:143], v[180:183], v[108:111]
	v_mfma_f32_16x16x32_bf16 v[104:107], v[132:135], v[188:191], v[104:107]
	v_mfma_f32_16x16x32_bf16 v[100:103], v[140:143], v[188:191], v[100:103]
	v_mfma_f32_16x16x32_bf16 v[128:131], v[136:139], v[168:171], v[128:131]
	v_mfma_f32_16x16x32_bf16 v[124:127], v[144:147], v[168:171], v[124:127]
	v_mfma_f32_16x16x32_bf16 v[120:123], v[136:139], v[176:179], v[120:123]
	v_mfma_f32_16x16x32_bf16 v[116:119], v[144:147], v[176:179], v[116:119]
	v_mfma_f32_16x16x32_bf16 v[112:115], v[136:139], v[184:187], v[112:115]
	v_mfma_f32_16x16x32_bf16 v[108:111], v[144:147], v[184:187], v[108:111]
	v_mfma_f32_16x16x32_bf16 v[104:107], v[136:139], v[192:195], v[104:107]
	v_mfma_f32_16x16x32_bf16 v[100:103], v[144:147], v[192:195], v[100:103]
	v_mfma_f32_16x16x32_bf16 v[96:99], v[148:151], v[164:167], v[96:99]
	v_mfma_f32_16x16x32_bf16 v[92:95], v[156:159], v[164:167], v[92:95]
	v_mfma_f32_16x16x32_bf16 v[88:91], v[148:151], v[172:175], v[88:91]
	v_mfma_f32_16x16x32_bf16 v[80:83], v[156:159], v[172:175], v[80:83]
	v_mfma_f32_16x16x32_bf16 v[64:67], v[148:151], v[180:183], v[64:67]
	v_mfma_f32_16x16x32_bf16 v[52:55], v[156:159], v[180:183], v[52:55]
	v_mfma_f32_16x16x32_bf16 v[32:35], v[148:151], v[188:191], v[32:35]
	v_mfma_f32_16x16x32_bf16 v[20:23], v[156:159], v[188:191], v[20:23]
	v_mfma_f32_16x16x32_bf16 v[96:99], v[152:155], v[168:171], v[96:99]
	v_mfma_f32_16x16x32_bf16 v[92:95], v[160:163], v[168:171], v[92:95]
	v_mfma_f32_16x16x32_bf16 v[88:91], v[152:155], v[176:179], v[88:91]
	v_mfma_f32_16x16x32_bf16 v[80:83], v[160:163], v[176:179], v[80:83]
	v_mfma_f32_16x16x32_bf16 v[64:67], v[152:155], v[184:187], v[64:67]
	v_mfma_f32_16x16x32_bf16 v[52:55], v[160:163], v[184:187], v[52:55]
	v_mfma_f32_16x16x32_bf16 v[32:35], v[152:155], v[192:195], v[32:35]
	v_mfma_f32_16x16x32_bf16 v[20:23], v[160:163], v[192:195], v[20:23]
	s_setprio 0
	s_barrier
	s_mov_b32 m0, s44
	v_lshl_add_u64 v[208:209], s[16:17], 0, v[198:199]
	s_add_u32 s62, s16, 0x100000
	ds_read_b128 v[164:167], v228 offset:16384
	ds_read_b128 v[168:171], v228 offset:17408
	ds_read_b128 v[172:175], v228 offset:18432
	ds_read_b128 v[176:179], v228 offset:19456
	ds_read_b128 v[180:183], v228 offset:20480
	ds_read_b128 v[184:187], v228 offset:21504
	ds_read_b128 v[188:191], v228 offset:22528
	ds_read_b128 v[192:195], v228 offset:23552
	global_load_lds_dwordx4 v[208:209], off
	v_lshl_add_u64 v[210:211], s[16:17], 0, v[202:203]
	s_mov_b32 m0, s45
	s_addc_u32 s63, s17, 0
	global_load_lds_dwordx4 v[210:211], off
	v_lshl_add_u64 v[212:213], s[62:63], 0, v[198:199]
	s_mov_b32 m0, s46
	v_lshl_add_u64 v[214:215], s[18:19], 0, v[200:201]
	global_load_lds_dwordx4 v[212:213], off
	v_lshl_add_u64 v[212:213], s[62:63], 0, v[202:203]
	s_mov_b32 m0, s47
	s_nop 0
	global_load_lds_dwordx4 v[212:213], off
	v_lshl_add_u64 v[212:213], s[18:19], 0, v[196:197]
	s_mov_b32 m0, s35
	s_nop 0
	global_load_lds_dwordx4 v[212:213], off
	s_mov_b32 m0, s48
	s_nop 0
	global_load_lds_dwordx4 v[214:215], off
	s_waitcnt vmcnt(8)
	s_waitcnt lgkmcnt(0)
	s_barrier
; #define PG8_STAGE(bufoff, gbase, voff) do { _Pragma("unroll") for (int _i = 0; _i < 2; ++_i) \
;         __builtin_amdgcn_global_load_lds((const unsigned*)((const char*)(gbase) + (voff)[_i]), (LAS unsigned*)(lds + (bufoff) + ldsw + _i * 8192), 16, 0, 0); } while (0)
; #define PG8_LDA(dst, b, h) do { _Pragma("unroll") for (int m = 0; m < 4; ++m) _Pragma("unroll") for (int k = 0; k < 2; ++k) dst[m][k] = *(const LAS bf16x8*)(pA + PG8_SA(b, h) + m * 2048 + k * 1024); } while (0)
; #define PG8_LDB(dst, b, h) do { _Pragma("unroll") for (int n = 0; n < 2; ++n) _Pragma("unroll") for (int k = 0; k < 2; ++k) dst[n][k] = *(const LAS bf16x8*)(pB + (PG8_SB(b, h) - 4 * HTB) + n * 2048 + k * 1024); } while (0)
; #define PG8_MMA(ai, bj, At, Bt) do { __builtin_amdgcn_s_setprio(1); _Pragma("unroll") for (int m = 0; m < 4; ++m) _Pragma("unroll") for (int n = 0; n < 2; ++n) _Pragma("unroll") for (int k = 0; k < 2; ++k) \
;         acc[ai][bj][m][n] = __builtin_amdgcn_mfma_f32_16x16x32_bf16(Bt[n][k], At[m][k], acc[ai][bj][m][n], 0, 0, 0); __builtin_amdgcn_s_setprio(0); } while (0)
; #define PG8_WAIT_V(n) asm volatile("s_waitcnt vmcnt(" #n ")" ::: "memory")
; #define PG8_WAIT_L(n) asm volatile("s_waitcnt lgkmcnt(" #n ")" ::: "memory")
; #define PG8_BAR __builtin_amdgcn_s_barrier()
; #define PG8_SCHED __builtin_amdgcn_sched_barrier(0)
; template <class Desc, class Epi, bool ALIGN_EPI>
; __device__ __forceinline__ void gemm_phase(LAS unsigned char* lds, const Desc& D, const Epi& E, int G, int c) {
;     ...
;             PG8_WAIT_V(8); PG8_WAIT_L(0); PG8_BAR; PG8_MMA(1, 0, At, B0); PG8_MMA(1, 1, At, B1); PG8_BAR; PG8_SCHED;
;             PG8_LDB(B0, 1, 0); PG8_LDB(B1, 1, 1); PG8_SCHED; PG8_LDA(At, 1, 0); PG8_STAGE(PG8_SA(0, 1), a2 + hstepA, voffA);
;             PG8_WAIT_V(8); PG8_WAIT_L(0); PG8_BAR; PG8_MMA(0, 0, At, B0); PG8_MMA(0, 1, At, B1); PG8_BAR; PG8_SCHED;
	s_setprio 1
	v_mfma_f32_16x16x32_bf16 v[84:87], v[132:135], v[164:167], v[84:87]
	v_mfma_f32_16x16x32_bf16 v[76:79], v[140:143], v[164:167], v[76:79]
	v_mfma_f32_16x16x32_bf16 v[72:75], v[132:135], v[172:175], v[72:75]
	v_mfma_f32_16x16x32_bf16 v[68:71], v[140:143], v[172:175], v[68:71]
	v_mfma_f32_16x16x32_bf16 v[60:63], v[132:135], v[180:183], v[60:63]
	v_mfma_f32_16x16x32_bf16 v[56:59], v[140:143], v[180:183], v[56:59]
	v_mfma_f32_16x16x32_bf16 v[48:51], v[132:135], v[188:191], v[48:51]
	v_mfma_f32_16x16x32_bf16 v[44:47], v[140:143], v[188:191], v[44:47]
	v_mfma_f32_16x16x32_bf16 v[84:87], v[136:139], v[168:171], v[84:87]
	v_mfma_f32_16x16x32_bf16 v[76:79], v[144:147], v[168:171], v[76:79]
	v_mfma_f32_16x16x32_bf16 v[72:75], v[136:139], v[176:179], v[72:75]
	v_mfma_f32_16x16x32_bf16 v[68:71], v[144:147], v[176:179], v[68:71]
	v_mfma_f32_16x16x32_bf16 v[60:63], v[136:139], v[184:187], v[60:63]
	v_mfma_f32_16x16x32_bf16 v[56:59], v[144:147], v[184:187], v[56:59]
	v_mfma_f32_16x16x32_bf16 v[48:51], v[136:139], v[192:195], v[48:51]
	v_mfma_f32_16x16x32_bf16 v[44:47], v[144:147], v[192:195], v[44:47]
	v_mfma_f32_16x16x32_bf16 v[40:43], v[148:151], v[164:167], v[40:43]
	v_mfma_f32_16x16x32_bf16 v[36:39], v[156:159], v[164:167], v[36:39]
	v_mfma_f32_16x16x32_bf16 v[28:31], v[148:151], v[172:175], v[28:31]
	v_mfma_f32_16x16x32_bf16 v[24:27], v[156:159], v[172:175], v[24:27]
	v_mfma_f32_16x16x32_bf16 v[16:19], v[148:151], v[180:183], v[16:19]
	v_mfma_f32_16x16x32_bf16 v[12:15], v[156:159], v[180:183], v[12:15]
	v_mfma_f32_16x16x32_bf16 v[8:11], v[148:151], v[188:191], v[8:11]
	v_mfma_f32_16x16x32_bf16 v[4:7], v[156:159], v[188:191], v[4:7]
	v_mfma_f32_16x16x32_bf16 v[40:43], v[152:155], v[168:171], v[40:43]
	v_mfma_f32_16x16x32_bf16 v[36:39], v[160:163], v[168:171], v[36:39]
	v_mfma_f32_16x16x32_bf16 v[28:31], v[152:155], v[176:179], v[28:31]
	v_mfma_f32_16x16x32_bf16 v[24:27], v[160:163], v[176:179], v[24:27]
	v_mfma_f32_16x16x32_bf16 v[16:19], v[152:155], v[184:187], v[16:19]
	v_mfma_f32_16x16x32_bf16 v[12:15], v[160:163], v[184:187], v[12:15]
	v_mfma_f32_16x16x32_bf16 v[8:11], v[152:155], v[192:195], v[8:11]
	v_mfma_f32_16x16x32_bf16 v[4:7], v[160:163], v[192:195], v[4:7]
	s_setprio 0
	s_barrier
	ds_read_b128 v[132:135], v229 offset:32768
	ds_read_b128 v[136:139], v229 offset:33792
	ds_read_b128 v[140:143], v229 offset:34816
	ds_read_b128 v[144:147], v229 offset:35840
	ds_read_b128 v[148:151], v229 offset:49152
	ds_read_b128 v[152:155], v229 offset:50176
	ds_read_b128 v[156:159], v229 offset:51200
	ds_read_b128 v[160:163], v229 offset:52224
	s_add_u32 s18, s18, 0x100000
	s_addc_u32 s19, s19, 0
	s_mov_b32 m0, s49
	v_lshl_add_u64 v[216:217], s[18:19], 0, v[196:197]
	ds_read_b128 v[164:167], v228 offset:32768
	ds_read_b128 v[168:171], v228 offset:33792
	ds_read_b128 v[172:175], v228 offset:34816
	ds_read_b128 v[176:179], v228 offset:35840
	ds_read_b128 v[180:183], v228 offset:36864
	ds_read_b128 v[184:187], v228 offset:37888
	ds_read_b128 v[188:191], v228 offset:38912
	ds_read_b128 v[192:195], v228 offset:39936
	global_load_lds_dwordx4 v[216:217], off
	v_lshl_add_u64 v[216:217], s[18:19], 0, v[200:201]
	s_mov_b32 m0, s50
	s_nop 0
	global_load_lds_dwordx4 v[216:217], off
	s_waitcnt vmcnt(8)
	s_waitcnt lgkmcnt(0)
	s_barrier
	s_setprio 1
	v_mfma_f32_16x16x32_bf16 v[128:131], v[132:135], v[164:167], v[128:131]
	v_mfma_f32_16x16x32_bf16 v[124:127], v[140:143], v[164:167], v[124:127]
	v_mfma_f32_16x16x32_bf16 v[120:123], v[132:135], v[172:175], v[120:123]
	v_mfma_f32_16x16x32_bf16 v[116:119], v[140:143], v[172:175], v[116:119]
	v_mfma_f32_16x16x32_bf16 v[112:115], v[132:135], v[180:183], v[112:115]
	v_mfma_f32_16x16x32_bf16 v[108:111], v[140:143], v[180:183], v[108:111]
	v_mfma_f32_16x16x32_bf16 v[104:107], v[132:135], v[188:191], v[104:107]
	v_mfma_f32_16x16x32_bf16 v[100:103], v[140:143], v[188:191], v[100:103]
	v_mfma_f32_16x16x32_bf16 v[128:131], v[136:139], v[168:171], v[128:131]
	v_mfma_f32_16x16x32_bf16 v[124:127], v[144:147], v[168:171], v[124:127]
	v_mfma_f32_16x16x32_bf16 v[120:123], v[136:139], v[176:179], v[120:123]
	v_mfma_f32_16x16x32_bf16 v[116:119], v[144:147], v[176:179], v[116:119]
	v_mfma_f32_16x16x32_bf16 v[112:115], v[136:139], v[184:187], v[112:115]
	v_mfma_f32_16x16x32_bf16 v[108:111], v[144:147], v[184:187], v[108:111]
	v_mfma_f32_16x16x32_bf16 v[104:107], v[136:139], v[192:195], v[104:107]
	v_mfma_f32_16x16x32_bf16 v[100:103], v[144:147], v[192:195], v[100:103]
	v_mfma_f32_16x16x32_bf16 v[96:99], v[148:151], v[164:167], v[96:99]
	v_mfma_f32_16x16x32_bf16 v[92:95], v[156:159], v[164:167], v[92:95]
	v_mfma_f32_16x16x32_bf16 v[88:91], v[148:151], v[172:175], v[88:91]
	v_mfma_f32_16x16x32_bf16 v[80:83], v[156:159], v[172:175], v[80:83]
	v_mfma_f32_16x16x32_bf16 v[64:67], v[148:151], v[180:183], v[64:67]
	v_mfma_f32_16x16x32_bf16 v[52:55], v[156:159], v[180:183], v[52:55]
	v_mfma_f32_16x16x32_bf16 v[32:35], v[148:151], v[188:191], v[32:35]
	v_mfma_f32_16x16x32_bf16 v[20:23], v[156:159], v[188:191], v[20:23]
	v_mfma_f32_16x16x32_bf16 v[96:99], v[152:155], v[168:171], v[96:99]
	v_mfma_f32_16x16x32_bf16 v[92:95], v[160:163], v[168:171], v[92:95]
	v_mfma_f32_16x16x32_bf16 v[88:91], v[152:155], v[176:179], v[88:91]
	v_mfma_f32_16x16x32_bf16 v[80:83], v[160:163], v[176:179], v[80:83]
	v_mfma_f32_16x16x32_bf16 v[64:67], v[152:155], v[184:187], v[64:67]
	v_mfma_f32_16x16x32_bf16 v[52:55], v[160:163], v[184:187], v[52:55]
	v_mfma_f32_16x16x32_bf16 v[32:35], v[152:155], v[192:195], v[32:35]
	v_mfma_f32_16x16x32_bf16 v[20:23], v[160:163], v[192:195], v[20:23]
	s_setprio 0
	s_barrier
;     __device__ __forceinline__ int nt(const Unit& u) const { return (u.pn >> 1) < 2 ? 22 : 20; }
; #define PG8_STAGE(bufoff, gbase, voff) do { _Pragma("unroll") for (int _i = 0; _i < 2; ++_i) \
;         __builtin_amdgcn_global_load_lds((const unsigned*)((const char*)(gbase) + (voff)[_i]), (LAS unsigned*)(lds + (bufoff) + ldsw + _i * 8192), 16, 0, 0); } while (0)
; #define PG8_LDA(dst, b, h) do { _Pragma("unroll") for (int m = 0; m < 4; ++m) _Pragma("unroll") for (int k = 0; k < 2; ++k) dst[m][k] = *(const LAS bf16x8*)(pA + PG8_SA(b, h) + m * 2048 + k * 1024); } while (0)
; #define PG8_MMA(ai, bj, At, Bt) do { __builtin_amdgcn_s_setprio(1); _Pragma("unroll") for (int m = 0; m < 4; ++m) _Pragma("unroll") for (int n = 0; n < 2; ++n) _Pragma("unroll") for (int k = 0; k < 2; ++k) \
;         acc[ai][bj][m][n] = __builtin_amdgcn_mfma_f32_16x16x32_bf16(Bt[n][k], At[m][k], acc[ai][bj][m][n], 0, 0, 0); __builtin_amdgcn_s_setprio(0); } while (0)
; #define PG8_WAIT_V(n) asm volatile("s_waitcnt vmcnt(" #n ")" ::: "memory")
; #define PG8_WAIT_L(n) asm volatile("s_waitcnt lgkmcnt(" #n ")" ::: "memory")
; #define PG8_BAR __builtin_amdgcn_s_barrier()
; #define PG8_SCHED __builtin_amdgcn_sched_barrier(0)
; template <class Desc, class Epi, bool ALIGN_EPI>
; __device__ __forceinline__ void gemm_phase(LAS unsigned char* lds, const Desc& D, const Epi& E, int G, int c) {
;     ...
;         for (int t = 0; t < nt; t += 2) {
;     ...
;             PG8_LDA(At, 1, 1); PG8_STAGE(PG8_SB(1, 0), b3, voffB); PG8_STAGE(PG8_SB(1, 1), b3 + hstepB, voffB); PG8_STAGE(PG8_SA(1, 0), a3, voffA);
;             PG8_WAIT_V(8); PG8_WAIT_L(0); PG8_BAR; PG8_MMA(1, 0, At, B0); PG8_MMA(1, 1, At, B1); PG8_BAR; PG8_SCHED;
;         }
	s_mov_b32 m0, s52
	v_lshl_add_u64 v[208:209], v[208:209], 0, s[76:77]
	s_add_u32 s16, s16, 0x100080
	ds_read_b128 v[164:167], v228 offset:49152
	ds_read_b128 v[168:171], v228 offset:50176
	ds_read_b128 v[172:175], v228 offset:51200
	ds_read_b128 v[176:179], v228 offset:52224
	ds_read_b128 v[180:183], v228 offset:53248
	ds_read_b128 v[184:187], v228 offset:54272
	ds_read_b128 v[188:191], v228 offset:55296
	ds_read_b128 v[192:195], v228 offset:56320
	global_load_lds_dwordx4 v[208:209], off
	v_lshl_add_u64 v[208:209], v[210:211], 0, s[76:77]
	s_mov_b32 m0, s53
	s_addc_u32 s17, s17, 0
	global_load_lds_dwordx4 v[208:209], off
	v_lshl_add_u64 v[208:209], s[16:17], 0, v[198:199]
	s_mov_b32 m0, s56
	s_nop 0
	global_load_lds_dwordx4 v[208:209], off
	v_lshl_add_u64 v[208:209], s[16:17], 0, v[202:203]
	s_mov_b32 m0, s57
	s_nop 0
	global_load_lds_dwordx4 v[208:209], off
	v_lshl_add_u64 v[208:209], v[212:213], 0, s[76:77]
	s_mov_b32 m0, s54
	s_nop 0
	global_load_lds_dwordx4 v[208:209], off
	v_lshl_add_u64 v[208:209], v[214:215], 0, s[76:77]
	s_mov_b32 m0, s55
	s_nop 0
	global_load_lds_dwordx4 v[208:209], off
	s_waitcnt vmcnt(8)
	s_waitcnt lgkmcnt(0)
	s_barrier
	s_setprio 1
	v_mfma_f32_16x16x32_bf16 v[84:87], v[132:135], v[164:167], v[84:87]
	v_mfma_f32_16x16x32_bf16 v[76:79], v[140:143], v[164:167], v[76:79]
	v_mfma_f32_16x16x32_bf16 v[72:75], v[132:135], v[172:175], v[72:75]
	v_mfma_f32_16x16x32_bf16 v[68:71], v[140:143], v[172:175], v[68:71]
	v_mfma_f32_16x16x32_bf16 v[60:63], v[132:135], v[180:183], v[60:63]
	v_mfma_f32_16x16x32_bf16 v[56:59], v[140:143], v[180:183], v[56:59]
	v_mfma_f32_16x16x32_bf16 v[48:51], v[132:135], v[188:191], v[48:51]
	v_mfma_f32_16x16x32_bf16 v[44:47], v[140:143], v[188:191], v[44:47]
	v_mfma_f32_16x16x32_bf16 v[84:87], v[136:139], v[168:171], v[84:87]
	v_mfma_f32_16x16x32_bf16 v[76:79], v[144:147], v[168:171], v[76:79]
	v_mfma_f32_16x16x32_bf16 v[72:75], v[136:139], v[176:179], v[72:75]
	v_mfma_f32_16x16x32_bf16 v[68:71], v[144:147], v[176:179], v[68:71]
	v_mfma_f32_16x16x32_bf16 v[60:63], v[136:139], v[184:187], v[60:63]
	v_mfma_f32_16x16x32_bf16 v[56:59], v[144:147], v[184:187], v[56:59]
	v_mfma_f32_16x16x32_bf16 v[48:51], v[136:139], v[192:195], v[48:51]
	v_mfma_f32_16x16x32_bf16 v[44:47], v[144:147], v[192:195], v[44:47]
	v_mfma_f32_16x16x32_bf16 v[40:43], v[148:151], v[164:167], v[40:43]
	v_mfma_f32_16x16x32_bf16 v[36:39], v[156:159], v[164:167], v[36:39]
	v_mfma_f32_16x16x32_bf16 v[28:31], v[148:151], v[172:175], v[28:31]
	v_mfma_f32_16x16x32_bf16 v[24:27], v[156:159], v[172:175], v[24:27]
	v_mfma_f32_16x16x32_bf16 v[16:19], v[148:151], v[180:183], v[16:19]
	v_mfma_f32_16x16x32_bf16 v[12:15], v[156:159], v[180:183], v[12:15]
	v_mfma_f32_16x16x32_bf16 v[8:11], v[148:151], v[188:191], v[8:11]
	v_mfma_f32_16x16x32_bf16 v[4:7], v[156:159], v[188:191], v[4:7]
	v_mfma_f32_16x16x32_bf16 v[40:43], v[152:155], v[168:171], v[40:43]
	v_mfma_f32_16x16x32_bf16 v[36:39], v[160:163], v[168:171], v[36:39]
	v_mfma_f32_16x16x32_bf16 v[28:31], v[152:155], v[176:179], v[28:31]
	v_mfma_f32_16x16x32_bf16 v[24:27], v[160:163], v[176:179], v[24:27]
	v_mfma_f32_16x16x32_bf16 v[16:19], v[152:155], v[184:187], v[16:19]
	v_mfma_f32_16x16x32_bf16 v[12:15], v[160:163], v[184:187], v[12:15]
	v_mfma_f32_16x16x32_bf16 v[8:11], v[152:155], v[192:195], v[8:11]
	v_mfma_f32_16x16x32_bf16 v[4:7], v[160:163], v[192:195], v[4:7]
	s_setprio 0
	s_barrier
	s_add_u32 s12, s12, 0x100
	s_addc_u32 s13, s13, 0
	s_add_u32 s3, s3, 0x100
	s_addc_u32 s11, s11, 0
	s_cmp_ge_u32 s20, s2
	s_mov_b32 s14, s20
	s_cbranch_scc0 .LBB0_1164
	s_and_b64 vcc, exec, s[8:9]
	s_cbranch_vccz .LBB0_1167
	s_barrier

; #define PG8_STAGE(bufoff, gbase, voff) do { _Pragma("unroll") for (int _i = 0; _i < 2; ++_i) \
;         __builtin_amdgcn_global_load_lds((const unsigned*)((const char*)(gbase) + (voff)[_i]), (LAS unsigned*)(lds + (bufoff) + ldsw + _i * 8192), 16, 0, 0); } while (0)
; #define PG8_LDA(dst, b, h) do { _Pragma("unroll") for (int m = 0; m < 4; ++m) _Pragma("unroll") for (int k = 0; k < 2; ++k) dst[m][k] = *(const LAS bf16x8*)(pA + PG8_SA(b, h) + m * 2048 + k * 1024); } while (0)
; #define PG8_LDB(dst, b, h) do { _Pragma("unroll") for (int n = 0; n < 2; ++n) _Pragma("unroll") for (int k = 0; k < 2; ++k) dst[n][k] = *(const LAS bf16x8*)(pB + (PG8_SB(b, h) - 4 * HTB) + n * 2048 + k * 1024); } while (0)
; #define PG8_MMA(ai, bj, At, Bt) do { __builtin_amdgcn_s_setprio(1); _Pragma("unroll") for (int m = 0; m < 4; ++m) _Pragma("unroll") for (int n = 0; n < 2; ++n) _Pragma("unroll") for (int k = 0; k < 2; ++k) \
;         acc[ai][bj][m][n] = __builtin_amdgcn_mfma_f32_16x16x32_bf16(Bt[n][k], At[m][k], acc[ai][bj][m][n], 0, 0, 0); __builtin_amdgcn_s_setprio(0); } while (0)
; #define PG8_WAIT_V(n) asm volatile("s_waitcnt vmcnt(" #n ")" ::: "memory")
; #define PG8_WAIT_L(n) asm volatile("s_waitcnt lgkmcnt(" #n ")" ::: "memory")
; #define PG8_BAR __builtin_amdgcn_s_barrier()
; #define PG8_SCHED __builtin_amdgcn_sched_barrier(0)
; template <class Desc, class Epi, bool ALIGN_EPI>
; __device__ __forceinline__ void gemm_phase(LAS unsigned char* lds, const Desc& D, const Epi& E, int G, int c) {
;     ...
;             const char* a1 = cA + (size_t)(t + 1) * kstep;
;             const char* a2 = last ? nA : cA + (size_t)(t + 2) * kstep; const char* b2 = last ? nB : cB + (size_t)(t + 2) * kstep;
;             const char* a3 = a2 + kstep; const char* b3 = b2 + kstep;
;             PG8_LDB(B0, 0, 0); PG8_LDB(B1, 0, 1); PG8_SCHED; PG8_LDA(At, 0, 0); PG8_STAGE(PG8_SA(1, 1), a1 + hstepA, voffA);
;             PG8_WAIT_V(8); PG8_WAIT_L(0); PG8_BAR; PG8_MMA(0, 0, At, B0); PG8_MMA(0, 1, At, B1); PG8_BAR; PG8_SCHED;
;             PG8_LDA(At, 0, 1); PG8_STAGE(PG8_SB(0, 0), b2, voffB); PG8_STAGE(PG8_SB(0, 1), b2 + hstepB, voffB); PG8_STAGE(PG8_SA(0, 0), a2, voffA);
;             PG8_WAIT_V(8); PG8_WAIT_L(0); PG8_BAR; PG8_MMA(1, 0, At, B0); PG8_MMA(1, 1, At, B1); PG8_BAR; PG8_SCHED;
.LBB0_1324:
	ds_read_b128 v[144:147], v149
	ds_read_b128 v[152:155], v149 offset:1024
	ds_read_b128 v[156:159], v149 offset:2048
	ds_read_b128 v[160:163], v149 offset:3072
	ds_read_b128 v[164:167], v149 offset:16384
	ds_read_b128 v[168:171], v149 offset:17408
	ds_read_b128 v[172:175], v149 offset:18432
	ds_read_b128 v[176:179], v149 offset:19456
	s_add_i32 s50, s18, 2
	s_add_u32 s19, s16, 0xfff00080
	s_addc_u32 s20, s17, -1
	s_cmp_eq_u32 s9, s18
	s_cselect_b32 s18, s12, s48
	s_cselect_b32 s21, s11, s20
	s_cselect_b32 s20, s10, s19
	s_cselect_b32 s19, s13, s49
	v_lshl_add_u64 v[212:213], s[16:17], 0, v[140:141]
	s_add_i32 m0, s24, 0xc000
	ds_read_b128 v[180:183], v148
	ds_read_b128 v[184:187], v148 offset:1024
	ds_read_b128 v[188:191], v148 offset:2048
	ds_read_b128 v[192:195], v148 offset:3072
	ds_read_b128 v[196:199], v148 offset:4096
	ds_read_b128 v[200:203], v148 offset:5120
	ds_read_b128 v[204:207], v148 offset:6144
	ds_read_b128 v[208:211], v148 offset:7168
	global_load_lds_dwordx4 v[212:213], off
	v_lshl_add_u64 v[212:213], s[16:17], 0, v[142:143]
	s_add_i32 m0, s24, 0xe000
	s_nop 0
	global_load_lds_dwordx4 v[212:213], off
	s_waitcnt vmcnt(8)
	s_waitcnt lgkmcnt(0)
	s_barrier
	s_setprio 1
	v_mfma_f32_16x16x32_bf16 v[128:131], v[144:147], v[180:183], v[128:131]
	v_mfma_f32_16x16x32_bf16 v[124:127], v[156:159], v[180:183], v[124:127]
	v_mfma_f32_16x16x32_bf16 v[120:123], v[144:147], v[188:191], v[120:123]
	v_mfma_f32_16x16x32_bf16 v[112:115], v[156:159], v[188:191], v[112:115]
	v_mfma_f32_16x16x32_bf16 v[104:107], v[144:147], v[196:199], v[104:107]
	v_mfma_f32_16x16x32_bf16 v[96:99], v[156:159], v[196:199], v[96:99]
	v_mfma_f32_16x16x32_bf16 v[88:91], v[144:147], v[204:207], v[88:91]
	v_mfma_f32_16x16x32_bf16 v[80:83], v[156:159], v[204:207], v[80:83]
	v_mfma_f32_16x16x32_bf16 v[128:131], v[152:155], v[184:187], v[128:131]
	v_mfma_f32_16x16x32_bf16 v[124:127], v[160:163], v[184:187], v[124:127]
	v_mfma_f32_16x16x32_bf16 v[120:123], v[152:155], v[192:195], v[120:123]
	v_mfma_f32_16x16x32_bf16 v[112:115], v[160:163], v[192:195], v[112:115]
	v_mfma_f32_16x16x32_bf16 v[104:107], v[152:155], v[200:203], v[104:107]
	v_mfma_f32_16x16x32_bf16 v[96:99], v[160:163], v[200:203], v[96:99]
	v_mfma_f32_16x16x32_bf16 v[88:91], v[152:155], v[208:211], v[88:91]
	v_mfma_f32_16x16x32_bf16 v[80:83], v[160:163], v[208:211], v[80:83]
	v_mfma_f32_16x16x32_bf16 v[116:119], v[164:167], v[180:183], v[116:119]
	v_mfma_f32_16x16x32_bf16 v[108:111], v[172:175], v[180:183], v[108:111]
	v_mfma_f32_16x16x32_bf16 v[100:103], v[164:167], v[188:191], v[100:103]
	v_mfma_f32_16x16x32_bf16 v[92:95], v[172:175], v[188:191], v[92:95]
	v_mfma_f32_16x16x32_bf16 v[84:87], v[164:167], v[196:199], v[84:87]
	v_mfma_f32_16x16x32_bf16 v[76:79], v[172:175], v[196:199], v[76:79]
	v_mfma_f32_16x16x32_bf16 v[72:75], v[164:167], v[204:207], v[72:75]
	v_mfma_f32_16x16x32_bf16 v[68:71], v[172:175], v[204:207], v[68:71]
	v_mfma_f32_16x16x32_bf16 v[116:119], v[168:171], v[184:187], v[116:119]
	v_mfma_f32_16x16x32_bf16 v[108:111], v[176:179], v[184:187], v[108:111]
	v_mfma_f32_16x16x32_bf16 v[100:103], v[168:171], v[192:195], v[100:103]
	v_mfma_f32_16x16x32_bf16 v[92:95], v[176:179], v[192:195], v[92:95]
	v_mfma_f32_16x16x32_bf16 v[84:87], v[168:171], v[200:203], v[84:87]
	v_mfma_f32_16x16x32_bf16 v[76:79], v[176:179], v[200:203], v[76:79]
	v_mfma_f32_16x16x32_bf16 v[72:75], v[168:171], v[208:211], v[72:75]
	v_mfma_f32_16x16x32_bf16 v[68:71], v[176:179], v[208:211], v[68:71]
	s_setprio 0
	s_barrier
	s_mov_b32 m0, s25
	v_lshl_add_u64 v[212:213], s[18:19], 0, v[136:137]
	s_add_u32 s52, s18, 0x100000
	ds_read_b128 v[180:183], v148 offset:16384
	ds_read_b128 v[184:187], v148 offset:17408
	ds_read_b128 v[188:191], v148 offset:18432
	ds_read_b128 v[192:195], v148 offset:19456
	ds_read_b128 v[196:199], v148 offset:20480
	ds_read_b128 v[200:203], v148 offset:21504
	ds_read_b128 v[204:207], v148 offset:22528
	ds_read_b128 v[208:211], v148 offset:23552
	global_load_lds_dwordx4 v[212:213], off
	v_lshl_add_u64 v[214:215], s[18:19], 0, v[132:133]
	s_mov_b32 m0, s26
	s_addc_u32 s53, s19, 0
	global_load_lds_dwordx4 v[214:215], off
	v_lshl_add_u64 v[216:217], s[52:53], 0, v[136:137]
	s_mov_b32 m0, s27
	v_lshl_add_u64 v[218:219], s[20:21], 0, v[134:135]
	global_load_lds_dwordx4 v[216:217], off
	v_lshl_add_u64 v[216:217], s[52:53], 0, v[132:133]
	s_mov_b32 m0, s30
	s_nop 0
	global_load_lds_dwordx4 v[216:217], off
	v_lshl_add_u64 v[216:217], s[20:21], 0, v[138:139]
	s_mov_b32 m0, s24
	s_nop 0
	global_load_lds_dwordx4 v[216:217], off
	s_mov_b32 m0, s31
	s_nop 0
	global_load_lds_dwordx4 v[218:219], off
	s_waitcnt vmcnt(8)
	s_waitcnt lgkmcnt(0)
	s_barrier
; #define PG8_STAGE(bufoff, gbase, voff) do { _Pragma("unroll") for (int _i = 0; _i < 2; ++_i) \
;         __builtin_amdgcn_global_load_lds((const unsigned*)((const char*)(gbase) + (voff)[_i]), (LAS unsigned*)(lds + (bufoff) + ldsw + _i * 8192), 16, 0, 0); } while (0)
; #define PG8_LDA(dst, b, h) do { _Pragma("unroll") for (int m = 0; m < 4; ++m) _Pragma("unroll") for (int k = 0; k < 2; ++k) dst[m][k] = *(const LAS bf16x8*)(pA + PG8_SA(b, h) + m * 2048 + k * 1024); } while (0)
; #define PG8_LDB(dst, b, h) do { _Pragma("unroll") for (int n = 0; n < 2; ++n) _Pragma("unroll") for (int k = 0; k < 2; ++k) dst[n][k] = *(const LAS bf16x8*)(pB + (PG8_SB(b, h) - 4 * HTB) + n * 2048 + k * 1024); } while (0)
; #define PG8_MMA(ai, bj, At, Bt) do { __builtin_amdgcn_s_setprio(1); _Pragma("unroll") for (int m = 0; m < 4; ++m) _Pragma("unroll") for (int n = 0; n < 2; ++n) _Pragma("unroll") for (int k = 0; k < 2; ++k) \
;         acc[ai][bj][m][n] = __builtin_amdgcn_mfma_f32_16x16x32_bf16(Bt[n][k], At[m][k], acc[ai][bj][m][n], 0, 0, 0); __builtin_amdgcn_s_setprio(0); } while (0)
; #define PG8_WAIT_V(n) asm volatile("s_waitcnt vmcnt(" #n ")" ::: "memory")
; #define PG8_WAIT_L(n) asm volatile("s_waitcnt lgkmcnt(" #n ")" ::: "memory")
; #define PG8_BAR __builtin_amdgcn_s_barrier()
; #define PG8_SCHED __builtin_amdgcn_sched_barrier(0)
; template <class Desc, class Epi, bool ALIGN_EPI>
; __device__ __forceinline__ void gemm_phase(LAS unsigned char* lds, const Desc& D, const Epi& E, int G, int c) {
;     ...
;             PG8_WAIT_V(8); PG8_WAIT_L(0); PG8_BAR; PG8_MMA(1, 0, At, B0); PG8_MMA(1, 1, At, B1); PG8_BAR; PG8_SCHED;
;             PG8_LDB(B0, 1, 0); PG8_LDB(B1, 1, 1); PG8_SCHED; PG8_LDA(At, 1, 0); PG8_STAGE(PG8_SA(0, 1), a2 + hstepA, voffA);
;             PG8_WAIT_V(8); PG8_WAIT_L(0); PG8_BAR; PG8_MMA(0, 0, At, B0); PG8_MMA(0, 1, At, B1); PG8_BAR; PG8_SCHED;
	s_setprio 1
	v_mfma_f32_16x16x32_bf16 v[64:67], v[144:147], v[180:183], v[64:67]
	v_mfma_f32_16x16x32_bf16 v[60:63], v[156:159], v[180:183], v[60:63]
	v_mfma_f32_16x16x32_bf16 v[56:59], v[144:147], v[188:191], v[56:59]
	v_mfma_f32_16x16x32_bf16 v[48:51], v[156:159], v[188:191], v[48:51]
	v_mfma_f32_16x16x32_bf16 v[40:43], v[144:147], v[196:199], v[40:43]
	v_mfma_f32_16x16x32_bf16 v[32:35], v[156:159], v[196:199], v[32:35]
	v_mfma_f32_16x16x32_bf16 v[24:27], v[144:147], v[204:207], v[24:27]
	v_mfma_f32_16x16x32_bf16 v[16:19], v[156:159], v[204:207], v[16:19]
	v_mfma_f32_16x16x32_bf16 v[64:67], v[152:155], v[184:187], v[64:67]
	v_mfma_f32_16x16x32_bf16 v[60:63], v[160:163], v[184:187], v[60:63]
	v_mfma_f32_16x16x32_bf16 v[56:59], v[152:155], v[192:195], v[56:59]
	v_mfma_f32_16x16x32_bf16 v[48:51], v[160:163], v[192:195], v[48:51]
	v_mfma_f32_16x16x32_bf16 v[40:43], v[152:155], v[200:203], v[40:43]
	v_mfma_f32_16x16x32_bf16 v[32:35], v[160:163], v[200:203], v[32:35]
	v_mfma_f32_16x16x32_bf16 v[24:27], v[152:155], v[208:211], v[24:27]
	v_mfma_f32_16x16x32_bf16 v[16:19], v[160:163], v[208:211], v[16:19]
	v_mfma_f32_16x16x32_bf16 v[52:55], v[164:167], v[180:183], v[52:55]
	v_mfma_f32_16x16x32_bf16 v[44:47], v[172:175], v[180:183], v[44:47]
	v_mfma_f32_16x16x32_bf16 v[36:39], v[164:167], v[188:191], v[36:39]
	v_mfma_f32_16x16x32_bf16 v[28:31], v[172:175], v[188:191], v[28:31]
	v_mfma_f32_16x16x32_bf16 v[20:23], v[164:167], v[196:199], v[20:23]
	v_mfma_f32_16x16x32_bf16 v[12:15], v[172:175], v[196:199], v[12:15]
	v_mfma_f32_16x16x32_bf16 v[8:11], v[164:167], v[204:207], v[8:11]
	v_mfma_f32_16x16x32_bf16 v[4:7], v[172:175], v[204:207], v[4:7]
	v_mfma_f32_16x16x32_bf16 v[52:55], v[168:171], v[184:187], v[52:55]
	v_mfma_f32_16x16x32_bf16 v[44:47], v[176:179], v[184:187], v[44:47]
	v_mfma_f32_16x16x32_bf16 v[36:39], v[168:171], v[192:195], v[36:39]
	v_mfma_f32_16x16x32_bf16 v[28:31], v[176:179], v[192:195], v[28:31]
	v_mfma_f32_16x16x32_bf16 v[20:23], v[168:171], v[200:203], v[20:23]
	v_mfma_f32_16x16x32_bf16 v[12:15], v[176:179], v[200:203], v[12:15]
	v_mfma_f32_16x16x32_bf16 v[8:11], v[168:171], v[208:211], v[8:11]
	v_mfma_f32_16x16x32_bf16 v[4:7], v[176:179], v[208:211], v[4:7]
	s_setprio 0
	s_barrier
	ds_read_b128 v[144:147], v149 offset:32768
	ds_read_b128 v[152:155], v149 offset:33792
	ds_read_b128 v[156:159], v149 offset:34816
	ds_read_b128 v[160:163], v149 offset:35840
	ds_read_b128 v[164:167], v149 offset:49152
	ds_read_b128 v[168:171], v149 offset:50176
	ds_read_b128 v[172:175], v149 offset:51200
	ds_read_b128 v[176:179], v149 offset:52224
	s_add_u32 s20, s20, 0x100000
	s_addc_u32 s21, s21, 0
	s_mov_b32 m0, s33
	v_lshl_add_u64 v[220:221], s[20:21], 0, v[138:139]
	ds_read_b128 v[180:183], v148 offset:32768
	ds_read_b128 v[184:187], v148 offset:33792
	ds_read_b128 v[188:191], v148 offset:34816
	ds_read_b128 v[192:195], v148 offset:35840
	ds_read_b128 v[196:199], v148 offset:36864
	ds_read_b128 v[200:203], v148 offset:37888
	ds_read_b128 v[204:207], v148 offset:38912
	ds_read_b128 v[208:211], v148 offset:39936
	global_load_lds_dwordx4 v[220:221], off
	v_lshl_add_u64 v[220:221], s[20:21], 0, v[134:135]
	s_mov_b32 m0, s34
	s_nop 0
	global_load_lds_dwordx4 v[220:221], off
	s_waitcnt vmcnt(8)
	s_waitcnt lgkmcnt(0)
	s_barrier
	s_setprio 1
	v_mfma_f32_16x16x32_bf16 v[128:131], v[144:147], v[180:183], v[128:131]
	v_mfma_f32_16x16x32_bf16 v[124:127], v[156:159], v[180:183], v[124:127]
	v_mfma_f32_16x16x32_bf16 v[120:123], v[144:147], v[188:191], v[120:123]
	v_mfma_f32_16x16x32_bf16 v[112:115], v[156:159], v[188:191], v[112:115]
	v_mfma_f32_16x16x32_bf16 v[104:107], v[144:147], v[196:199], v[104:107]
	v_mfma_f32_16x16x32_bf16 v[96:99], v[156:159], v[196:199], v[96:99]
	v_mfma_f32_16x16x32_bf16 v[88:91], v[144:147], v[204:207], v[88:91]
	v_mfma_f32_16x16x32_bf16 v[80:83], v[156:159], v[204:207], v[80:83]
	v_mfma_f32_16x16x32_bf16 v[128:131], v[152:155], v[184:187], v[128:131]
	v_mfma_f32_16x16x32_bf16 v[124:127], v[160:163], v[184:187], v[124:127]
	v_mfma_f32_16x16x32_bf16 v[120:123], v[152:155], v[192:195], v[120:123]
	v_mfma_f32_16x16x32_bf16 v[112:115], v[160:163], v[192:195], v[112:115]
	v_mfma_f32_16x16x32_bf16 v[104:107], v[152:155], v[200:203], v[104:107]
	v_mfma_f32_16x16x32_bf16 v[96:99], v[160:163], v[200:203], v[96:99]
	v_mfma_f32_16x16x32_bf16 v[88:91], v[152:155], v[208:211], v[88:91]
	v_mfma_f32_16x16x32_bf16 v[80:83], v[160:163], v[208:211], v[80:83]
	v_mfma_f32_16x16x32_bf16 v[116:119], v[164:167], v[180:183], v[116:119]
	v_mfma_f32_16x16x32_bf16 v[108:111], v[172:175], v[180:183], v[108:111]
	v_mfma_f32_16x16x32_bf16 v[100:103], v[164:167], v[188:191], v[100:103]
	v_mfma_f32_16x16x32_bf16 v[92:95], v[172:175], v[188:191], v[92:95]
	v_mfma_f32_16x16x32_bf16 v[84:87], v[164:167], v[196:199], v[84:87]
	v_mfma_f32_16x16x32_bf16 v[76:79], v[172:175], v[196:199], v[76:79]
	v_mfma_f32_16x16x32_bf16 v[72:75], v[164:167], v[204:207], v[72:75]
	v_mfma_f32_16x16x32_bf16 v[68:71], v[172:175], v[204:207], v[68:71]
	v_mfma_f32_16x16x32_bf16 v[116:119], v[168:171], v[184:187], v[116:119]
	v_mfma_f32_16x16x32_bf16 v[108:111], v[176:179], v[184:187], v[108:111]
	v_mfma_f32_16x16x32_bf16 v[100:103], v[168:171], v[192:195], v[100:103]
	v_mfma_f32_16x16x32_bf16 v[92:95], v[176:179], v[192:195], v[92:95]
	v_mfma_f32_16x16x32_bf16 v[84:87], v[168:171], v[200:203], v[84:87]
	v_mfma_f32_16x16x32_bf16 v[76:79], v[176:179], v[200:203], v[76:79]
	v_mfma_f32_16x16x32_bf16 v[72:75], v[168:171], v[208:211], v[72:75]
	v_mfma_f32_16x16x32_bf16 v[68:71], v[176:179], v[208:211], v[68:71]
	s_setprio 0
	s_barrier
;     __device__ __forceinline__ int nt(const Unit& u) const { return (u.pn >> 1) < 2 ? 22 : 20; }
; #define PG8_STAGE(bufoff, gbase, voff) do { _Pragma("unroll") for (int _i = 0; _i < 2; ++_i) \
;         __builtin_amdgcn_global_load_lds((const unsigned*)((const char*)(gbase) + (voff)[_i]), (LAS unsigned*)(lds + (bufoff) + ldsw + _i * 8192), 16, 0, 0); } while (0)
; #define PG8_LDA(dst, b, h) do { _Pragma("unroll") for (int m = 0; m < 4; ++m) _Pragma("unroll") for (int k = 0; k < 2; ++k) dst[m][k] = *(const LAS bf16x8*)(pA + PG8_SA(b, h) + m * 2048 + k * 1024); } while (0)
; #define PG8_MMA(ai, bj, At, Bt) do { __builtin_amdgcn_s_setprio(1); _Pragma("unroll") for (int m = 0; m < 4; ++m) _Pragma("unroll") for (int n = 0; n < 2; ++n) _Pragma("unroll") for (int k = 0; k < 2; ++k) \
;         acc[ai][bj][m][n] = __builtin_amdgcn_mfma_f32_16x16x32_bf16(Bt[n][k], At[m][k], acc[ai][bj][m][n], 0, 0, 0); __builtin_amdgcn_s_setprio(0); } while (0)
; #define PG8_WAIT_V(n) asm volatile("s_waitcnt vmcnt(" #n ")" ::: "memory")
; #define PG8_WAIT_L(n) asm volatile("s_waitcnt lgkmcnt(" #n ")" ::: "memory")
; #define PG8_BAR __builtin_amdgcn_s_barrier()
; #define PG8_SCHED __builtin_amdgcn_sched_barrier(0)
; template <class Desc, class Epi, bool ALIGN_EPI>
; __device__ __forceinline__ void gemm_phase(LAS unsigned char* lds, const Desc& D, const Epi& E, int G, int c) {
;     ...
;         for (int t = 0; t < nt; t += 2) {
;     ...
;             PG8_LDA(At, 1, 1); PG8_STAGE(PG8_SB(1, 0), b3, voffB); PG8_STAGE(PG8_SB(1, 1), b3 + hstepB, voffB); PG8_STAGE(PG8_SA(1, 0), a3, voffA);
;             PG8_WAIT_V(8); PG8_WAIT_L(0); PG8_BAR; PG8_MMA(1, 0, At, B0); PG8_MMA(1, 1, At, B1); PG8_BAR; PG8_SCHED;
;         }
	s_mov_b32 m0, s35
	v_lshl_add_u64 v[212:213], v[212:213], 0, s[76:77]
	s_add_u32 s18, s18, 0x100080
	ds_read_b128 v[180:183], v148 offset:49152
	ds_read_b128 v[184:187], v148 offset:50176
	ds_read_b128 v[188:191], v148 offset:51200
	ds_read_b128 v[192:195], v148 offset:52224
	ds_read_b128 v[196:199], v148 offset:53248
	ds_read_b128 v[200:203], v148 offset:54272
	ds_read_b128 v[204:207], v148 offset:55296
	ds_read_b128 v[208:211], v148 offset:56320
	global_load_lds_dwordx4 v[212:213], off
	v_lshl_add_u64 v[212:213], v[214:215], 0, s[76:77]
	s_mov_b32 m0, s38
	s_addc_u32 s19, s19, 0
	global_load_lds_dwordx4 v[212:213], off
	v_lshl_add_u64 v[212:213], s[18:19], 0, v[136:137]
	s_mov_b32 m0, s41
	s_nop 0
	global_load_lds_dwordx4 v[212:213], off
	v_lshl_add_u64 v[212:213], s[18:19], 0, v[132:133]
	s_mov_b32 m0, s42
	s_nop 0
	global_load_lds_dwordx4 v[212:213], off
	v_lshl_add_u64 v[212:213], v[216:217], 0, s[76:77]
	s_mov_b32 m0, s39
	s_nop 0
	global_load_lds_dwordx4 v[212:213], off
	v_lshl_add_u64 v[212:213], v[218:219], 0, s[76:77]
	s_mov_b32 m0, s40
	s_nop 0
	global_load_lds_dwordx4 v[212:213], off
	s_waitcnt vmcnt(8)
	s_waitcnt lgkmcnt(0)
	s_barrier
	s_setprio 1
	v_mfma_f32_16x16x32_bf16 v[64:67], v[144:147], v[180:183], v[64:67]
	v_mfma_f32_16x16x32_bf16 v[60:63], v[156:159], v[180:183], v[60:63]
	v_mfma_f32_16x16x32_bf16 v[56:59], v[144:147], v[188:191], v[56:59]
	v_mfma_f32_16x16x32_bf16 v[48:51], v[156:159], v[188:191], v[48:51]
	v_mfma_f32_16x16x32_bf16 v[40:43], v[144:147], v[196:199], v[40:43]
	v_mfma_f32_16x16x32_bf16 v[32:35], v[156:159], v[196:199], v[32:35]
	v_mfma_f32_16x16x32_bf16 v[24:27], v[144:147], v[204:207], v[24:27]
	v_mfma_f32_16x16x32_bf16 v[16:19], v[156:159], v[204:207], v[16:19]
	v_mfma_f32_16x16x32_bf16 v[64:67], v[152:155], v[184:187], v[64:67]
	v_mfma_f32_16x16x32_bf16 v[60:63], v[160:163], v[184:187], v[60:63]
	v_mfma_f32_16x16x32_bf16 v[56:59], v[152:155], v[192:195], v[56:59]
	v_mfma_f32_16x16x32_bf16 v[48:51], v[160:163], v[192:195], v[48:51]
	v_mfma_f32_16x16x32_bf16 v[40:43], v[152:155], v[200:203], v[40:43]
	v_mfma_f32_16x16x32_bf16 v[32:35], v[160:163], v[200:203], v[32:35]
	v_mfma_f32_16x16x32_bf16 v[24:27], v[152:155], v[208:211], v[24:27]
	v_mfma_f32_16x16x32_bf16 v[16:19], v[160:163], v[208:211], v[16:19]
	v_mfma_f32_16x16x32_bf16 v[52:55], v[164:167], v[180:183], v[52:55]
	v_mfma_f32_16x16x32_bf16 v[44:47], v[172:175], v[180:183], v[44:47]
	v_mfma_f32_16x16x32_bf16 v[36:39], v[164:167], v[188:191], v[36:39]
	v_mfma_f32_16x16x32_bf16 v[28:31], v[172:175], v[188:191], v[28:31]
	v_mfma_f32_16x16x32_bf16 v[20:23], v[164:167], v[196:199], v[20:23]
	v_mfma_f32_16x16x32_bf16 v[12:15], v[172:175], v[196:199], v[12:15]
	v_mfma_f32_16x16x32_bf16 v[8:11], v[164:167], v[204:207], v[8:11]
	v_mfma_f32_16x16x32_bf16 v[4:7], v[172:175], v[204:207], v[4:7]
	v_mfma_f32_16x16x32_bf16 v[52:55], v[168:171], v[184:187], v[52:55]
	v_mfma_f32_16x16x32_bf16 v[44:47], v[176:179], v[184:187], v[44:47]
	v_mfma_f32_16x16x32_bf16 v[36:39], v[168:171], v[192:195], v[36:39]
	v_mfma_f32_16x16x32_bf16 v[28:31], v[176:179], v[192:195], v[28:31]
	v_mfma_f32_16x16x32_bf16 v[20:23], v[168:171], v[200:203], v[20:23]
	v_mfma_f32_16x16x32_bf16 v[12:15], v[176:179], v[200:203], v[12:15]
	v_mfma_f32_16x16x32_bf16 v[8:11], v[168:171], v[208:211], v[8:11]
	v_mfma_f32_16x16x32_bf16 v[4:7], v[176:179], v[208:211], v[4:7]
	s_setprio 0
	s_barrier
	s_add_u32 s16, s16, 0x100
	s_addc_u32 s17, s17, 0
	s_add_u32 s48, s48, 0x100
	s_addc_u32 s49, s49, 0
	s_cmp_ge_u32 s50, s46
	s_mov_b32 s18, s50
	s_cbranch_scc0 .LBB0_1324
	s_and_b64 vcc, exec, s[6:7]
	s_cbranch_vccz .LBB0_1327
	s_barrier

; #define PG8_STAGE(bufoff, gbase, voff) do { _Pragma("unroll") for (int _i = 0; _i < 2; ++_i) \
;         __builtin_amdgcn_global_load_lds((const unsigned*)((const char*)(gbase) + (voff)[_i]), (LAS unsigned*)(lds + (bufoff) + ldsw + _i * 8192), 16, 0, 0); } while (0)
; #define PG8_LDA(dst, b, h) do { _Pragma("unroll") for (int m = 0; m < 4; ++m) _Pragma("unroll") for (int k = 0; k < 2; ++k) dst[m][k] = *(const LAS bf16x8*)(pA + PG8_SA(b, h) + m * 2048 + k * 1024); } while (0)
; #define PG8_LDB(dst, b, h) do { _Pragma("unroll") for (int n = 0; n < 2; ++n) _Pragma("unroll") for (int k = 0; k < 2; ++k) dst[n][k] = *(const LAS bf16x8*)(pB + (PG8_SB(b, h) - 4 * HTB) + n * 2048 + k * 1024); } while (0)
; #define PG8_MMA(ai, bj, At, Bt) do { __builtin_amdgcn_s_setprio(1); _Pragma("unroll") for (int m = 0; m < 4; ++m) _Pragma("unroll") for (int n = 0; n < 2; ++n) _Pragma("unroll") for (int k = 0; k < 2; ++k) \
;         acc[ai][bj][m][n] = __builtin_amdgcn_mfma_f32_16x16x32_bf16(Bt[n][k], At[m][k], acc[ai][bj][m][n], 0, 0, 0); __builtin_amdgcn_s_setprio(0); } while (0)
; #define PG8_WAIT_V(n) asm volatile("s_waitcnt vmcnt(" #n ")" ::: "memory")
; #define PG8_WAIT_L(n) asm volatile("s_waitcnt lgkmcnt(" #n ")" ::: "memory")
; #define PG8_BAR __builtin_amdgcn_s_barrier()
; #define PG8_SCHED __builtin_amdgcn_sched_barrier(0)
; template <class Desc, class Epi, bool ALIGN_EPI>
; __device__ __forceinline__ void gemm_phase(LAS unsigned char* lds, const Desc& D, const Epi& E, int G, int c) {
;     ...
;             const char* a1 = cA + (size_t)(t + 1) * kstep;
;             const char* a2 = last ? nA : cA + (size_t)(t + 2) * kstep; const char* b2 = last ? nB : cB + (size_t)(t + 2) * kstep;
;             const char* a3 = a2 + kstep; const char* b3 = b2 + kstep;
;             PG8_LDB(B0, 0, 0); PG8_LDB(B1, 0, 1); PG8_SCHED; PG8_LDA(At, 0, 0); PG8_STAGE(PG8_SA(1, 1), a1 + hstepA, voffA);
;             PG8_WAIT_V(8); PG8_WAIT_L(0); PG8_BAR; PG8_MMA(0, 0, At, B0); PG8_MMA(0, 1, At, B1); PG8_BAR; PG8_SCHED;
;             PG8_LDA(At, 0, 1); PG8_STAGE(PG8_SB(0, 0), b2, voffB); PG8_STAGE(PG8_SB(0, 1), b2 + hstepB, voffB); PG8_STAGE(PG8_SA(0, 0), a2, voffA);
;             PG8_WAIT_V(8); PG8_WAIT_L(0); PG8_BAR; PG8_MMA(1, 0, At, B0); PG8_MMA(1, 1, At, B1); PG8_BAR; PG8_SCHED;
.LBB0_1479:
	ds_read_b128 v[116:119], v225
	ds_read_b128 v[128:131], v225 offset:1024
	ds_read_b128 v[132:135], v225 offset:2048
	ds_read_b128 v[136:139], v225 offset:3072
	ds_read_b128 v[140:143], v225 offset:16384
	ds_read_b128 v[144:147], v225 offset:17408
	ds_read_b128 v[148:151], v225 offset:18432
	ds_read_b128 v[152:155], v225 offset:19456
	s_add_u32 s12, s0, 0xfffe0080
	s_addc_u32 s13, s1, -1
	s_cmp_eq_u32 s52, 4
	s_cselect_b32 s17, s37, s13
	s_cselect_b32 s16, s36, s12
	s_cselect_b32 s13, s21, s33
	s_cselect_b32 s12, s24, s27
	v_lshl_add_u64 v[208:209], s[0:1], 0, v[200:201]
	s_add_i32 m0, s31, 0xc000
	ds_read_b128 v[164:167], v224
	ds_read_b128 v[168:171], v224 offset:1024
	ds_read_b128 v[172:175], v224 offset:2048
	ds_read_b128 v[176:179], v224 offset:3072
	ds_read_b128 v[180:183], v224 offset:4096
	ds_read_b128 v[184:187], v224 offset:5120
	ds_read_b128 v[188:191], v224 offset:6144
	ds_read_b128 v[204:207], v224 offset:7168
	global_load_lds_dwordx4 v[208:209], off
	v_lshl_add_u64 v[208:209], s[0:1], 0, v[202:203]
	s_add_i32 m0, s31, 0xe000
	s_nop 0
	global_load_lds_dwordx4 v[208:209], off
	s_waitcnt vmcnt(8)
	s_waitcnt lgkmcnt(0)
	s_barrier
	s_setprio 1
	v_mfma_f32_16x16x32_bf16 v[160:163], v[116:119], v[164:167], v[160:163]
	v_mfma_f32_16x16x32_bf16 v[156:159], v[132:135], v[164:167], v[156:159]
	v_mfma_f32_16x16x32_bf16 v[112:115], v[116:119], v[172:175], v[112:115]
	v_mfma_f32_16x16x32_bf16 v[108:111], v[132:135], v[172:175], v[108:111]
	v_mfma_f32_16x16x32_bf16 v[96:99], v[116:119], v[180:183], v[96:99]
	v_mfma_f32_16x16x32_bf16 v[92:95], v[132:135], v[180:183], v[92:95]
	v_mfma_f32_16x16x32_bf16 v[80:83], v[116:119], v[188:191], v[80:83]
	v_mfma_f32_16x16x32_bf16 v[76:79], v[132:135], v[188:191], v[76:79]
	v_mfma_f32_16x16x32_bf16 v[160:163], v[128:131], v[168:171], v[160:163]
	v_mfma_f32_16x16x32_bf16 v[156:159], v[136:139], v[168:171], v[156:159]
	v_mfma_f32_16x16x32_bf16 v[112:115], v[128:131], v[176:179], v[112:115]
	v_mfma_f32_16x16x32_bf16 v[108:111], v[136:139], v[176:179], v[108:111]
	v_mfma_f32_16x16x32_bf16 v[96:99], v[128:131], v[184:187], v[96:99]
	v_mfma_f32_16x16x32_bf16 v[92:95], v[136:139], v[184:187], v[92:95]
	v_mfma_f32_16x16x32_bf16 v[80:83], v[128:131], v[204:207], v[80:83]
	v_mfma_f32_16x16x32_bf16 v[76:79], v[136:139], v[204:207], v[76:79]
	v_mfma_f32_16x16x32_bf16 v[124:127], v[140:143], v[164:167], v[124:127]
	v_mfma_f32_16x16x32_bf16 v[120:123], v[148:151], v[164:167], v[120:123]
	v_mfma_f32_16x16x32_bf16 v[104:107], v[140:143], v[172:175], v[104:107]
	v_mfma_f32_16x16x32_bf16 v[100:103], v[148:151], v[172:175], v[100:103]
	v_mfma_f32_16x16x32_bf16 v[88:91], v[140:143], v[180:183], v[88:91]
	v_mfma_f32_16x16x32_bf16 v[84:87], v[148:151], v[180:183], v[84:87]
	v_mfma_f32_16x16x32_bf16 v[72:75], v[140:143], v[188:191], v[72:75]
	v_mfma_f32_16x16x32_bf16 v[68:71], v[148:151], v[188:191], v[68:71]
	v_mfma_f32_16x16x32_bf16 v[124:127], v[144:147], v[168:171], v[124:127]
	v_mfma_f32_16x16x32_bf16 v[120:123], v[152:155], v[168:171], v[120:123]
	v_mfma_f32_16x16x32_bf16 v[104:107], v[144:147], v[176:179], v[104:107]
	v_mfma_f32_16x16x32_bf16 v[100:103], v[152:155], v[176:179], v[100:103]
	v_mfma_f32_16x16x32_bf16 v[88:91], v[144:147], v[184:187], v[88:91]
	v_mfma_f32_16x16x32_bf16 v[84:87], v[152:155], v[184:187], v[84:87]
	v_mfma_f32_16x16x32_bf16 v[72:75], v[144:147], v[204:207], v[72:75]
	v_mfma_f32_16x16x32_bf16 v[68:71], v[152:155], v[204:207], v[68:71]
	s_setprio 0
	s_barrier
	s_mov_b32 m0, s34
	v_lshl_add_u64 v[208:209], s[12:13], 0, v[196:197]
	s_add_u32 s54, s12, 0x20000
	ds_read_b128 v[164:167], v224 offset:16384
	ds_read_b128 v[168:171], v224 offset:17408
	ds_read_b128 v[172:175], v224 offset:18432
	ds_read_b128 v[176:179], v224 offset:19456
	ds_read_b128 v[180:183], v224 offset:20480
	ds_read_b128 v[184:187], v224 offset:21504
	ds_read_b128 v[188:191], v224 offset:22528
	ds_read_b128 v[204:207], v224 offset:23552
	global_load_lds_dwordx4 v[208:209], off
	v_lshl_add_u64 v[210:211], s[12:13], 0, v[192:193]
	s_mov_b32 m0, s35
	s_addc_u32 s55, s13, 0
	global_load_lds_dwordx4 v[210:211], off
	v_lshl_add_u64 v[212:213], s[54:55], 0, v[196:197]
	s_mov_b32 m0, s40
	v_lshl_add_u64 v[214:215], s[16:17], 0, v[194:195]
	global_load_lds_dwordx4 v[212:213], off
	v_lshl_add_u64 v[212:213], s[54:55], 0, v[192:193]
	s_mov_b32 m0, s41
	s_nop 0
	global_load_lds_dwordx4 v[212:213], off
	v_lshl_add_u64 v[212:213], s[16:17], 0, v[198:199]
	s_mov_b32 m0, s31
	s_nop 0
	global_load_lds_dwordx4 v[212:213], off
	s_mov_b32 m0, s42
	s_nop 0
	global_load_lds_dwordx4 v[214:215], off
	s_waitcnt vmcnt(8)
	s_waitcnt lgkmcnt(0)
	s_barrier
; #define PG8_STAGE(bufoff, gbase, voff) do { _Pragma("unroll") for (int _i = 0; _i < 2; ++_i) \
;         __builtin_amdgcn_global_load_lds((const unsigned*)((const char*)(gbase) + (voff)[_i]), (LAS unsigned*)(lds + (bufoff) + ldsw + _i * 8192), 16, 0, 0); } while (0)
; #define PG8_LDA(dst, b, h) do { _Pragma("unroll") for (int m = 0; m < 4; ++m) _Pragma("unroll") for (int k = 0; k < 2; ++k) dst[m][k] = *(const LAS bf16x8*)(pA + PG8_SA(b, h) + m * 2048 + k * 1024); } while (0)
; #define PG8_LDB(dst, b, h) do { _Pragma("unroll") for (int n = 0; n < 2; ++n) _Pragma("unroll") for (int k = 0; k < 2; ++k) dst[n][k] = *(const LAS bf16x8*)(pB + (PG8_SB(b, h) - 4 * HTB) + n * 2048 + k * 1024); } while (0)
; #define PG8_MMA(ai, bj, At, Bt) do { __builtin_amdgcn_s_setprio(1); _Pragma("unroll") for (int m = 0; m < 4; ++m) _Pragma("unroll") for (int n = 0; n < 2; ++n) _Pragma("unroll") for (int k = 0; k < 2; ++k) \
;         acc[ai][bj][m][n] = __builtin_amdgcn_mfma_f32_16x16x32_bf16(Bt[n][k], At[m][k], acc[ai][bj][m][n], 0, 0, 0); __builtin_amdgcn_s_setprio(0); } while (0)
; #define PG8_WAIT_V(n) asm volatile("s_waitcnt vmcnt(" #n ")" ::: "memory")
; #define PG8_WAIT_L(n) asm volatile("s_waitcnt lgkmcnt(" #n ")" ::: "memory")
; #define PG8_BAR __builtin_amdgcn_s_barrier()
; #define PG8_SCHED __builtin_amdgcn_sched_barrier(0)
; template <class Desc, class Epi, bool ALIGN_EPI>
; __device__ __forceinline__ void gemm_phase(LAS unsigned char* lds, const Desc& D, const Epi& E, int G, int c) {
;     ...
;             PG8_WAIT_V(8); PG8_WAIT_L(0); PG8_BAR; PG8_MMA(1, 0, At, B0); PG8_MMA(1, 1, At, B1); PG8_BAR; PG8_SCHED;
;             PG8_LDB(B0, 1, 0); PG8_LDB(B1, 1, 1); PG8_SCHED; PG8_LDA(At, 1, 0); PG8_STAGE(PG8_SA(0, 1), a2 + hstepA, voffA);
;             PG8_WAIT_V(8); PG8_WAIT_L(0); PG8_BAR; PG8_MMA(0, 0, At, B0); PG8_MMA(0, 1, At, B1); PG8_BAR; PG8_SCHED;
	s_setprio 1
	v_mfma_f32_16x16x32_bf16 v[64:67], v[116:119], v[164:167], v[64:67]
	v_mfma_f32_16x16x32_bf16 v[60:63], v[132:135], v[164:167], v[60:63]
	v_mfma_f32_16x16x32_bf16 v[48:51], v[116:119], v[172:175], v[48:51]
	v_mfma_f32_16x16x32_bf16 v[44:47], v[132:135], v[172:175], v[44:47]
	v_mfma_f32_16x16x32_bf16 v[32:35], v[116:119], v[180:183], v[32:35]
	v_mfma_f32_16x16x32_bf16 v[28:31], v[132:135], v[180:183], v[28:31]
	v_mfma_f32_16x16x32_bf16 v[16:19], v[116:119], v[188:191], v[16:19]
	v_mfma_f32_16x16x32_bf16 v[12:15], v[132:135], v[188:191], v[12:15]
	v_mfma_f32_16x16x32_bf16 v[64:67], v[128:131], v[168:171], v[64:67]
	v_mfma_f32_16x16x32_bf16 v[60:63], v[136:139], v[168:171], v[60:63]
	v_mfma_f32_16x16x32_bf16 v[48:51], v[128:131], v[176:179], v[48:51]
	v_mfma_f32_16x16x32_bf16 v[44:47], v[136:139], v[176:179], v[44:47]
	v_mfma_f32_16x16x32_bf16 v[32:35], v[128:131], v[184:187], v[32:35]
	v_mfma_f32_16x16x32_bf16 v[28:31], v[136:139], v[184:187], v[28:31]
	v_mfma_f32_16x16x32_bf16 v[16:19], v[128:131], v[204:207], v[16:19]
	v_mfma_f32_16x16x32_bf16 v[12:15], v[136:139], v[204:207], v[12:15]
	v_mfma_f32_16x16x32_bf16 v[56:59], v[140:143], v[164:167], v[56:59]
	v_mfma_f32_16x16x32_bf16 v[52:55], v[148:151], v[164:167], v[52:55]
	v_mfma_f32_16x16x32_bf16 v[40:43], v[140:143], v[172:175], v[40:43]
	v_mfma_f32_16x16x32_bf16 v[36:39], v[148:151], v[172:175], v[36:39]
	v_mfma_f32_16x16x32_bf16 v[24:27], v[140:143], v[180:183], v[24:27]
	v_mfma_f32_16x16x32_bf16 v[20:23], v[148:151], v[180:183], v[20:23]
	v_mfma_f32_16x16x32_bf16 v[8:11], v[140:143], v[188:191], v[8:11]
	v_mfma_f32_16x16x32_bf16 v[4:7], v[148:151], v[188:191], v[4:7]
	v_mfma_f32_16x16x32_bf16 v[56:59], v[144:147], v[168:171], v[56:59]
	v_mfma_f32_16x16x32_bf16 v[52:55], v[152:155], v[168:171], v[52:55]
	v_mfma_f32_16x16x32_bf16 v[40:43], v[144:147], v[176:179], v[40:43]
	v_mfma_f32_16x16x32_bf16 v[36:39], v[152:155], v[176:179], v[36:39]
	v_mfma_f32_16x16x32_bf16 v[24:27], v[144:147], v[184:187], v[24:27]
	v_mfma_f32_16x16x32_bf16 v[20:23], v[152:155], v[184:187], v[20:23]
	v_mfma_f32_16x16x32_bf16 v[8:11], v[144:147], v[204:207], v[8:11]
	v_mfma_f32_16x16x32_bf16 v[4:7], v[152:155], v[204:207], v[4:7]
	s_setprio 0
	s_barrier
	ds_read_b128 v[116:119], v225 offset:32768
	ds_read_b128 v[128:131], v225 offset:33792
	ds_read_b128 v[132:135], v225 offset:34816
	ds_read_b128 v[136:139], v225 offset:35840
	ds_read_b128 v[140:143], v225 offset:49152
	ds_read_b128 v[144:147], v225 offset:50176
	ds_read_b128 v[148:151], v225 offset:51200
	ds_read_b128 v[152:155], v225 offset:52224
	s_add_u32 s16, s16, 0x20000
	s_addc_u32 s17, s17, 0
	s_mov_b32 m0, s43
	v_lshl_add_u64 v[216:217], s[16:17], 0, v[198:199]
	ds_read_b128 v[164:167], v224 offset:32768
	ds_read_b128 v[168:171], v224 offset:33792
	ds_read_b128 v[172:175], v224 offset:34816
	ds_read_b128 v[176:179], v224 offset:35840
	ds_read_b128 v[180:183], v224 offset:36864
	ds_read_b128 v[184:187], v224 offset:37888
	ds_read_b128 v[188:191], v224 offset:38912
	ds_read_b128 v[204:207], v224 offset:39936
	global_load_lds_dwordx4 v[216:217], off
	v_lshl_add_u64 v[216:217], s[16:17], 0, v[194:195]
	s_mov_b32 m0, s44
	s_nop 0
	global_load_lds_dwordx4 v[216:217], off
	s_waitcnt vmcnt(8)
	s_waitcnt lgkmcnt(0)
	s_barrier
	s_setprio 1
	v_mfma_f32_16x16x32_bf16 v[160:163], v[116:119], v[164:167], v[160:163]
	v_mfma_f32_16x16x32_bf16 v[156:159], v[132:135], v[164:167], v[156:159]
	v_mfma_f32_16x16x32_bf16 v[112:115], v[116:119], v[172:175], v[112:115]
	v_mfma_f32_16x16x32_bf16 v[108:111], v[132:135], v[172:175], v[108:111]
	v_mfma_f32_16x16x32_bf16 v[96:99], v[116:119], v[180:183], v[96:99]
	v_mfma_f32_16x16x32_bf16 v[92:95], v[132:135], v[180:183], v[92:95]
	v_mfma_f32_16x16x32_bf16 v[80:83], v[116:119], v[188:191], v[80:83]
	v_mfma_f32_16x16x32_bf16 v[76:79], v[132:135], v[188:191], v[76:79]
	v_mfma_f32_16x16x32_bf16 v[160:163], v[128:131], v[168:171], v[160:163]
	v_mfma_f32_16x16x32_bf16 v[156:159], v[136:139], v[168:171], v[156:159]
	v_mfma_f32_16x16x32_bf16 v[112:115], v[128:131], v[176:179], v[112:115]
	v_mfma_f32_16x16x32_bf16 v[108:111], v[136:139], v[176:179], v[108:111]
	v_mfma_f32_16x16x32_bf16 v[96:99], v[128:131], v[184:187], v[96:99]
	v_mfma_f32_16x16x32_bf16 v[92:95], v[136:139], v[184:187], v[92:95]
	v_mfma_f32_16x16x32_bf16 v[80:83], v[128:131], v[204:207], v[80:83]
	v_mfma_f32_16x16x32_bf16 v[76:79], v[136:139], v[204:207], v[76:79]
	v_mfma_f32_16x16x32_bf16 v[124:127], v[140:143], v[164:167], v[124:127]
	v_mfma_f32_16x16x32_bf16 v[120:123], v[148:151], v[164:167], v[120:123]
	v_mfma_f32_16x16x32_bf16 v[104:107], v[140:143], v[172:175], v[104:107]
	v_mfma_f32_16x16x32_bf16 v[100:103], v[148:151], v[172:175], v[100:103]
	v_mfma_f32_16x16x32_bf16 v[88:91], v[140:143], v[180:183], v[88:91]
	v_mfma_f32_16x16x32_bf16 v[84:87], v[148:151], v[180:183], v[84:87]
	v_mfma_f32_16x16x32_bf16 v[72:75], v[140:143], v[188:191], v[72:75]
	v_mfma_f32_16x16x32_bf16 v[68:71], v[148:151], v[188:191], v[68:71]
	v_mfma_f32_16x16x32_bf16 v[124:127], v[144:147], v[168:171], v[124:127]
	v_mfma_f32_16x16x32_bf16 v[120:123], v[152:155], v[168:171], v[120:123]
	v_mfma_f32_16x16x32_bf16 v[104:107], v[144:147], v[176:179], v[104:107]
	v_mfma_f32_16x16x32_bf16 v[100:103], v[152:155], v[176:179], v[100:103]
	v_mfma_f32_16x16x32_bf16 v[88:91], v[144:147], v[184:187], v[88:91]
	v_mfma_f32_16x16x32_bf16 v[84:87], v[152:155], v[184:187], v[84:87]
	v_mfma_f32_16x16x32_bf16 v[72:75], v[144:147], v[204:207], v[72:75]
	v_mfma_f32_16x16x32_bf16 v[68:71], v[152:155], v[204:207], v[68:71]
	s_setprio 0
	s_barrier
;     __device__ __forceinline__ int nt(const Unit& u) const { return (u.pn >> 1) < 2 ? 22 : 20; }
; #define PG8_STAGE(bufoff, gbase, voff) do { _Pragma("unroll") for (int _i = 0; _i < 2; ++_i) \
;         __builtin_amdgcn_global_load_lds((const unsigned*)((const char*)(gbase) + (voff)[_i]), (LAS unsigned*)(lds + (bufoff) + ldsw + _i * 8192), 16, 0, 0); } while (0)
; #define PG8_LDA(dst, b, h) do { _Pragma("unroll") for (int m = 0; m < 4; ++m) _Pragma("unroll") for (int k = 0; k < 2; ++k) dst[m][k] = *(const LAS bf16x8*)(pA + PG8_SA(b, h) + m * 2048 + k * 1024); } while (0)
; #define PG8_MMA(ai, bj, At, Bt) do { __builtin_amdgcn_s_setprio(1); _Pragma("unroll") for (int m = 0; m < 4; ++m) _Pragma("unroll") for (int n = 0; n < 2; ++n) _Pragma("unroll") for (int k = 0; k < 2; ++k) \
;         acc[ai][bj][m][n] = __builtin_amdgcn_mfma_f32_16x16x32_bf16(Bt[n][k], At[m][k], acc[ai][bj][m][n], 0, 0, 0); __builtin_amdgcn_s_setprio(0); } while (0)
; #define PG8_WAIT_V(n) asm volatile("s_waitcnt vmcnt(" #n ")" ::: "memory")
; #define PG8_WAIT_L(n) asm volatile("s_waitcnt lgkmcnt(" #n ")" ::: "memory")
; #define PG8_BAR __builtin_amdgcn_s_barrier()
; #define PG8_SCHED __builtin_amdgcn_sched_barrier(0)
; template <class Desc, class Epi, bool ALIGN_EPI>
; __device__ __forceinline__ void gemm_phase(LAS unsigned char* lds, const Desc& D, const Epi& E, int G, int c) {
;     ...
;         for (int t = 0; t < nt; t += 2) {
;     ...
;             PG8_LDA(At, 1, 1); PG8_STAGE(PG8_SB(1, 0), b3, voffB); PG8_STAGE(PG8_SB(1, 1), b3 + hstepB, voffB); PG8_STAGE(PG8_SA(1, 0), a3, voffA);
;             PG8_WAIT_V(8); PG8_WAIT_L(0); PG8_BAR; PG8_MMA(1, 0, At, B0); PG8_MMA(1, 1, At, B1); PG8_BAR; PG8_SCHED;
;         }
	s_mov_b32 m0, s45
	v_lshl_add_u64 v[208:209], v[208:209], 0, s[76:77]
	s_add_u32 s12, s12, 0x20080
	ds_read_b128 v[164:167], v224 offset:49152
	ds_read_b128 v[168:171], v224 offset:50176
	ds_read_b128 v[172:175], v224 offset:51200
	ds_read_b128 v[176:179], v224 offset:52224
	ds_read_b128 v[180:183], v224 offset:53248
	ds_read_b128 v[184:187], v224 offset:54272
	ds_read_b128 v[188:191], v224 offset:55296
	ds_read_b128 v[204:207], v224 offset:56320
	global_load_lds_dwordx4 v[208:209], off
	v_lshl_add_u64 v[208:209], v[210:211], 0, s[76:77]
	s_mov_b32 m0, s46
	s_addc_u32 s13, s13, 0
	global_load_lds_dwordx4 v[208:209], off
	v_lshl_add_u64 v[208:209], s[12:13], 0, v[196:197]
	s_mov_b32 m0, s49
	s_nop 0
	global_load_lds_dwordx4 v[208:209], off
	v_lshl_add_u64 v[208:209], s[12:13], 0, v[192:193]
	s_mov_b32 m0, s50
	s_nop 0
	global_load_lds_dwordx4 v[208:209], off
	v_lshl_add_u64 v[208:209], v[212:213], 0, s[76:77]
	s_mov_b32 m0, s47
	s_nop 0
	global_load_lds_dwordx4 v[208:209], off
	v_lshl_add_u64 v[208:209], v[214:215], 0, s[76:77]
	s_mov_b32 m0, s48
	s_nop 0
	global_load_lds_dwordx4 v[208:209], off
	s_waitcnt vmcnt(8)
	s_waitcnt lgkmcnt(0)
	s_barrier
	s_setprio 1
	v_mfma_f32_16x16x32_bf16 v[64:67], v[116:119], v[164:167], v[64:67]
	v_mfma_f32_16x16x32_bf16 v[60:63], v[132:135], v[164:167], v[60:63]
	v_mfma_f32_16x16x32_bf16 v[48:51], v[116:119], v[172:175], v[48:51]
	v_mfma_f32_16x16x32_bf16 v[44:47], v[132:135], v[172:175], v[44:47]
	v_mfma_f32_16x16x32_bf16 v[32:35], v[116:119], v[180:183], v[32:35]
	v_mfma_f32_16x16x32_bf16 v[28:31], v[132:135], v[180:183], v[28:31]
	v_mfma_f32_16x16x32_bf16 v[16:19], v[116:119], v[188:191], v[16:19]
	v_mfma_f32_16x16x32_bf16 v[12:15], v[132:135], v[188:191], v[12:15]
	v_mfma_f32_16x16x32_bf16 v[64:67], v[128:131], v[168:171], v[64:67]
	v_mfma_f32_16x16x32_bf16 v[60:63], v[136:139], v[168:171], v[60:63]
	v_mfma_f32_16x16x32_bf16 v[48:51], v[128:131], v[176:179], v[48:51]
	v_mfma_f32_16x16x32_bf16 v[44:47], v[136:139], v[176:179], v[44:47]
	v_mfma_f32_16x16x32_bf16 v[32:35], v[128:131], v[184:187], v[32:35]
	v_mfma_f32_16x16x32_bf16 v[28:31], v[136:139], v[184:187], v[28:31]
	v_mfma_f32_16x16x32_bf16 v[16:19], v[128:131], v[204:207], v[16:19]
	v_mfma_f32_16x16x32_bf16 v[12:15], v[136:139], v[204:207], v[12:15]
	v_mfma_f32_16x16x32_bf16 v[56:59], v[140:143], v[164:167], v[56:59]
	v_mfma_f32_16x16x32_bf16 v[52:55], v[148:151], v[164:167], v[52:55]
	v_mfma_f32_16x16x32_bf16 v[40:43], v[140:143], v[172:175], v[40:43]
	v_mfma_f32_16x16x32_bf16 v[36:39], v[148:151], v[172:175], v[36:39]
	v_mfma_f32_16x16x32_bf16 v[24:27], v[140:143], v[180:183], v[24:27]
	v_mfma_f32_16x16x32_bf16 v[20:23], v[148:151], v[180:183], v[20:23]
	v_mfma_f32_16x16x32_bf16 v[8:11], v[140:143], v[188:191], v[8:11]
	v_mfma_f32_16x16x32_bf16 v[4:7], v[148:151], v[188:191], v[4:7]
	v_mfma_f32_16x16x32_bf16 v[56:59], v[144:147], v[168:171], v[56:59]
	v_mfma_f32_16x16x32_bf16 v[52:55], v[152:155], v[168:171], v[52:55]
	v_mfma_f32_16x16x32_bf16 v[40:43], v[144:147], v[176:179], v[40:43]
	v_mfma_f32_16x16x32_bf16 v[36:39], v[152:155], v[176:179], v[36:39]
	v_mfma_f32_16x16x32_bf16 v[24:27], v[144:147], v[184:187], v[24:27]
	v_mfma_f32_16x16x32_bf16 v[20:23], v[152:155], v[184:187], v[20:23]
	v_mfma_f32_16x16x32_bf16 v[8:11], v[144:147], v[204:207], v[8:11]
	v_mfma_f32_16x16x32_bf16 v[4:7], v[152:155], v[204:207], v[4:7]
	s_setprio 0
	s_barrier
	s_add_i32 s52, s52, 2
	s_add_u32 s0, s0, 0x100
	s_addc_u32 s1, s1, 0
	s_add_u32 s27, s27, 0x100
	s_addc_u32 s33, s33, 0
	s_cmp_gt_u32 s52, 5
	s_cbranch_scc0 .LBB0_1479
	s_and_b64 vcc, exec, s[8:9]
	s_cbranch_vccz .LBB0_1482
	s_barrier

; #define PG8_STAGE(bufoff, gbase, voff) do { _Pragma("unroll") for (int _i = 0; _i < 2; ++_i) \
;         __builtin_amdgcn_global_load_lds((const unsigned*)((const char*)(gbase) + (voff)[_i]), (LAS unsigned*)(lds + (bufoff) + ldsw + _i * 8192), 16, 0, 0); } while (0)
; #define PG8_LDA(dst, b, h) do { _Pragma("unroll") for (int m = 0; m < 4; ++m) _Pragma("unroll") for (int k = 0; k < 2; ++k) dst[m][k] = *(const LAS bf16x8*)(pA + PG8_SA(b, h) + m * 2048 + k * 1024); } while (0)
; #define PG8_LDB(dst, b, h) do { _Pragma("unroll") for (int n = 0; n < 2; ++n) _Pragma("unroll") for (int k = 0; k < 2; ++k) dst[n][k] = *(const LAS bf16x8*)(pB + (PG8_SB(b, h) - 4 * HTB) + n * 2048 + k * 1024); } while (0)
; #define PG8_MMA(ai, bj, At, Bt) do { __builtin_amdgcn_s_setprio(1); _Pragma("unroll") for (int m = 0; m < 4; ++m) _Pragma("unroll") for (int n = 0; n < 2; ++n) _Pragma("unroll") for (int k = 0; k < 2; ++k) \
;         acc[ai][bj][m][n] = __builtin_amdgcn_mfma_f32_16x16x32_bf16(Bt[n][k], At[m][k], acc[ai][bj][m][n], 0, 0, 0); __builtin_amdgcn_s_setprio(0); } while (0)
; #define PG8_WAIT_V(n) asm volatile("s_waitcnt vmcnt(" #n ")" ::: "memory")
; #define PG8_WAIT_L(n) asm volatile("s_waitcnt lgkmcnt(" #n ")" ::: "memory")
; #define PG8_BAR __builtin_amdgcn_s_barrier()
; #define PG8_SCHED __builtin_amdgcn_sched_barrier(0)
; template <class Desc, class Epi, bool ALIGN_EPI>
; __device__ __forceinline__ void gemm_phase(LAS unsigned char* lds, const Desc& D, const Epi& E, int G, int c) {
;     ...
;             const char* a1 = cA + (size_t)(t + 1) * kstep;
;             const char* a2 = last ? nA : cA + (size_t)(t + 2) * kstep; const char* b2 = last ? nB : cB + (size_t)(t + 2) * kstep;
;             const char* a3 = a2 + kstep; const char* b3 = b2 + kstep;
;             PG8_LDB(B0, 0, 0); PG8_LDB(B1, 0, 1); PG8_SCHED; PG8_LDA(At, 0, 0); PG8_STAGE(PG8_SA(1, 1), a1 + hstepA, voffA);
;             PG8_WAIT_V(8); PG8_WAIT_L(0); PG8_BAR; PG8_MMA(0, 0, At, B0); PG8_MMA(0, 1, At, B1); PG8_BAR; PG8_SCHED;
;             PG8_LDA(At, 0, 1); PG8_STAGE(PG8_SB(0, 0), b2, voffB); PG8_STAGE(PG8_SB(0, 1), b2 + hstepB, voffB); PG8_STAGE(PG8_SA(0, 0), a2, voffA);
;             PG8_WAIT_V(8); PG8_WAIT_L(0); PG8_BAR; PG8_MMA(1, 0, At, B0); PG8_MMA(1, 1, At, B1); PG8_BAR; PG8_SCHED;
.LBB0_1517:
	ds_read_b128 v[116:119], v225
	ds_read_b128 v[128:131], v225 offset:1024
	ds_read_b128 v[132:135], v225 offset:2048
	ds_read_b128 v[136:139], v225 offset:3072
	ds_read_b128 v[140:143], v225 offset:16384
	ds_read_b128 v[144:147], v225 offset:17408
	ds_read_b128 v[148:151], v225 offset:18432
	ds_read_b128 v[152:155], v225 offset:19456
	s_add_u32 s12, s0, 0xfffe0080
	s_addc_u32 s13, s1, -1
	s_cmp_eq_u32 s54, 4
	s_cselect_b32 s17, s37, s13
	s_cselect_b32 s16, s36, s12
	s_cselect_b32 s13, s21, s33
	s_cselect_b32 s12, s24, s27
	v_lshl_add_u64 v[208:209], s[0:1], 0, v[200:201]
	s_add_i32 m0, s31, 0xc000
	ds_read_b128 v[164:167], v224
	ds_read_b128 v[168:171], v224 offset:1024
	ds_read_b128 v[172:175], v224 offset:2048
	ds_read_b128 v[176:179], v224 offset:3072
	ds_read_b128 v[180:183], v224 offset:4096
	ds_read_b128 v[184:187], v224 offset:5120
	ds_read_b128 v[188:191], v224 offset:6144
	ds_read_b128 v[204:207], v224 offset:7168
	global_load_lds_dwordx4 v[208:209], off
	v_lshl_add_u64 v[208:209], s[0:1], 0, v[202:203]
	s_add_i32 m0, s31, 0xe000
	s_nop 0
	global_load_lds_dwordx4 v[208:209], off
	s_waitcnt vmcnt(8)
	s_waitcnt lgkmcnt(0)
	s_barrier
	s_setprio 1
	v_mfma_f32_16x16x32_bf16 v[160:163], v[116:119], v[164:167], v[160:163]
	v_mfma_f32_16x16x32_bf16 v[156:159], v[132:135], v[164:167], v[156:159]
	v_mfma_f32_16x16x32_bf16 v[112:115], v[116:119], v[172:175], v[112:115]
	v_mfma_f32_16x16x32_bf16 v[108:111], v[132:135], v[172:175], v[108:111]
	v_mfma_f32_16x16x32_bf16 v[96:99], v[116:119], v[180:183], v[96:99]
	v_mfma_f32_16x16x32_bf16 v[92:95], v[132:135], v[180:183], v[92:95]
	v_mfma_f32_16x16x32_bf16 v[80:83], v[116:119], v[188:191], v[80:83]
	v_mfma_f32_16x16x32_bf16 v[76:79], v[132:135], v[188:191], v[76:79]
	v_mfma_f32_16x16x32_bf16 v[160:163], v[128:131], v[168:171], v[160:163]
	v_mfma_f32_16x16x32_bf16 v[156:159], v[136:139], v[168:171], v[156:159]
	v_mfma_f32_16x16x32_bf16 v[112:115], v[128:131], v[176:179], v[112:115]
	v_mfma_f32_16x16x32_bf16 v[108:111], v[136:139], v[176:179], v[108:111]
	v_mfma_f32_16x16x32_bf16 v[96:99], v[128:131], v[184:187], v[96:99]
	v_mfma_f32_16x16x32_bf16 v[92:95], v[136:139], v[184:187], v[92:95]
	v_mfma_f32_16x16x32_bf16 v[80:83], v[128:131], v[204:207], v[80:83]
	v_mfma_f32_16x16x32_bf16 v[76:79], v[136:139], v[204:207], v[76:79]
	v_mfma_f32_16x16x32_bf16 v[124:127], v[140:143], v[164:167], v[124:127]
	v_mfma_f32_16x16x32_bf16 v[120:123], v[148:151], v[164:167], v[120:123]
	v_mfma_f32_16x16x32_bf16 v[104:107], v[140:143], v[172:175], v[104:107]
	v_mfma_f32_16x16x32_bf16 v[100:103], v[148:151], v[172:175], v[100:103]
	v_mfma_f32_16x16x32_bf16 v[88:91], v[140:143], v[180:183], v[88:91]
	v_mfma_f32_16x16x32_bf16 v[84:87], v[148:151], v[180:183], v[84:87]
	v_mfma_f32_16x16x32_bf16 v[72:75], v[140:143], v[188:191], v[72:75]
	v_mfma_f32_16x16x32_bf16 v[68:71], v[148:151], v[188:191], v[68:71]
	v_mfma_f32_16x16x32_bf16 v[124:127], v[144:147], v[168:171], v[124:127]
	v_mfma_f32_16x16x32_bf16 v[120:123], v[152:155], v[168:171], v[120:123]
	v_mfma_f32_16x16x32_bf16 v[104:107], v[144:147], v[176:179], v[104:107]
	v_mfma_f32_16x16x32_bf16 v[100:103], v[152:155], v[176:179], v[100:103]
	v_mfma_f32_16x16x32_bf16 v[88:91], v[144:147], v[184:187], v[88:91]
	v_mfma_f32_16x16x32_bf16 v[84:87], v[152:155], v[184:187], v[84:87]
	v_mfma_f32_16x16x32_bf16 v[72:75], v[144:147], v[204:207], v[72:75]
	v_mfma_f32_16x16x32_bf16 v[68:71], v[152:155], v[204:207], v[68:71]
	s_setprio 0
	s_barrier
	s_mov_b32 m0, s34
	v_lshl_add_u64 v[208:209], s[12:13], 0, v[196:197]
	s_add_u32 s56, s12, 0x20000
	ds_read_b128 v[164:167], v224 offset:16384
	ds_read_b128 v[168:171], v224 offset:17408
	ds_read_b128 v[172:175], v224 offset:18432
	ds_read_b128 v[176:179], v224 offset:19456
	ds_read_b128 v[180:183], v224 offset:20480
	ds_read_b128 v[184:187], v224 offset:21504
	ds_read_b128 v[188:191], v224 offset:22528
	ds_read_b128 v[204:207], v224 offset:23552
	global_load_lds_dwordx4 v[208:209], off
	v_lshl_add_u64 v[210:211], s[12:13], 0, v[192:193]
	s_mov_b32 m0, s35
	s_addc_u32 s57, s13, 0
	global_load_lds_dwordx4 v[210:211], off
	v_lshl_add_u64 v[212:213], s[56:57], 0, v[196:197]
	s_mov_b32 m0, s42
	v_lshl_add_u64 v[214:215], s[16:17], 0, v[194:195]
	global_load_lds_dwordx4 v[212:213], off
	v_lshl_add_u64 v[212:213], s[56:57], 0, v[192:193]
	s_mov_b32 m0, s43
	s_nop 0
	global_load_lds_dwordx4 v[212:213], off
	v_lshl_add_u64 v[212:213], s[16:17], 0, v[198:199]
	s_mov_b32 m0, s31
	s_nop 0
	global_load_lds_dwordx4 v[212:213], off
	s_mov_b32 m0, s44
	s_nop 0
	global_load_lds_dwordx4 v[214:215], off
	s_waitcnt vmcnt(8)
	s_waitcnt lgkmcnt(0)
	s_barrier
; #define PG8_STAGE(bufoff, gbase, voff) do { _Pragma("unroll") for (int _i = 0; _i < 2; ++_i) \
;         __builtin_amdgcn_global_load_lds((const unsigned*)((const char*)(gbase) + (voff)[_i]), (LAS unsigned*)(lds + (bufoff) + ldsw + _i * 8192), 16, 0, 0); } while (0)
; #define PG8_LDA(dst, b, h) do { _Pragma("unroll") for (int m = 0; m < 4; ++m) _Pragma("unroll") for (int k = 0; k < 2; ++k) dst[m][k] = *(const LAS bf16x8*)(pA + PG8_SA(b, h) + m * 2048 + k * 1024); } while (0)
; #define PG8_LDB(dst, b, h) do { _Pragma("unroll") for (int n = 0; n < 2; ++n) _Pragma("unroll") for (int k = 0; k < 2; ++k) dst[n][k] = *(const LAS bf16x8*)(pB + (PG8_SB(b, h) - 4 * HTB) + n * 2048 + k * 1024); } while (0)
; #define PG8_MMA(ai, bj, At, Bt) do { __builtin_amdgcn_s_setprio(1); _Pragma("unroll") for (int m = 0; m < 4; ++m) _Pragma("unroll") for (int n = 0; n < 2; ++n) _Pragma("unroll") for (int k = 0; k < 2; ++k) \
;         acc[ai][bj][m][n] = __builtin_amdgcn_mfma_f32_16x16x32_bf16(Bt[n][k], At[m][k], acc[ai][bj][m][n], 0, 0, 0); __builtin_amdgcn_s_setprio(0); } while (0)
; #define PG8_WAIT_V(n) asm volatile("s_waitcnt vmcnt(" #n ")" ::: "memory")
; #define PG8_WAIT_L(n) asm volatile("s_waitcnt lgkmcnt(" #n ")" ::: "memory")
; #define PG8_BAR __builtin_amdgcn_s_barrier()
; #define PG8_SCHED __builtin_amdgcn_sched_barrier(0)
; template <class Desc, class Epi, bool ALIGN_EPI>
; __device__ __forceinline__ void gemm_phase(LAS unsigned char* lds, const Desc& D, const Epi& E, int G, int c) {
;     ...
;             PG8_WAIT_V(8); PG8_WAIT_L(0); PG8_BAR; PG8_MMA(1, 0, At, B0); PG8_MMA(1, 1, At, B1); PG8_BAR; PG8_SCHED;
;             PG8_LDB(B0, 1, 0); PG8_LDB(B1, 1, 1); PG8_SCHED; PG8_LDA(At, 1, 0); PG8_STAGE(PG8_SA(0, 1), a2 + hstepA, voffA);
;             PG8_WAIT_V(8); PG8_WAIT_L(0); PG8_BAR; PG8_MMA(0, 0, At, B0); PG8_MMA(0, 1, At, B1); PG8_BAR; PG8_SCHED;
	s_setprio 1
	v_mfma_f32_16x16x32_bf16 v[64:67], v[116:119], v[164:167], v[64:67]
	v_mfma_f32_16x16x32_bf16 v[60:63], v[132:135], v[164:167], v[60:63]
	v_mfma_f32_16x16x32_bf16 v[48:51], v[116:119], v[172:175], v[48:51]
	v_mfma_f32_16x16x32_bf16 v[44:47], v[132:135], v[172:175], v[44:47]
	v_mfma_f32_16x16x32_bf16 v[32:35], v[116:119], v[180:183], v[32:35]
	v_mfma_f32_16x16x32_bf16 v[28:31], v[132:135], v[180:183], v[28:31]
	v_mfma_f32_16x16x32_bf16 v[16:19], v[116:119], v[188:191], v[16:19]
	v_mfma_f32_16x16x32_bf16 v[12:15], v[132:135], v[188:191], v[12:15]
	v_mfma_f32_16x16x32_bf16 v[64:67], v[128:131], v[168:171], v[64:67]
	v_mfma_f32_16x16x32_bf16 v[60:63], v[136:139], v[168:171], v[60:63]
	v_mfma_f32_16x16x32_bf16 v[48:51], v[128:131], v[176:179], v[48:51]
	v_mfma_f32_16x16x32_bf16 v[44:47], v[136:139], v[176:179], v[44:47]
	v_mfma_f32_16x16x32_bf16 v[32:35], v[128:131], v[184:187], v[32:35]
	v_mfma_f32_16x16x32_bf16 v[28:31], v[136:139], v[184:187], v[28:31]
	v_mfma_f32_16x16x32_bf16 v[16:19], v[128:131], v[204:207], v[16:19]
	v_mfma_f32_16x16x32_bf16 v[12:15], v[136:139], v[204:207], v[12:15]
	v_mfma_f32_16x16x32_bf16 v[56:59], v[140:143], v[164:167], v[56:59]
	v_mfma_f32_16x16x32_bf16 v[52:55], v[148:151], v[164:167], v[52:55]
	v_mfma_f32_16x16x32_bf16 v[40:43], v[140:143], v[172:175], v[40:43]
	v_mfma_f32_16x16x32_bf16 v[36:39], v[148:151], v[172:175], v[36:39]
	v_mfma_f32_16x16x32_bf16 v[24:27], v[140:143], v[180:183], v[24:27]
	v_mfma_f32_16x16x32_bf16 v[20:23], v[148:151], v[180:183], v[20:23]
	v_mfma_f32_16x16x32_bf16 v[8:11], v[140:143], v[188:191], v[8:11]
	v_mfma_f32_16x16x32_bf16 v[4:7], v[148:151], v[188:191], v[4:7]
	v_mfma_f32_16x16x32_bf16 v[56:59], v[144:147], v[168:171], v[56:59]
	v_mfma_f32_16x16x32_bf16 v[52:55], v[152:155], v[168:171], v[52:55]
	v_mfma_f32_16x16x32_bf16 v[40:43], v[144:147], v[176:179], v[40:43]
	v_mfma_f32_16x16x32_bf16 v[36:39], v[152:155], v[176:179], v[36:39]
	v_mfma_f32_16x16x32_bf16 v[24:27], v[144:147], v[184:187], v[24:27]
	v_mfma_f32_16x16x32_bf16 v[20:23], v[152:155], v[184:187], v[20:23]
	v_mfma_f32_16x16x32_bf16 v[8:11], v[144:147], v[204:207], v[8:11]
	v_mfma_f32_16x16x32_bf16 v[4:7], v[152:155], v[204:207], v[4:7]
	s_setprio 0
	s_barrier
	ds_read_b128 v[116:119], v225 offset:32768
	ds_read_b128 v[128:131], v225 offset:33792
	ds_read_b128 v[132:135], v225 offset:34816
	ds_read_b128 v[136:139], v225 offset:35840
	ds_read_b128 v[140:143], v225 offset:49152
	ds_read_b128 v[144:147], v225 offset:50176
	ds_read_b128 v[148:151], v225 offset:51200
	ds_read_b128 v[152:155], v225 offset:52224
	s_add_u32 s16, s16, 0x20000
	s_addc_u32 s17, s17, 0
	s_mov_b32 m0, s45
	v_lshl_add_u64 v[216:217], s[16:17], 0, v[198:199]
	ds_read_b128 v[164:167], v224 offset:32768
	ds_read_b128 v[168:171], v224 offset:33792
	ds_read_b128 v[172:175], v224 offset:34816
	ds_read_b128 v[176:179], v224 offset:35840
	ds_read_b128 v[180:183], v224 offset:36864
	ds_read_b128 v[184:187], v224 offset:37888
	ds_read_b128 v[188:191], v224 offset:38912
	ds_read_b128 v[204:207], v224 offset:39936
	global_load_lds_dwordx4 v[216:217], off
	v_lshl_add_u64 v[216:217], s[16:17], 0, v[194:195]
	s_mov_b32 m0, s46
	s_nop 0
	global_load_lds_dwordx4 v[216:217], off
	s_waitcnt vmcnt(8)
	s_waitcnt lgkmcnt(0)
	s_barrier
	s_setprio 1
	v_mfma_f32_16x16x32_bf16 v[160:163], v[116:119], v[164:167], v[160:163]
	v_mfma_f32_16x16x32_bf16 v[156:159], v[132:135], v[164:167], v[156:159]
	v_mfma_f32_16x16x32_bf16 v[112:115], v[116:119], v[172:175], v[112:115]
	v_mfma_f32_16x16x32_bf16 v[108:111], v[132:135], v[172:175], v[108:111]
	v_mfma_f32_16x16x32_bf16 v[96:99], v[116:119], v[180:183], v[96:99]
	v_mfma_f32_16x16x32_bf16 v[92:95], v[132:135], v[180:183], v[92:95]
	v_mfma_f32_16x16x32_bf16 v[80:83], v[116:119], v[188:191], v[80:83]
	v_mfma_f32_16x16x32_bf16 v[76:79], v[132:135], v[188:191], v[76:79]
	v_mfma_f32_16x16x32_bf16 v[160:163], v[128:131], v[168:171], v[160:163]
	v_mfma_f32_16x16x32_bf16 v[156:159], v[136:139], v[168:171], v[156:159]
	v_mfma_f32_16x16x32_bf16 v[112:115], v[128:131], v[176:179], v[112:115]
	v_mfma_f32_16x16x32_bf16 v[108:111], v[136:139], v[176:179], v[108:111]
	v_mfma_f32_16x16x32_bf16 v[96:99], v[128:131], v[184:187], v[96:99]
	v_mfma_f32_16x16x32_bf16 v[92:95], v[136:139], v[184:187], v[92:95]
	v_mfma_f32_16x16x32_bf16 v[80:83], v[128:131], v[204:207], v[80:83]
	v_mfma_f32_16x16x32_bf16 v[76:79], v[136:139], v[204:207], v[76:79]
	v_mfma_f32_16x16x32_bf16 v[124:127], v[140:143], v[164:167], v[124:127]
	v_mfma_f32_16x16x32_bf16 v[120:123], v[148:151], v[164:167], v[120:123]
	v_mfma_f32_16x16x32_bf16 v[104:107], v[140:143], v[172:175], v[104:107]
	v_mfma_f32_16x16x32_bf16 v[100:103], v[148:151], v[172:175], v[100:103]
	v_mfma_f32_16x16x32_bf16 v[88:91], v[140:143], v[180:183], v[88:91]
	v_mfma_f32_16x16x32_bf16 v[84:87], v[148:151], v[180:183], v[84:87]
	v_mfma_f32_16x16x32_bf16 v[72:75], v[140:143], v[188:191], v[72:75]
	v_mfma_f32_16x16x32_bf16 v[68:71], v[148:151], v[188:191], v[68:71]
	v_mfma_f32_16x16x32_bf16 v[124:127], v[144:147], v[168:171], v[124:127]
	v_mfma_f32_16x16x32_bf16 v[120:123], v[152:155], v[168:171], v[120:123]
	v_mfma_f32_16x16x32_bf16 v[104:107], v[144:147], v[176:179], v[104:107]
	v_mfma_f32_16x16x32_bf16 v[100:103], v[152:155], v[176:179], v[100:103]
	v_mfma_f32_16x16x32_bf16 v[88:91], v[144:147], v[184:187], v[88:91]
	v_mfma_f32_16x16x32_bf16 v[84:87], v[152:155], v[184:187], v[84:87]
	v_mfma_f32_16x16x32_bf16 v[72:75], v[144:147], v[204:207], v[72:75]
	v_mfma_f32_16x16x32_bf16 v[68:71], v[152:155], v[204:207], v[68:71]
	s_setprio 0
	s_barrier
;     __device__ __forceinline__ int nt(const Unit& u) const { return (u.pn >> 1) < 2 ? 22 : 20; }
; #define PG8_STAGE(bufoff, gbase, voff) do { _Pragma("unroll") for (int _i = 0; _i < 2; ++_i) \
;         __builtin_amdgcn_global_load_lds((const unsigned*)((const char*)(gbase) + (voff)[_i]), (LAS unsigned*)(lds + (bufoff) + ldsw + _i * 8192), 16, 0, 0); } while (0)
; #define PG8_LDA(dst, b, h) do { _Pragma("unroll") for (int m = 0; m < 4; ++m) _Pragma("unroll") for (int k = 0; k < 2; ++k) dst[m][k] = *(const LAS bf16x8*)(pA + PG8_SA(b, h) + m * 2048 + k * 1024); } while (0)
; #define PG8_MMA(ai, bj, At, Bt) do { __builtin_amdgcn_s_setprio(1); _Pragma("unroll") for (int m = 0; m < 4; ++m) _Pragma("unroll") for (int n = 0; n < 2; ++n) _Pragma("unroll") for (int k = 0; k < 2; ++k) \
;         acc[ai][bj][m][n] = __builtin_amdgcn_mfma_f32_16x16x32_bf16(Bt[n][k], At[m][k], acc[ai][bj][m][n], 0, 0, 0); __builtin_amdgcn_s_setprio(0); } while (0)
; #define PG8_WAIT_V(n) asm volatile("s_waitcnt vmcnt(" #n ")" ::: "memory")
; #define PG8_WAIT_L(n) asm volatile("s_waitcnt lgkmcnt(" #n ")" ::: "memory")
; #define PG8_BAR __builtin_amdgcn_s_barrier()
; #define PG8_SCHED __builtin_amdgcn_sched_barrier(0)
; template <class Desc, class Epi, bool ALIGN_EPI>
; __device__ __forceinline__ void gemm_phase(LAS unsigned char* lds, const Desc& D, const Epi& E, int G, int c) {
;     ...
;         for (int t = 0; t < nt; t += 2) {
;     ...
;             PG8_LDA(At, 1, 1); PG8_STAGE(PG8_SB(1, 0), b3, voffB); PG8_STAGE(PG8_SB(1, 1), b3 + hstepB, voffB); PG8_STAGE(PG8_SA(1, 0), a3, voffA);
;             PG8_WAIT_V(8); PG8_WAIT_L(0); PG8_BAR; PG8_MMA(1, 0, At, B0); PG8_MMA(1, 1, At, B1); PG8_BAR; PG8_SCHED;
;         }
	s_mov_b32 m0, s47
	v_lshl_add_u64 v[208:209], v[208:209], 0, s[76:77]
	s_add_u32 s12, s12, 0x20080
	ds_read_b128 v[164:167], v224 offset:49152
	ds_read_b128 v[168:171], v224 offset:50176
	ds_read_b128 v[172:175], v224 offset:51200
	ds_read_b128 v[176:179], v224 offset:52224
	ds_read_b128 v[180:183], v224 offset:53248
	ds_read_b128 v[184:187], v224 offset:54272
	ds_read_b128 v[188:191], v224 offset:55296
	ds_read_b128 v[204:207], v224 offset:56320
	global_load_lds_dwordx4 v[208:209], off
	v_lshl_add_u64 v[208:209], v[210:211], 0, s[76:77]
	s_mov_b32 m0, s48
	s_addc_u32 s13, s13, 0
	global_load_lds_dwordx4 v[208:209], off
	v_lshl_add_u64 v[208:209], s[12:13], 0, v[196:197]
	s_mov_b32 m0, s51
	s_nop 0
	global_load_lds_dwordx4 v[208:209], off
	v_lshl_add_u64 v[208:209], s[12:13], 0, v[192:193]
	s_mov_b32 m0, s52
	s_nop 0
	global_load_lds_dwordx4 v[208:209], off
	v_lshl_add_u64 v[208:209], v[212:213], 0, s[76:77]
	s_mov_b32 m0, s49
	s_nop 0
	global_load_lds_dwordx4 v[208:209], off
	v_lshl_add_u64 v[208:209], v[214:215], 0, s[76:77]
	s_mov_b32 m0, s50
	s_nop 0
	global_load_lds_dwordx4 v[208:209], off
	s_waitcnt vmcnt(8)
	s_waitcnt lgkmcnt(0)
	s_barrier
	s_setprio 1
	v_mfma_f32_16x16x32_bf16 v[64:67], v[116:119], v[164:167], v[64:67]
	v_mfma_f32_16x16x32_bf16 v[60:63], v[132:135], v[164:167], v[60:63]
	v_mfma_f32_16x16x32_bf16 v[48:51], v[116:119], v[172:175], v[48:51]
	v_mfma_f32_16x16x32_bf16 v[44:47], v[132:135], v[172:175], v[44:47]
	v_mfma_f32_16x16x32_bf16 v[32:35], v[116:119], v[180:183], v[32:35]
	v_mfma_f32_16x16x32_bf16 v[28:31], v[132:135], v[180:183], v[28:31]
	v_mfma_f32_16x16x32_bf16 v[16:19], v[116:119], v[188:191], v[16:19]
	v_mfma_f32_16x16x32_bf16 v[12:15], v[132:135], v[188:191], v[12:15]
	v_mfma_f32_16x16x32_bf16 v[64:67], v[128:131], v[168:171], v[64:67]
	v_mfma_f32_16x16x32_bf16 v[60:63], v[136:139], v[168:171], v[60:63]
	v_mfma_f32_16x16x32_bf16 v[48:51], v[128:131], v[176:179], v[48:51]
	v_mfma_f32_16x16x32_bf16 v[44:47], v[136:139], v[176:179], v[44:47]
	v_mfma_f32_16x16x32_bf16 v[32:35], v[128:131], v[184:187], v[32:35]
	v_mfma_f32_16x16x32_bf16 v[28:31], v[136:139], v[184:187], v[28:31]
	v_mfma_f32_16x16x32_bf16 v[16:19], v[128:131], v[204:207], v[16:19]
	v_mfma_f32_16x16x32_bf16 v[12:15], v[136:139], v[204:207], v[12:15]
	v_mfma_f32_16x16x32_bf16 v[56:59], v[140:143], v[164:167], v[56:59]
	v_mfma_f32_16x16x32_bf16 v[52:55], v[148:151], v[164:167], v[52:55]
	v_mfma_f32_16x16x32_bf16 v[40:43], v[140:143], v[172:175], v[40:43]
	v_mfma_f32_16x16x32_bf16 v[36:39], v[148:151], v[172:175], v[36:39]
	v_mfma_f32_16x16x32_bf16 v[24:27], v[140:143], v[180:183], v[24:27]
	v_mfma_f32_16x16x32_bf16 v[20:23], v[148:151], v[180:183], v[20:23]
	v_mfma_f32_16x16x32_bf16 v[8:11], v[140:143], v[188:191], v[8:11]
	v_mfma_f32_16x16x32_bf16 v[4:7], v[148:151], v[188:191], v[4:7]
	v_mfma_f32_16x16x32_bf16 v[56:59], v[144:147], v[168:171], v[56:59]
	v_mfma_f32_16x16x32_bf16 v[52:55], v[152:155], v[168:171], v[52:55]
	v_mfma_f32_16x16x32_bf16 v[40:43], v[144:147], v[176:179], v[40:43]
	v_mfma_f32_16x16x32_bf16 v[36:39], v[152:155], v[176:179], v[36:39]
	v_mfma_f32_16x16x32_bf16 v[24:27], v[144:147], v[184:187], v[24:27]
	v_mfma_f32_16x16x32_bf16 v[20:23], v[152:155], v[184:187], v[20:23]
	v_mfma_f32_16x16x32_bf16 v[8:11], v[144:147], v[204:207], v[8:11]
	v_mfma_f32_16x16x32_bf16 v[4:7], v[152:155], v[204:207], v[4:7]
	s_setprio 0
	s_barrier
	s_add_i32 s54, s54, 2
	s_add_u32 s0, s0, 0x100
	s_addc_u32 s1, s1, 0
	s_add_u32 s27, s27, 0x100
	s_addc_u32 s33, s33, 0
	s_cmp_gt_u32 s54, 5
	s_cbranch_scc0 .LBB0_1517
	s_and_b64 vcc, exec, s[10:11]
	s_cbranch_vccz .LBB0_1520
	s_barrier

; #define PG8_STAGE(bufoff, gbase, voff) do { _Pragma("unroll") for (int _i = 0; _i < 2; ++_i) \
;         __builtin_amdgcn_global_load_lds((const unsigned*)((const char*)(gbase) + (voff)[_i]), (LAS unsigned*)(lds + (bufoff) + ldsw + _i * 8192), 16, 0, 0); } while (0)
; #define PG8_LDA(dst, b, h) do { _Pragma("unroll") for (int m = 0; m < 4; ++m) _Pragma("unroll") for (int k = 0; k < 2; ++k) dst[m][k] = *(const LAS bf16x8*)(pA + PG8_SA(b, h) + m * 2048 + k * 1024); } while (0)
; #define PG8_LDB(dst, b, h) do { _Pragma("unroll") for (int n = 0; n < 2; ++n) _Pragma("unroll") for (int k = 0; k < 2; ++k) dst[n][k] = *(const LAS bf16x8*)(pB + (PG8_SB(b, h) - 4 * HTB) + n * 2048 + k * 1024); } while (0)
; #define PG8_MMA(ai, bj, At, Bt) do { __builtin_amdgcn_s_setprio(1); _Pragma("unroll") for (int m = 0; m < 4; ++m) _Pragma("unroll") for (int n = 0; n < 2; ++n) _Pragma("unroll") for (int k = 0; k < 2; ++k) \
;         acc[ai][bj][m][n] = __builtin_amdgcn_mfma_f32_16x16x32_bf16(Bt[n][k], At[m][k], acc[ai][bj][m][n], 0, 0, 0); __builtin_amdgcn_s_setprio(0); } while (0)
; #define PG8_WAIT_V(n) asm volatile("s_waitcnt vmcnt(" #n ")" ::: "memory")
; #define PG8_WAIT_L(n) asm volatile("s_waitcnt lgkmcnt(" #n ")" ::: "memory")
; #define PG8_BAR __builtin_amdgcn_s_barrier()
; #define PG8_SCHED __builtin_amdgcn_sched_barrier(0)
; template <class Desc, class Epi, bool ALIGN_EPI>
; __device__ __forceinline__ void gemm_phase(LAS unsigned char* lds, const Desc& D, const Epi& E, int G, int c) {
;     ...
;             const char* a1 = cA + (size_t)(t + 1) * kstep;
;             const char* a2 = last ? nA : cA + (size_t)(t + 2) * kstep; const char* b2 = last ? nB : cB + (size_t)(t + 2) * kstep;
;             const char* a3 = a2 + kstep; const char* b3 = b2 + kstep;
;             PG8_LDB(B0, 0, 0); PG8_LDB(B1, 0, 1); PG8_SCHED; PG8_LDA(At, 0, 0); PG8_STAGE(PG8_SA(1, 1), a1 + hstepA, voffA);
;             PG8_WAIT_V(8); PG8_WAIT_L(0); PG8_BAR; PG8_MMA(0, 0, At, B0); PG8_MMA(0, 1, At, B1); PG8_BAR; PG8_SCHED;
;             PG8_LDA(At, 0, 1); PG8_STAGE(PG8_SB(0, 0), b2, voffB); PG8_STAGE(PG8_SB(0, 1), b2 + hstepB, voffB); PG8_STAGE(PG8_SA(0, 0), a2, voffA);
;             PG8_WAIT_V(8); PG8_WAIT_L(0); PG8_BAR; PG8_MMA(1, 0, At, B0); PG8_MMA(1, 1, At, B1); PG8_BAR; PG8_SCHED;
.LBB0_1580:
	s_or_b32 s14, s30, 1
	s_add_i32 s30, s30, 2
	s_mov_b32 s31, s15
	s_lshl_b64 s[72:73], s[14:15], 7
	s_lshl_b64 s[74:75], s[30:31], 7
	s_add_u32 s14, s18, s74
	ds_read_b128 v[140:143], v163
	ds_read_b128 v[144:147], v163 offset:1024
	ds_read_b128 v[148:151], v163 offset:2048
	ds_read_b128 v[152:155], v163 offset:3072
	ds_read_b128 v[156:159], v163 offset:16384
	ds_read_b128 v[166:169], v163 offset:17408
	ds_read_b128 v[170:173], v163 offset:18432
	ds_read_b128 v[174:177], v163 offset:19456
	s_addc_u32 s31, s19, s75
	s_and_b64 s[46:47], s[34:35], exec
	s_cselect_b32 s47, s43, s31
	s_cselect_b32 s46, s42, s14
	s_add_u32 s14, s20, s74
	s_addc_u32 s31, s21, s75
	s_and_b64 s[34:35], s[34:35], exec
	s_cselect_b32 s35, s3, s31
	s_cselect_b32 s34, s13, s14
	s_add_u32 s14, s18, s72
	s_addc_u32 s31, s19, s73
	s_add_u32 s72, s14, 0x100000
	s_addc_u32 s73, s31, 0
	s_add_i32 m0, s52, 0xc000
	ds_read_b128 v[178:181], v162
	ds_read_b128 v[182:185], v162 offset:1024
	ds_read_b128 v[186:189], v162 offset:2048
	ds_read_b128 v[190:193], v162 offset:3072
	ds_read_b128 v[194:197], v162 offset:4096
	ds_read_b128 v[198:201], v162 offset:5120
	ds_read_b128 v[202:205], v162 offset:6144
	ds_read_b128 v[206:209], v162 offset:7168
	global_load_lds_dwordx4 v132, s[72:73]
	s_add_i32 m0, s52, 0xe000
	s_nop 0
	global_load_lds_dwordx4 v136, s[72:73]
	s_waitcnt vmcnt(8)
	s_waitcnt lgkmcnt(0)
	s_barrier
	s_setprio 1
	v_mfma_f32_16x16x32_bf16 v[128:131], v[140:143], v[178:181], v[128:131]
	v_mfma_f32_16x16x32_bf16 v[124:127], v[148:151], v[178:181], v[124:127]
	v_mfma_f32_16x16x32_bf16 v[120:123], v[140:143], v[186:189], v[120:123]
	v_mfma_f32_16x16x32_bf16 v[116:119], v[148:151], v[186:189], v[116:119]
	v_mfma_f32_16x16x32_bf16 v[112:115], v[140:143], v[194:197], v[112:115]
	v_mfma_f32_16x16x32_bf16 v[108:111], v[148:151], v[194:197], v[108:111]
	v_mfma_f32_16x16x32_bf16 v[104:107], v[140:143], v[202:205], v[104:107]
	v_mfma_f32_16x16x32_bf16 v[100:103], v[148:151], v[202:205], v[100:103]
	v_mfma_f32_16x16x32_bf16 v[128:131], v[144:147], v[182:185], v[128:131]
	v_mfma_f32_16x16x32_bf16 v[124:127], v[152:155], v[182:185], v[124:127]
	v_mfma_f32_16x16x32_bf16 v[120:123], v[144:147], v[190:193], v[120:123]
	v_mfma_f32_16x16x32_bf16 v[116:119], v[152:155], v[190:193], v[116:119]
	v_mfma_f32_16x16x32_bf16 v[112:115], v[144:147], v[198:201], v[112:115]
	v_mfma_f32_16x16x32_bf16 v[108:111], v[152:155], v[198:201], v[108:111]
	v_mfma_f32_16x16x32_bf16 v[104:107], v[144:147], v[206:209], v[104:107]
	v_mfma_f32_16x16x32_bf16 v[100:103], v[152:155], v[206:209], v[100:103]
	v_mfma_f32_16x16x32_bf16 v[96:99], v[156:159], v[178:181], v[96:99]
	v_mfma_f32_16x16x32_bf16 v[92:95], v[170:173], v[178:181], v[92:95]
	v_mfma_f32_16x16x32_bf16 v[88:91], v[156:159], v[186:189], v[88:91]
	v_mfma_f32_16x16x32_bf16 v[84:87], v[170:173], v[186:189], v[84:87]
	v_mfma_f32_16x16x32_bf16 v[80:83], v[156:159], v[194:197], v[80:83]
	v_mfma_f32_16x16x32_bf16 v[76:79], v[170:173], v[194:197], v[76:79]
	v_mfma_f32_16x16x32_bf16 v[72:75], v[156:159], v[202:205], v[72:75]
	v_mfma_f32_16x16x32_bf16 v[68:71], v[170:173], v[202:205], v[68:71]
	v_mfma_f32_16x16x32_bf16 v[96:99], v[166:169], v[182:185], v[96:99]
	v_mfma_f32_16x16x32_bf16 v[92:95], v[174:177], v[182:185], v[92:95]
	v_mfma_f32_16x16x32_bf16 v[88:91], v[166:169], v[190:193], v[88:91]
	v_mfma_f32_16x16x32_bf16 v[84:87], v[174:177], v[190:193], v[84:87]
	v_mfma_f32_16x16x32_bf16 v[80:83], v[166:169], v[198:201], v[80:83]
	v_mfma_f32_16x16x32_bf16 v[76:79], v[174:177], v[198:201], v[76:79]
	v_mfma_f32_16x16x32_bf16 v[72:75], v[166:169], v[206:209], v[72:75]
	v_mfma_f32_16x16x32_bf16 v[68:71], v[174:177], v[206:209], v[68:71]
	s_setprio 0
	s_barrier
	s_mov_b32 m0, s53
	s_add_u32 s72, s34, 0x100000
	s_addc_u32 s73, s35, 0
	ds_read_b128 v[178:181], v162 offset:16384
	ds_read_b128 v[182:185], v162 offset:17408
	ds_read_b128 v[186:189], v162 offset:18432
	ds_read_b128 v[190:193], v162 offset:19456
	ds_read_b128 v[194:197], v162 offset:20480
	ds_read_b128 v[198:201], v162 offset:21504
	ds_read_b128 v[202:205], v162 offset:22528
	ds_read_b128 v[206:209], v162 offset:23552
	global_load_lds_dwordx4 v134, s[34:35]
	s_mov_b32 m0, s54
	s_nop 0
	global_load_lds_dwordx4 v138, s[34:35]
	s_mov_b32 m0, s55
	s_nop 0
	global_load_lds_dwordx4 v134, s[72:73]
	s_mov_b32 m0, s56
	s_nop 0
	global_load_lds_dwordx4 v138, s[72:73]
	s_mov_b32 m0, s52
	s_nop 0
	global_load_lds_dwordx4 v132, s[46:47]
	s_mov_b32 m0, s57
	s_nop 0
	global_load_lds_dwordx4 v136, s[46:47]
	s_waitcnt vmcnt(8)
	s_waitcnt lgkmcnt(0)
	s_barrier
; #define PG8_STAGE(bufoff, gbase, voff) do { _Pragma("unroll") for (int _i = 0; _i < 2; ++_i) \
;         __builtin_amdgcn_global_load_lds((const unsigned*)((const char*)(gbase) + (voff)[_i]), (LAS unsigned*)(lds + (bufoff) + ldsw + _i * 8192), 16, 0, 0); } while (0)
; #define PG8_LDA(dst, b, h) do { _Pragma("unroll") for (int m = 0; m < 4; ++m) _Pragma("unroll") for (int k = 0; k < 2; ++k) dst[m][k] = *(const LAS bf16x8*)(pA + PG8_SA(b, h) + m * 2048 + k * 1024); } while (0)
; #define PG8_LDB(dst, b, h) do { _Pragma("unroll") for (int n = 0; n < 2; ++n) _Pragma("unroll") for (int k = 0; k < 2; ++k) dst[n][k] = *(const LAS bf16x8*)(pB + (PG8_SB(b, h) - 4 * HTB) + n * 2048 + k * 1024); } while (0)
; #define PG8_MMA(ai, bj, At, Bt) do { __builtin_amdgcn_s_setprio(1); _Pragma("unroll") for (int m = 0; m < 4; ++m) _Pragma("unroll") for (int n = 0; n < 2; ++n) _Pragma("unroll") for (int k = 0; k < 2; ++k) \
;         acc[ai][bj][m][n] = __builtin_amdgcn_mfma_f32_16x16x32_bf16(Bt[n][k], At[m][k], acc[ai][bj][m][n], 0, 0, 0); __builtin_amdgcn_s_setprio(0); } while (0)
; #define PG8_WAIT_V(n) asm volatile("s_waitcnt vmcnt(" #n ")" ::: "memory")
; #define PG8_WAIT_L(n) asm volatile("s_waitcnt lgkmcnt(" #n ")" ::: "memory")
; #define PG8_BAR __builtin_amdgcn_s_barrier()
; #define PG8_SCHED __builtin_amdgcn_sched_barrier(0)
; template <class Desc, class Epi, bool ALIGN_EPI>
; __device__ __forceinline__ void gemm_phase(LAS unsigned char* lds, const Desc& D, const Epi& E, int G, int c) {
;     ...
;             PG8_WAIT_V(8); PG8_WAIT_L(0); PG8_BAR; PG8_MMA(1, 0, At, B0); PG8_MMA(1, 1, At, B1); PG8_BAR; PG8_SCHED;
;             PG8_LDB(B0, 1, 0); PG8_LDB(B1, 1, 1); PG8_SCHED; PG8_LDA(At, 1, 0); PG8_STAGE(PG8_SA(0, 1), a2 + hstepA, voffA);
;             PG8_WAIT_V(8); PG8_WAIT_L(0); PG8_BAR; PG8_MMA(0, 0, At, B0); PG8_MMA(0, 1, At, B1); PG8_BAR; PG8_SCHED;
	s_setprio 1
	v_mfma_f32_16x16x32_bf16 v[64:67], v[140:143], v[178:181], v[64:67]
	v_mfma_f32_16x16x32_bf16 v[52:55], v[148:151], v[178:181], v[52:55]
	v_mfma_f32_16x16x32_bf16 v[32:35], v[140:143], v[186:189], v[32:35]
	v_mfma_f32_16x16x32_bf16 v[20:23], v[148:151], v[186:189], v[20:23]
	v_mfma_f32_16x16x32_bf16 v[16:19], v[140:143], v[194:197], v[16:19]
	v_mfma_f32_16x16x32_bf16 v[12:15], v[148:151], v[194:197], v[12:15]
	v_mfma_f32_16x16x32_bf16 v[8:11], v[140:143], v[202:205], v[8:11]
	v_mfma_f32_16x16x32_bf16 v[4:7], v[148:151], v[202:205], v[4:7]
	v_mfma_f32_16x16x32_bf16 v[64:67], v[144:147], v[182:185], v[64:67]
	v_mfma_f32_16x16x32_bf16 v[52:55], v[152:155], v[182:185], v[52:55]
	v_mfma_f32_16x16x32_bf16 v[32:35], v[144:147], v[190:193], v[32:35]
	v_mfma_f32_16x16x32_bf16 v[20:23], v[152:155], v[190:193], v[20:23]
	v_mfma_f32_16x16x32_bf16 v[16:19], v[144:147], v[198:201], v[16:19]
	v_mfma_f32_16x16x32_bf16 v[12:15], v[152:155], v[198:201], v[12:15]
	v_mfma_f32_16x16x32_bf16 v[8:11], v[144:147], v[206:209], v[8:11]
	v_mfma_f32_16x16x32_bf16 v[4:7], v[152:155], v[206:209], v[4:7]
	v_mfma_f32_16x16x32_bf16 v[60:63], v[156:159], v[178:181], v[60:63]
	v_mfma_f32_16x16x32_bf16 v[56:59], v[170:173], v[178:181], v[56:59]
	v_mfma_f32_16x16x32_bf16 v[48:51], v[156:159], v[186:189], v[48:51]
	v_mfma_f32_16x16x32_bf16 v[44:47], v[170:173], v[186:189], v[44:47]
	v_mfma_f32_16x16x32_bf16 v[40:43], v[156:159], v[194:197], v[40:43]
	v_mfma_f32_16x16x32_bf16 v[36:39], v[170:173], v[194:197], v[36:39]
	v_mfma_f32_16x16x32_bf16 v[28:31], v[156:159], v[202:205], v[28:31]
	v_mfma_f32_16x16x32_bf16 v[24:27], v[170:173], v[202:205], v[24:27]
	v_mfma_f32_16x16x32_bf16 v[60:63], v[166:169], v[182:185], v[60:63]
	v_mfma_f32_16x16x32_bf16 v[56:59], v[174:177], v[182:185], v[56:59]
	v_mfma_f32_16x16x32_bf16 v[48:51], v[166:169], v[190:193], v[48:51]
	v_mfma_f32_16x16x32_bf16 v[44:47], v[174:177], v[190:193], v[44:47]
	v_mfma_f32_16x16x32_bf16 v[40:43], v[166:169], v[198:201], v[40:43]
	v_mfma_f32_16x16x32_bf16 v[36:39], v[174:177], v[198:201], v[36:39]
	v_mfma_f32_16x16x32_bf16 v[28:31], v[166:169], v[206:209], v[28:31]
	v_mfma_f32_16x16x32_bf16 v[24:27], v[174:177], v[206:209], v[24:27]
	s_setprio 0
	s_barrier
	ds_read_b128 v[140:143], v163 offset:32768
	ds_read_b128 v[144:147], v163 offset:33792
	ds_read_b128 v[148:151], v163 offset:34816
	ds_read_b128 v[152:155], v163 offset:35840
	ds_read_b128 v[156:159], v163 offset:49152
	ds_read_b128 v[166:169], v163 offset:50176
	ds_read_b128 v[170:173], v163 offset:51200
	ds_read_b128 v[174:177], v163 offset:52224
	s_add_u32 s46, s46, 0x100000
	s_addc_u32 s47, s47, 0
	s_mov_b32 m0, s58
	ds_read_b128 v[178:181], v162 offset:32768
	ds_read_b128 v[182:185], v162 offset:33792
	ds_read_b128 v[186:189], v162 offset:34816
	ds_read_b128 v[190:193], v162 offset:35840
	ds_read_b128 v[194:197], v162 offset:36864
	ds_read_b128 v[198:201], v162 offset:37888
	ds_read_b128 v[202:205], v162 offset:38912
	ds_read_b128 v[206:209], v162 offset:39936
	global_load_lds_dwordx4 v132, s[46:47]
	s_mov_b32 m0, s59
	s_nop 0
	global_load_lds_dwordx4 v136, s[46:47]
	s_waitcnt vmcnt(8)
	s_waitcnt lgkmcnt(0)
	s_barrier
	s_setprio 1
	v_mfma_f32_16x16x32_bf16 v[128:131], v[140:143], v[178:181], v[128:131]
	v_mfma_f32_16x16x32_bf16 v[124:127], v[148:151], v[178:181], v[124:127]
	v_mfma_f32_16x16x32_bf16 v[120:123], v[140:143], v[186:189], v[120:123]
	v_mfma_f32_16x16x32_bf16 v[116:119], v[148:151], v[186:189], v[116:119]
	v_mfma_f32_16x16x32_bf16 v[112:115], v[140:143], v[194:197], v[112:115]
	v_mfma_f32_16x16x32_bf16 v[108:111], v[148:151], v[194:197], v[108:111]
	v_mfma_f32_16x16x32_bf16 v[104:107], v[140:143], v[202:205], v[104:107]
	v_mfma_f32_16x16x32_bf16 v[100:103], v[148:151], v[202:205], v[100:103]
	v_mfma_f32_16x16x32_bf16 v[128:131], v[144:147], v[182:185], v[128:131]
	v_mfma_f32_16x16x32_bf16 v[124:127], v[152:155], v[182:185], v[124:127]
	v_mfma_f32_16x16x32_bf16 v[120:123], v[144:147], v[190:193], v[120:123]
	v_mfma_f32_16x16x32_bf16 v[116:119], v[152:155], v[190:193], v[116:119]
	v_mfma_f32_16x16x32_bf16 v[112:115], v[144:147], v[198:201], v[112:115]
	v_mfma_f32_16x16x32_bf16 v[108:111], v[152:155], v[198:201], v[108:111]
	v_mfma_f32_16x16x32_bf16 v[104:107], v[144:147], v[206:209], v[104:107]
	v_mfma_f32_16x16x32_bf16 v[100:103], v[152:155], v[206:209], v[100:103]
	v_mfma_f32_16x16x32_bf16 v[96:99], v[156:159], v[178:181], v[96:99]
	v_mfma_f32_16x16x32_bf16 v[92:95], v[170:173], v[178:181], v[92:95]
	v_mfma_f32_16x16x32_bf16 v[88:91], v[156:159], v[186:189], v[88:91]
	v_mfma_f32_16x16x32_bf16 v[84:87], v[170:173], v[186:189], v[84:87]
	v_mfma_f32_16x16x32_bf16 v[80:83], v[156:159], v[194:197], v[80:83]
	v_mfma_f32_16x16x32_bf16 v[76:79], v[170:173], v[194:197], v[76:79]
	v_mfma_f32_16x16x32_bf16 v[72:75], v[156:159], v[202:205], v[72:75]
	v_mfma_f32_16x16x32_bf16 v[68:71], v[170:173], v[202:205], v[68:71]
	v_mfma_f32_16x16x32_bf16 v[96:99], v[166:169], v[182:185], v[96:99]
	v_mfma_f32_16x16x32_bf16 v[92:95], v[174:177], v[182:185], v[92:95]
	v_mfma_f32_16x16x32_bf16 v[88:91], v[166:169], v[190:193], v[88:91]
	v_mfma_f32_16x16x32_bf16 v[84:87], v[174:177], v[190:193], v[84:87]
	v_mfma_f32_16x16x32_bf16 v[80:83], v[166:169], v[198:201], v[80:83]
	v_mfma_f32_16x16x32_bf16 v[76:79], v[174:177], v[198:201], v[76:79]
	v_mfma_f32_16x16x32_bf16 v[72:75], v[166:169], v[206:209], v[72:75]
	v_mfma_f32_16x16x32_bf16 v[68:71], v[174:177], v[206:209], v[68:71]
	s_setprio 0
	s_barrier
;     __device__ __forceinline__ int nt(const Unit& u) const { return (u.pn >> 1) < 2 ? 22 : 20; }
; #define PG8_STAGE(bufoff, gbase, voff) do { _Pragma("unroll") for (int _i = 0; _i < 2; ++_i) \
;         __builtin_amdgcn_global_load_lds((const unsigned*)((const char*)(gbase) + (voff)[_i]), (LAS unsigned*)(lds + (bufoff) + ldsw + _i * 8192), 16, 0, 0); } while (0)
; #define PG8_LDA(dst, b, h) do { _Pragma("unroll") for (int m = 0; m < 4; ++m) _Pragma("unroll") for (int k = 0; k < 2; ++k) dst[m][k] = *(const LAS bf16x8*)(pA + PG8_SA(b, h) + m * 2048 + k * 1024); } while (0)
; #define PG8_MMA(ai, bj, At, Bt) do { __builtin_amdgcn_s_setprio(1); _Pragma("unroll") for (int m = 0; m < 4; ++m) _Pragma("unroll") for (int n = 0; n < 2; ++n) _Pragma("unroll") for (int k = 0; k < 2; ++k) \
;         acc[ai][bj][m][n] = __builtin_amdgcn_mfma_f32_16x16x32_bf16(Bt[n][k], At[m][k], acc[ai][bj][m][n], 0, 0, 0); __builtin_amdgcn_s_setprio(0); } while (0)
; #define PG8_WAIT_V(n) asm volatile("s_waitcnt vmcnt(" #n ")" ::: "memory")
; #define PG8_WAIT_L(n) asm volatile("s_waitcnt lgkmcnt(" #n ")" ::: "memory")
; #define PG8_BAR __builtin_amdgcn_s_barrier()
; #define PG8_SCHED __builtin_amdgcn_sched_barrier(0)
; template <class Desc, class Epi, bool ALIGN_EPI>
; __device__ __forceinline__ void gemm_phase(LAS unsigned char* lds, const Desc& D, const Epi& E, int G, int c) {
;     ...
;         for (int t = 0; t < nt; t += 2) {
;     ...
;             PG8_LDA(At, 1, 1); PG8_STAGE(PG8_SB(1, 0), b3, voffB); PG8_STAGE(PG8_SB(1, 1), b3 + hstepB, voffB); PG8_STAGE(PG8_SA(1, 0), a3, voffA);
;             PG8_WAIT_V(8); PG8_WAIT_L(0); PG8_BAR; PG8_MMA(1, 0, At, B0); PG8_MMA(1, 1, At, B1); PG8_BAR; PG8_SCHED;
;         }
	s_mov_b32 m0, s61
	s_add_u32 s74, s34, 0x80
	s_addc_u32 s75, s35, 0
	s_add_u32 s34, s34, 0x100080
	s_addc_u32 s35, s35, 0
	ds_read_b128 v[178:181], v162 offset:49152
	ds_read_b128 v[182:185], v162 offset:50176
	ds_read_b128 v[186:189], v162 offset:51200
	ds_read_b128 v[190:193], v162 offset:52224
	ds_read_b128 v[194:197], v162 offset:53248
	ds_read_b128 v[198:201], v162 offset:54272
	ds_read_b128 v[202:205], v162 offset:55296
	ds_read_b128 v[206:209], v162 offset:56320
	global_load_lds_dwordx4 v134, s[74:75]
	s_mov_b32 m0, s62
	s_nop 0
	global_load_lds_dwordx4 v138, s[74:75]
	s_mov_b32 m0, s65
	s_nop 0
	global_load_lds_dwordx4 v134, s[34:35]
	s_mov_b32 m0, s67
	s_nop 0
	global_load_lds_dwordx4 v138, s[34:35]
	s_sub_u32 s74, s46, 0xfff80
	s_subb_u32 s75, s47, 0
	s_mov_b32 m0, s63
	s_nop 0
	global_load_lds_dwordx4 v132, s[74:75]
	s_mov_b32 m0, s64
	s_nop 0
	global_load_lds_dwordx4 v136, s[74:75]
	s_waitcnt vmcnt(8)
	s_waitcnt lgkmcnt(0)
	s_barrier
	s_setprio 1
	v_mfma_f32_16x16x32_bf16 v[64:67], v[140:143], v[178:181], v[64:67]
	v_mfma_f32_16x16x32_bf16 v[52:55], v[148:151], v[178:181], v[52:55]
	v_mfma_f32_16x16x32_bf16 v[32:35], v[140:143], v[186:189], v[32:35]
	v_mfma_f32_16x16x32_bf16 v[20:23], v[148:151], v[186:189], v[20:23]
	v_mfma_f32_16x16x32_bf16 v[16:19], v[140:143], v[194:197], v[16:19]
	v_mfma_f32_16x16x32_bf16 v[12:15], v[148:151], v[194:197], v[12:15]
	v_mfma_f32_16x16x32_bf16 v[8:11], v[140:143], v[202:205], v[8:11]
	v_mfma_f32_16x16x32_bf16 v[4:7], v[148:151], v[202:205], v[4:7]
	v_mfma_f32_16x16x32_bf16 v[64:67], v[144:147], v[182:185], v[64:67]
	v_mfma_f32_16x16x32_bf16 v[52:55], v[152:155], v[182:185], v[52:55]
	v_mfma_f32_16x16x32_bf16 v[32:35], v[144:147], v[190:193], v[32:35]
	v_mfma_f32_16x16x32_bf16 v[20:23], v[152:155], v[190:193], v[20:23]
	v_mfma_f32_16x16x32_bf16 v[16:19], v[144:147], v[198:201], v[16:19]
	v_mfma_f32_16x16x32_bf16 v[12:15], v[152:155], v[198:201], v[12:15]
	v_mfma_f32_16x16x32_bf16 v[8:11], v[144:147], v[206:209], v[8:11]
	v_mfma_f32_16x16x32_bf16 v[4:7], v[152:155], v[206:209], v[4:7]
	v_mfma_f32_16x16x32_bf16 v[60:63], v[156:159], v[178:181], v[60:63]
	v_mfma_f32_16x16x32_bf16 v[56:59], v[170:173], v[178:181], v[56:59]
	v_mfma_f32_16x16x32_bf16 v[48:51], v[156:159], v[186:189], v[48:51]
	v_mfma_f32_16x16x32_bf16 v[44:47], v[170:173], v[186:189], v[44:47]
	v_mfma_f32_16x16x32_bf16 v[40:43], v[156:159], v[194:197], v[40:43]
	v_mfma_f32_16x16x32_bf16 v[36:39], v[170:173], v[194:197], v[36:39]
	v_mfma_f32_16x16x32_bf16 v[28:31], v[156:159], v[202:205], v[28:31]
	v_mfma_f32_16x16x32_bf16 v[24:27], v[170:173], v[202:205], v[24:27]
	v_mfma_f32_16x16x32_bf16 v[60:63], v[166:169], v[182:185], v[60:63]
	v_mfma_f32_16x16x32_bf16 v[56:59], v[174:177], v[182:185], v[56:59]
	v_mfma_f32_16x16x32_bf16 v[48:51], v[166:169], v[190:193], v[48:51]
	v_mfma_f32_16x16x32_bf16 v[44:47], v[174:177], v[190:193], v[44:47]
	v_mfma_f32_16x16x32_bf16 v[40:43], v[166:169], v[198:201], v[40:43]
	v_mfma_f32_16x16x32_bf16 v[36:39], v[174:177], v[198:201], v[36:39]
	v_mfma_f32_16x16x32_bf16 v[28:31], v[166:169], v[206:209], v[28:31]
	v_mfma_f32_16x16x32_bf16 v[24:27], v[174:177], v[206:209], v[24:27]
	s_setprio 0
	s_barrier
	s_cmp_ge_u32 s30, s2
	s_cbranch_scc1 .LBB0_1591

; #define PG8_STAGE(bufoff, gbase, voff) do { _Pragma("unroll") for (int _i = 0; _i < 2; ++_i) \
;         __builtin_amdgcn_global_load_lds((const unsigned*)((const char*)(gbase) + (voff)[_i]), (LAS unsigned*)(lds + (bufoff) + ldsw + _i * 8192), 16, 0, 0); } while (0)
; #define PG8_LDA(dst, b, h) do { _Pragma("unroll") for (int m = 0; m < 4; ++m) _Pragma("unroll") for (int k = 0; k < 2; ++k) dst[m][k] = *(const LAS bf16x8*)(pA + PG8_SA(b, h) + m * 2048 + k * 1024); } while (0)
; #define PG8_LDB(dst, b, h) do { _Pragma("unroll") for (int n = 0; n < 2; ++n) _Pragma("unroll") for (int k = 0; k < 2; ++k) dst[n][k] = *(const LAS bf16x8*)(pB + (PG8_SB(b, h) - 4 * HTB) + n * 2048 + k * 1024); } while (0)
; #define PG8_MMA(ai, bj, At, Bt) do { __builtin_amdgcn_s_setprio(1); _Pragma("unroll") for (int m = 0; m < 4; ++m) _Pragma("unroll") for (int n = 0; n < 2; ++n) _Pragma("unroll") for (int k = 0; k < 2; ++k) \
;         acc[ai][bj][m][n] = __builtin_amdgcn_mfma_f32_16x16x32_bf16(Bt[n][k], At[m][k], acc[ai][bj][m][n], 0, 0, 0); __builtin_amdgcn_s_setprio(0); } while (0)
; #define PG8_WAIT_V(n) asm volatile("s_waitcnt vmcnt(" #n ")" ::: "memory")
; #define PG8_WAIT_L(n) asm volatile("s_waitcnt lgkmcnt(" #n ")" ::: "memory")
; #define PG8_BAR __builtin_amdgcn_s_barrier()
; #define PG8_SCHED __builtin_amdgcn_sched_barrier(0)
; template <class Desc, class Epi, bool ALIGN_EPI>
; __device__ __forceinline__ void gemm_phase(LAS unsigned char* lds, const Desc& D, const Epi& E, int G, int c) {
;     ...
;             const char* a1 = cA + (size_t)(t + 1) * kstep;
;             const char* a2 = last ? nA : cA + (size_t)(t + 2) * kstep; const char* b2 = last ? nB : cB + (size_t)(t + 2) * kstep;
;             const char* a3 = a2 + kstep; const char* b3 = b2 + kstep;
;             PG8_LDB(B0, 0, 0); PG8_LDB(B1, 0, 1); PG8_SCHED; PG8_LDA(At, 0, 0); PG8_STAGE(PG8_SA(1, 1), a1 + hstepA, voffA);
;             PG8_WAIT_V(8); PG8_WAIT_L(0); PG8_BAR; PG8_MMA(0, 0, At, B0); PG8_MMA(0, 1, At, B1); PG8_BAR; PG8_SCHED;
;             PG8_LDA(At, 0, 1); PG8_STAGE(PG8_SB(0, 0), b2, voffB); PG8_STAGE(PG8_SB(0, 1), b2 + hstepB, voffB); PG8_STAGE(PG8_SA(0, 0), a2, voffA);
;             PG8_WAIT_V(8); PG8_WAIT_L(0); PG8_BAR; PG8_MMA(1, 0, At, B0); PG8_MMA(1, 1, At, B1); PG8_BAR; PG8_SCHED;
.LBB0_1765:
	s_or_b32 s14, s39, 1
	s_lshl_b64 s[40:41], s[14:15], 7
	s_add_i32 s14, s39, 2
	s_lshl_b64 s[42:43], s[14:15], 7
	s_add_u32 s39, s12, s42
	s_waitcnt lgkmcnt(0)
	ds_read_b128 v[132:135], v248
	ds_read_b128 v[136:139], v248 offset:1024
	ds_read_b128 v[140:143], v248 offset:2048
	ds_read_b128 v[144:147], v248 offset:3072
	ds_read_b128 v[148:151], v248 offset:16384
	ds_read_b128 v[152:155], v248 offset:17408
	ds_read_b128 v[156:159], v248 offset:18432
	ds_read_b128 v[160:163], v248 offset:19456
	s_addc_u32 s78, s13, s43
	s_and_b64 s[30:31], s[20:21], exec
	s_cselect_b32 s31, s49, s78
	s_cselect_b32 s30, s48, s39
	s_add_u32 s39, s16, s42
	s_addc_u32 s42, s17, s43
	s_and_b64 s[20:21], s[20:21], exec
	s_cselect_b32 s21, s51, s42
	s_cselect_b32 s20, s50, s39
	s_add_u32 s39, s12, s40
	s_addc_u32 s41, s13, s41
	s_add_u32 s40, s39, 0x2b0000
	s_addc_u32 s41, s41, 0
	v_lshl_add_u64 v[196:197], s[40:41], 0, v[200:201]
	s_add_i32 m0, s56, 0xc000
	ds_read_b128 v[164:167], v247
	ds_read_b128 v[168:171], v247 offset:1024
	ds_read_b128 v[172:175], v247 offset:2048
	ds_read_b128 v[176:179], v247 offset:3072
	ds_read_b128 v[180:183], v247 offset:4096
	ds_read_b128 v[184:187], v247 offset:5120
	ds_read_b128 v[188:191], v247 offset:6144
	ds_read_b128 v[192:195], v247 offset:7168
	global_load_lds_dwordx4 v[196:197], off
	v_lshl_add_u64 v[196:197], s[40:41], 0, v[204:205]
	s_add_i32 m0, s56, 0xe000
	s_nop 0
	global_load_lds_dwordx4 v[196:197], off
	s_waitcnt vmcnt(8)
	s_waitcnt lgkmcnt(0)
	s_barrier
	s_setprio 1
	v_mfma_f32_16x16x32_bf16 v[128:131], v[132:135], v[164:167], v[128:131]
	v_mfma_f32_16x16x32_bf16 v[124:127], v[140:143], v[164:167], v[124:127]
	v_mfma_f32_16x16x32_bf16 v[120:123], v[132:135], v[172:175], v[120:123]
	v_mfma_f32_16x16x32_bf16 v[116:119], v[140:143], v[172:175], v[116:119]
	v_mfma_f32_16x16x32_bf16 v[112:115], v[132:135], v[180:183], v[112:115]
	v_mfma_f32_16x16x32_bf16 v[108:111], v[140:143], v[180:183], v[108:111]
	v_mfma_f32_16x16x32_bf16 v[104:107], v[132:135], v[188:191], v[104:107]
	v_mfma_f32_16x16x32_bf16 v[100:103], v[140:143], v[188:191], v[100:103]
	v_mfma_f32_16x16x32_bf16 v[128:131], v[136:139], v[168:171], v[128:131]
	v_mfma_f32_16x16x32_bf16 v[124:127], v[144:147], v[168:171], v[124:127]
	v_mfma_f32_16x16x32_bf16 v[120:123], v[136:139], v[176:179], v[120:123]
	v_mfma_f32_16x16x32_bf16 v[116:119], v[144:147], v[176:179], v[116:119]
	v_mfma_f32_16x16x32_bf16 v[112:115], v[136:139], v[184:187], v[112:115]
	v_mfma_f32_16x16x32_bf16 v[108:111], v[144:147], v[184:187], v[108:111]
	v_mfma_f32_16x16x32_bf16 v[104:107], v[136:139], v[192:195], v[104:107]
	v_mfma_f32_16x16x32_bf16 v[100:103], v[144:147], v[192:195], v[100:103]
	v_mfma_f32_16x16x32_bf16 v[96:99], v[148:151], v[164:167], v[96:99]
	v_mfma_f32_16x16x32_bf16 v[92:95], v[156:159], v[164:167], v[92:95]
	v_mfma_f32_16x16x32_bf16 v[88:91], v[148:151], v[172:175], v[88:91]
	v_mfma_f32_16x16x32_bf16 v[80:83], v[156:159], v[172:175], v[80:83]
	v_mfma_f32_16x16x32_bf16 v[64:67], v[148:151], v[180:183], v[64:67]
	v_mfma_f32_16x16x32_bf16 v[52:55], v[156:159], v[180:183], v[52:55]
	v_mfma_f32_16x16x32_bf16 v[32:35], v[148:151], v[188:191], v[32:35]
	v_mfma_f32_16x16x32_bf16 v[20:23], v[156:159], v[188:191], v[20:23]
	v_mfma_f32_16x16x32_bf16 v[96:99], v[152:155], v[168:171], v[96:99]
	v_mfma_f32_16x16x32_bf16 v[92:95], v[160:163], v[168:171], v[92:95]
	v_mfma_f32_16x16x32_bf16 v[88:91], v[152:155], v[176:179], v[88:91]
	v_mfma_f32_16x16x32_bf16 v[80:83], v[160:163], v[176:179], v[80:83]
	v_mfma_f32_16x16x32_bf16 v[64:67], v[152:155], v[184:187], v[64:67]
	v_mfma_f32_16x16x32_bf16 v[52:55], v[160:163], v[184:187], v[52:55]
	v_mfma_f32_16x16x32_bf16 v[32:35], v[152:155], v[192:195], v[32:35]
	v_mfma_f32_16x16x32_bf16 v[20:23], v[160:163], v[192:195], v[20:23]
	s_setprio 0
	s_barrier
	s_mov_b32 m0, s57
	v_lshl_add_u64 v[196:197], s[20:21], 0, v[202:203]
	s_add_u32 s40, s20, 0x2b0000
	ds_read_b128 v[164:167], v247 offset:16384
	ds_read_b128 v[168:171], v247 offset:17408
	ds_read_b128 v[172:175], v247 offset:18432
	ds_read_b128 v[176:179], v247 offset:19456
	ds_read_b128 v[180:183], v247 offset:20480
	ds_read_b128 v[184:187], v247 offset:21504
	ds_read_b128 v[188:191], v247 offset:22528
	ds_read_b128 v[192:195], v247 offset:23552
	global_load_lds_dwordx4 v[196:197], off
	v_lshl_add_u64 v[198:199], s[20:21], 0, v[206:207]
	s_mov_b32 m0, s58
	s_addc_u32 s41, s21, 0
	global_load_lds_dwordx4 v[198:199], off
	v_lshl_add_u64 v[208:209], s[40:41], 0, v[202:203]
	s_mov_b32 m0, s59
	v_lshl_add_u64 v[210:211], s[30:31], 0, v[204:205]
	global_load_lds_dwordx4 v[208:209], off
	v_lshl_add_u64 v[208:209], s[40:41], 0, v[206:207]
	s_mov_b32 m0, s60
	s_nop 0
	global_load_lds_dwordx4 v[208:209], off
	v_lshl_add_u64 v[208:209], s[30:31], 0, v[200:201]
	s_mov_b32 m0, s56
	s_nop 0
	global_load_lds_dwordx4 v[208:209], off
	s_mov_b32 m0, s61
	s_nop 0
	global_load_lds_dwordx4 v[210:211], off
	s_waitcnt vmcnt(8)
	s_waitcnt lgkmcnt(0)
	s_barrier
; #define PG8_STAGE(bufoff, gbase, voff) do { _Pragma("unroll") for (int _i = 0; _i < 2; ++_i) \
;         __builtin_amdgcn_global_load_lds((const unsigned*)((const char*)(gbase) + (voff)[_i]), (LAS unsigned*)(lds + (bufoff) + ldsw + _i * 8192), 16, 0, 0); } while (0)
; #define PG8_LDA(dst, b, h) do { _Pragma("unroll") for (int m = 0; m < 4; ++m) _Pragma("unroll") for (int k = 0; k < 2; ++k) dst[m][k] = *(const LAS bf16x8*)(pA + PG8_SA(b, h) + m * 2048 + k * 1024); } while (0)
; #define PG8_LDB(dst, b, h) do { _Pragma("unroll") for (int n = 0; n < 2; ++n) _Pragma("unroll") for (int k = 0; k < 2; ++k) dst[n][k] = *(const LAS bf16x8*)(pB + (PG8_SB(b, h) - 4 * HTB) + n * 2048 + k * 1024); } while (0)
; #define PG8_MMA(ai, bj, At, Bt) do { __builtin_amdgcn_s_setprio(1); _Pragma("unroll") for (int m = 0; m < 4; ++m) _Pragma("unroll") for (int n = 0; n < 2; ++n) _Pragma("unroll") for (int k = 0; k < 2; ++k) \
;         acc[ai][bj][m][n] = __builtin_amdgcn_mfma_f32_16x16x32_bf16(Bt[n][k], At[m][k], acc[ai][bj][m][n], 0, 0, 0); __builtin_amdgcn_s_setprio(0); } while (0)
; #define PG8_WAIT_V(n) asm volatile("s_waitcnt vmcnt(" #n ")" ::: "memory")
; #define PG8_WAIT_L(n) asm volatile("s_waitcnt lgkmcnt(" #n ")" ::: "memory")
; #define PG8_BAR __builtin_amdgcn_s_barrier()
; #define PG8_SCHED __builtin_amdgcn_sched_barrier(0)
; template <class Desc, class Epi, bool ALIGN_EPI>
; __device__ __forceinline__ void gemm_phase(LAS unsigned char* lds, const Desc& D, const Epi& E, int G, int c) {
;     ...
;             PG8_WAIT_V(8); PG8_WAIT_L(0); PG8_BAR; PG8_MMA(1, 0, At, B0); PG8_MMA(1, 1, At, B1); PG8_BAR; PG8_SCHED;
;             PG8_LDB(B0, 1, 0); PG8_LDB(B1, 1, 1); PG8_SCHED; PG8_LDA(At, 1, 0); PG8_STAGE(PG8_SA(0, 1), a2 + hstepA, voffA);
;             PG8_WAIT_V(8); PG8_WAIT_L(0); PG8_BAR; PG8_MMA(0, 0, At, B0); PG8_MMA(0, 1, At, B1); PG8_BAR; PG8_SCHED;
	s_setprio 1
	v_mfma_f32_16x16x32_bf16 v[84:87], v[132:135], v[164:167], v[84:87]
	v_mfma_f32_16x16x32_bf16 v[76:79], v[140:143], v[164:167], v[76:79]
	v_mfma_f32_16x16x32_bf16 v[72:75], v[132:135], v[172:175], v[72:75]
	v_mfma_f32_16x16x32_bf16 v[68:71], v[140:143], v[172:175], v[68:71]
	v_mfma_f32_16x16x32_bf16 v[60:63], v[132:135], v[180:183], v[60:63]
	v_mfma_f32_16x16x32_bf16 v[56:59], v[140:143], v[180:183], v[56:59]
	v_mfma_f32_16x16x32_bf16 v[48:51], v[132:135], v[188:191], v[48:51]
	v_mfma_f32_16x16x32_bf16 v[44:47], v[140:143], v[188:191], v[44:47]
	v_mfma_f32_16x16x32_bf16 v[84:87], v[136:139], v[168:171], v[84:87]
	v_mfma_f32_16x16x32_bf16 v[76:79], v[144:147], v[168:171], v[76:79]
	v_mfma_f32_16x16x32_bf16 v[72:75], v[136:139], v[176:179], v[72:75]
	v_mfma_f32_16x16x32_bf16 v[68:71], v[144:147], v[176:179], v[68:71]
	v_mfma_f32_16x16x32_bf16 v[60:63], v[136:139], v[184:187], v[60:63]
	v_mfma_f32_16x16x32_bf16 v[56:59], v[144:147], v[184:187], v[56:59]
	v_mfma_f32_16x16x32_bf16 v[48:51], v[136:139], v[192:195], v[48:51]
	v_mfma_f32_16x16x32_bf16 v[44:47], v[144:147], v[192:195], v[44:47]
	v_mfma_f32_16x16x32_bf16 v[40:43], v[148:151], v[164:167], v[40:43]
	v_mfma_f32_16x16x32_bf16 v[36:39], v[156:159], v[164:167], v[36:39]
	v_mfma_f32_16x16x32_bf16 v[28:31], v[148:151], v[172:175], v[28:31]
	v_mfma_f32_16x16x32_bf16 v[24:27], v[156:159], v[172:175], v[24:27]
	v_mfma_f32_16x16x32_bf16 v[16:19], v[148:151], v[180:183], v[16:19]
	v_mfma_f32_16x16x32_bf16 v[12:15], v[156:159], v[180:183], v[12:15]
	v_mfma_f32_16x16x32_bf16 v[8:11], v[148:151], v[188:191], v[8:11]
	v_mfma_f32_16x16x32_bf16 v[4:7], v[156:159], v[188:191], v[4:7]
	v_mfma_f32_16x16x32_bf16 v[40:43], v[152:155], v[168:171], v[40:43]
	v_mfma_f32_16x16x32_bf16 v[36:39], v[160:163], v[168:171], v[36:39]
	v_mfma_f32_16x16x32_bf16 v[28:31], v[152:155], v[176:179], v[28:31]
	v_mfma_f32_16x16x32_bf16 v[24:27], v[160:163], v[176:179], v[24:27]
	v_mfma_f32_16x16x32_bf16 v[16:19], v[152:155], v[184:187], v[16:19]
	v_mfma_f32_16x16x32_bf16 v[12:15], v[160:163], v[184:187], v[12:15]
	v_mfma_f32_16x16x32_bf16 v[8:11], v[152:155], v[192:195], v[8:11]
	v_mfma_f32_16x16x32_bf16 v[4:7], v[160:163], v[192:195], v[4:7]
	s_setprio 0
	s_barrier
	ds_read_b128 v[132:135], v248 offset:32768
	ds_read_b128 v[136:139], v248 offset:33792
	ds_read_b128 v[140:143], v248 offset:34816
	ds_read_b128 v[144:147], v248 offset:35840
	ds_read_b128 v[148:151], v248 offset:49152
	ds_read_b128 v[152:155], v248 offset:50176
	ds_read_b128 v[156:159], v248 offset:51200
	ds_read_b128 v[160:163], v248 offset:52224
	s_add_u32 s30, s30, 0x2b0000
	s_addc_u32 s31, s31, 0
	s_mov_b32 m0, s62
	v_lshl_add_u64 v[212:213], s[30:31], 0, v[200:201]
	ds_read_b128 v[164:167], v247 offset:32768
	ds_read_b128 v[168:171], v247 offset:33792
	ds_read_b128 v[172:175], v247 offset:34816
	ds_read_b128 v[176:179], v247 offset:35840
	ds_read_b128 v[180:183], v247 offset:36864
	ds_read_b128 v[184:187], v247 offset:37888
	ds_read_b128 v[188:191], v247 offset:38912
	ds_read_b128 v[192:195], v247 offset:39936
	global_load_lds_dwordx4 v[212:213], off
	v_lshl_add_u64 v[212:213], s[30:31], 0, v[204:205]
	s_mov_b32 m0, s63
	s_nop 0
	global_load_lds_dwordx4 v[212:213], off
	s_waitcnt vmcnt(8)
	s_waitcnt lgkmcnt(0)
	s_barrier
	s_setprio 1
	v_mfma_f32_16x16x32_bf16 v[128:131], v[132:135], v[164:167], v[128:131]
	v_mfma_f32_16x16x32_bf16 v[124:127], v[140:143], v[164:167], v[124:127]
	v_mfma_f32_16x16x32_bf16 v[120:123], v[132:135], v[172:175], v[120:123]
	v_mfma_f32_16x16x32_bf16 v[116:119], v[140:143], v[172:175], v[116:119]
	v_mfma_f32_16x16x32_bf16 v[112:115], v[132:135], v[180:183], v[112:115]
	v_mfma_f32_16x16x32_bf16 v[108:111], v[140:143], v[180:183], v[108:111]
	v_mfma_f32_16x16x32_bf16 v[104:107], v[132:135], v[188:191], v[104:107]
	v_mfma_f32_16x16x32_bf16 v[100:103], v[140:143], v[188:191], v[100:103]
	v_mfma_f32_16x16x32_bf16 v[128:131], v[136:139], v[168:171], v[128:131]
	v_mfma_f32_16x16x32_bf16 v[124:127], v[144:147], v[168:171], v[124:127]
	v_mfma_f32_16x16x32_bf16 v[120:123], v[136:139], v[176:179], v[120:123]
	v_mfma_f32_16x16x32_bf16 v[116:119], v[144:147], v[176:179], v[116:119]
	v_mfma_f32_16x16x32_bf16 v[112:115], v[136:139], v[184:187], v[112:115]
	v_mfma_f32_16x16x32_bf16 v[108:111], v[144:147], v[184:187], v[108:111]
	v_mfma_f32_16x16x32_bf16 v[104:107], v[136:139], v[192:195], v[104:107]
	v_mfma_f32_16x16x32_bf16 v[100:103], v[144:147], v[192:195], v[100:103]
	v_mfma_f32_16x16x32_bf16 v[96:99], v[148:151], v[164:167], v[96:99]
	v_mfma_f32_16x16x32_bf16 v[92:95], v[156:159], v[164:167], v[92:95]
	v_mfma_f32_16x16x32_bf16 v[88:91], v[148:151], v[172:175], v[88:91]
	v_mfma_f32_16x16x32_bf16 v[80:83], v[156:159], v[172:175], v[80:83]
	v_mfma_f32_16x16x32_bf16 v[64:67], v[148:151], v[180:183], v[64:67]
	v_mfma_f32_16x16x32_bf16 v[52:55], v[156:159], v[180:183], v[52:55]
	v_mfma_f32_16x16x32_bf16 v[32:35], v[148:151], v[188:191], v[32:35]
	v_mfma_f32_16x16x32_bf16 v[20:23], v[156:159], v[188:191], v[20:23]
	v_mfma_f32_16x16x32_bf16 v[96:99], v[152:155], v[168:171], v[96:99]
	v_mfma_f32_16x16x32_bf16 v[92:95], v[160:163], v[168:171], v[92:95]
	v_mfma_f32_16x16x32_bf16 v[88:91], v[152:155], v[176:179], v[88:91]
	v_mfma_f32_16x16x32_bf16 v[80:83], v[160:163], v[176:179], v[80:83]
	v_mfma_f32_16x16x32_bf16 v[64:67], v[152:155], v[184:187], v[64:67]
	v_mfma_f32_16x16x32_bf16 v[52:55], v[160:163], v[184:187], v[52:55]
	v_mfma_f32_16x16x32_bf16 v[32:35], v[152:155], v[192:195], v[32:35]
	v_mfma_f32_16x16x32_bf16 v[20:23], v[160:163], v[192:195], v[20:23]
	s_setprio 0
	s_barrier
; #define PG8_STAGE(bufoff, gbase, voff) do { _Pragma("unroll") for (int _i = 0; _i < 2; ++_i) \
;         __builtin_amdgcn_global_load_lds((const unsigned*)((const char*)(gbase) + (voff)[_i]), (LAS unsigned*)(lds + (bufoff) + ldsw + _i * 8192), 16, 0, 0); } while (0)
; #define PG8_LDA(dst, b, h) do { _Pragma("unroll") for (int m = 0; m < 4; ++m) _Pragma("unroll") for (int k = 0; k < 2; ++k) dst[m][k] = *(const LAS bf16x8*)(pA + PG8_SA(b, h) + m * 2048 + k * 1024); } while (0)
; #define PG8_MMA(ai, bj, At, Bt) do { __builtin_amdgcn_s_setprio(1); _Pragma("unroll") for (int m = 0; m < 4; ++m) _Pragma("unroll") for (int n = 0; n < 2; ++n) _Pragma("unroll") for (int k = 0; k < 2; ++k) \
;         acc[ai][bj][m][n] = __builtin_amdgcn_mfma_f32_16x16x32_bf16(Bt[n][k], At[m][k], acc[ai][bj][m][n], 0, 0, 0); __builtin_amdgcn_s_setprio(0); } while (0)
; #define PG8_WAIT_V(n) asm volatile("s_waitcnt vmcnt(" #n ")" ::: "memory")
; #define PG8_WAIT_L(n) asm volatile("s_waitcnt lgkmcnt(" #n ")" ::: "memory")
; #define PG8_BAR __builtin_amdgcn_s_barrier()
; #define PG8_SCHED __builtin_amdgcn_sched_barrier(0)
; template <class Desc, class Epi, bool ALIGN_EPI>
; __device__ __forceinline__ void gemm_phase(LAS unsigned char* lds, const Desc& D, const Epi& E, int G, int c) {
;     ...
;             PG8_LDA(At, 1, 1); PG8_STAGE(PG8_SB(1, 0), b3, voffB); PG8_STAGE(PG8_SB(1, 1), b3 + hstepB, voffB); PG8_STAGE(PG8_SA(1, 0), a3, voffA);
;             PG8_WAIT_V(8); PG8_WAIT_L(0); PG8_BAR; PG8_MMA(1, 0, At, B0); PG8_MMA(1, 1, At, B1); PG8_BAR; PG8_SCHED;
;         }
	s_mov_b32 m0, s64
	v_lshl_add_u64 v[196:197], v[196:197], 0, s[76:77]
	s_add_u32 s20, s20, 0x2b0080
	ds_read_b128 v[164:167], v247 offset:49152
	ds_read_b128 v[168:171], v247 offset:50176
	ds_read_b128 v[172:175], v247 offset:51200
	ds_read_b128 v[176:179], v247 offset:52224
	ds_read_b128 v[180:183], v247 offset:53248
	ds_read_b128 v[184:187], v247 offset:54272
	ds_read_b128 v[188:191], v247 offset:55296
	ds_read_b128 v[192:195], v247 offset:56320
	global_load_lds_dwordx4 v[196:197], off
	v_lshl_add_u64 v[196:197], v[198:199], 0, s[76:77]
	s_mov_b32 m0, s65
	s_addc_u32 s21, s21, 0
	global_load_lds_dwordx4 v[196:197], off
	v_lshl_add_u64 v[196:197], s[20:21], 0, v[202:203]
	s_mov_b32 m0, s69
	s_nop 0
	global_load_lds_dwordx4 v[196:197], off
	v_lshl_add_u64 v[196:197], s[20:21], 0, v[206:207]
	s_mov_b32 m0, s70
	s_nop 0
	global_load_lds_dwordx4 v[196:197], off
	v_lshl_add_u64 v[196:197], v[208:209], 0, s[76:77]
	s_mov_b32 m0, s66
	s_nop 0
	global_load_lds_dwordx4 v[196:197], off
	v_lshl_add_u64 v[196:197], v[210:211], 0, s[76:77]
	s_mov_b32 m0, s67
	s_nop 0
	global_load_lds_dwordx4 v[196:197], off
	s_waitcnt vmcnt(8)
	s_waitcnt lgkmcnt(0)
	s_barrier
	s_setprio 1
	v_mfma_f32_16x16x32_bf16 v[84:87], v[132:135], v[164:167], v[84:87]
	v_mfma_f32_16x16x32_bf16 v[76:79], v[140:143], v[164:167], v[76:79]
	v_mfma_f32_16x16x32_bf16 v[72:75], v[132:135], v[172:175], v[72:75]
	v_mfma_f32_16x16x32_bf16 v[68:71], v[140:143], v[172:175], v[68:71]
	v_mfma_f32_16x16x32_bf16 v[60:63], v[132:135], v[180:183], v[60:63]
	v_mfma_f32_16x16x32_bf16 v[56:59], v[140:143], v[180:183], v[56:59]
	v_mfma_f32_16x16x32_bf16 v[48:51], v[132:135], v[188:191], v[48:51]
	v_mfma_f32_16x16x32_bf16 v[44:47], v[140:143], v[188:191], v[44:47]
	v_mfma_f32_16x16x32_bf16 v[84:87], v[136:139], v[168:171], v[84:87]
	v_mfma_f32_16x16x32_bf16 v[76:79], v[144:147], v[168:171], v[76:79]
	v_mfma_f32_16x16x32_bf16 v[72:75], v[136:139], v[176:179], v[72:75]
	v_mfma_f32_16x16x32_bf16 v[68:71], v[144:147], v[176:179], v[68:71]
	v_mfma_f32_16x16x32_bf16 v[60:63], v[136:139], v[184:187], v[60:63]
	v_mfma_f32_16x16x32_bf16 v[56:59], v[144:147], v[184:187], v[56:59]
	v_mfma_f32_16x16x32_bf16 v[48:51], v[136:139], v[192:195], v[48:51]
	v_mfma_f32_16x16x32_bf16 v[44:47], v[144:147], v[192:195], v[44:47]
	v_mfma_f32_16x16x32_bf16 v[40:43], v[148:151], v[164:167], v[40:43]
	v_mfma_f32_16x16x32_bf16 v[36:39], v[156:159], v[164:167], v[36:39]
	v_mfma_f32_16x16x32_bf16 v[28:31], v[148:151], v[172:175], v[28:31]
	v_mfma_f32_16x16x32_bf16 v[24:27], v[156:159], v[172:175], v[24:27]
	v_mfma_f32_16x16x32_bf16 v[16:19], v[148:151], v[180:183], v[16:19]
	v_mfma_f32_16x16x32_bf16 v[12:15], v[156:159], v[180:183], v[12:15]
	v_mfma_f32_16x16x32_bf16 v[8:11], v[148:151], v[188:191], v[8:11]
	v_mfma_f32_16x16x32_bf16 v[4:7], v[156:159], v[188:191], v[4:7]
	v_mfma_f32_16x16x32_bf16 v[40:43], v[152:155], v[168:171], v[40:43]
	v_mfma_f32_16x16x32_bf16 v[36:39], v[160:163], v[168:171], v[36:39]
	v_mfma_f32_16x16x32_bf16 v[28:31], v[152:155], v[176:179], v[28:31]
	v_mfma_f32_16x16x32_bf16 v[24:27], v[160:163], v[176:179], v[24:27]
	v_mfma_f32_16x16x32_bf16 v[16:19], v[152:155], v[184:187], v[16:19]
	v_mfma_f32_16x16x32_bf16 v[12:15], v[160:163], v[184:187], v[12:15]
	v_mfma_f32_16x16x32_bf16 v[8:11], v[152:155], v[192:195], v[8:11]
	v_mfma_f32_16x16x32_bf16 v[4:7], v[160:163], v[192:195], v[4:7]
	s_setprio 0
	s_barrier
	s_cmp_ge_u32 s14, s24
	s_mov_b32 s39, s14
	s_cbranch_scc1 .LBB0_1776
